# cache-shift copy: 16384 units moved from the four FFN-out slots into S5 pass A (one unit per wave item: loads behind the first MFMA burst, stores at the next item top); plus carry prefetch / ILP emiss
# speedup vs baseline: 1.0073x; 1.0073x over previous
.Lcpy1p_loop:
	s_add_i32 s101, s80, s100
	s_cmp_lt_u32 s101, 0x31f4
	s_cbranch_scc0 .Lcpy1p_tail
	s_mul_hi_u32 s81, s80, 0x2ad5802b
	s_lshr_b32 s81, s81, 8
	s_mul_i32 s82, s81, 0x5fa
	s_sub_i32 s82, s80, s82
	s_lshl_b32 s82, s82, 13
	s_and_b32 s83, s81, 31
	s_mul_i32 s83, s83, 0xc00000
	s_add_i32 s82, s82, s83
	s_cmp_lt_u32 s81, 32
	s_cselect_b32 s84, s92, s94
	s_cselect_b32 s85, s93, s95
	s_mov_b32 s83, 0x1f210000
	s_cselect_b32 s83, 0x7210000, s83
	s_add_u32 s84, s84, s82
	s_addc_u32 s85, s85, 0
	s_add_u32 s84, s84, 0xc000
	s_addc_u32 s85, s85, 0
	s_add_u32 s83, s83, s82
	s_add_u32 s86, s98, s83
	s_addc_u32 s87, s99, 0
	s_mul_hi_u32 s81, s101, 0x2ad5802b
	s_lshr_b32 s81, s81, 8
	s_mul_i32 s82, s81, 0x5fa
	s_sub_i32 s82, s101, s82
	s_lshl_b32 s82, s82, 13
	s_and_b32 s83, s81, 31
	s_mul_i32 s83, s83, 0xc00000
	s_add_i32 s82, s82, s83
	s_cmp_lt_u32 s81, 32
	s_cselect_b32 s88, s92, s94
	s_cselect_b32 s89, s93, s95
	s_mov_b32 s83, 0x1f210000
	s_cselect_b32 s83, 0x7210000, s83
	s_add_u32 s88, s88, s82
	s_addc_u32 s89, s89, 0
	s_add_u32 s88, s88, 0xc000
	s_addc_u32 s89, s89, 0
	s_add_u32 s83, s83, s82
	s_add_u32 s90, s98, s83
	s_addc_u32 s91, s99, 0
	global_load_dwordx4 v[64:67], v22, s[84:85] nt
	global_load_dwordx4 v[68:71], v22, s[84:85] offset:1024 nt
	global_load_dwordx4 v[72:75], v22, s[84:85] offset:2048 nt
	global_load_dwordx4 v[76:79], v22, s[84:85] offset:3072 nt
	global_load_dwordx4 v[80:83], v23, s[84:85] nt
	global_load_dwordx4 v[84:87], v23, s[84:85] offset:1024 nt
	global_load_dwordx4 v[88:91], v23, s[84:85] offset:2048 nt
	global_load_dwordx4 v[92:95], v23, s[84:85] offset:3072 nt
	global_load_dwordx4 v[96:99], v22, s[88:89] nt
	global_load_dwordx4 v[100:103], v22, s[88:89] offset:1024 nt
	global_load_dwordx4 v[104:107], v22, s[88:89] offset:2048 nt
	global_load_dwordx4 v[108:111], v22, s[88:89] offset:3072 nt
	global_load_dwordx4 v[112:115], v23, s[88:89] nt
	global_load_dwordx4 v[116:119], v23, s[88:89] offset:1024 nt
	global_load_dwordx4 v[120:123], v23, s[88:89] offset:2048 nt
	global_load_dwordx4 v[124:127], v23, s[88:89] offset:3072 nt
	s_waitcnt vmcnt(15)
	global_store_dwordx4 v22, v[64:67], s[86:87] nt
	s_waitcnt vmcnt(15)
	global_store_dwordx4 v22, v[68:71], s[86:87] offset:1024 nt
	s_waitcnt vmcnt(15)
	global_store_dwordx4 v22, v[72:75], s[86:87] offset:2048 nt
	s_waitcnt vmcnt(15)
	global_store_dwordx4 v22, v[76:79], s[86:87] offset:3072 nt
	s_waitcnt vmcnt(15)
	global_store_dwordx4 v23, v[80:83], s[86:87] nt
	s_waitcnt vmcnt(15)
	global_store_dwordx4 v23, v[84:87], s[86:87] offset:1024 nt
	s_waitcnt vmcnt(15)
	global_store_dwordx4 v23, v[88:91], s[86:87] offset:2048 nt
	s_waitcnt vmcnt(15)
	global_store_dwordx4 v23, v[92:95], s[86:87] offset:3072 nt
	s_waitcnt vmcnt(15)
	global_store_dwordx4 v22, v[96:99], s[90:91] nt
	s_waitcnt vmcnt(15)
	global_store_dwordx4 v22, v[100:103], s[90:91] offset:1024 nt
	s_waitcnt vmcnt(15)
	global_store_dwordx4 v22, v[104:107], s[90:91] offset:2048 nt
	s_waitcnt vmcnt(15)
	global_store_dwordx4 v22, v[108:111], s[90:91] offset:3072 nt
	s_waitcnt vmcnt(15)
	global_store_dwordx4 v23, v[112:115], s[90:91] nt
	s_waitcnt vmcnt(15)
	global_store_dwordx4 v23, v[116:119], s[90:91] offset:1024 nt
	s_waitcnt vmcnt(15)
	global_store_dwordx4 v23, v[120:123], s[90:91] offset:2048 nt
	s_waitcnt vmcnt(15)
	global_store_dwordx4 v23, v[124:127], s[90:91] offset:3072 nt
	s_add_i32 s80, s101, s100
	s_branch .Lcpy1p_loop
.Lcpy1p_tail:
	s_cmp_lt_u32 s80, 0x31f4
	s_cbranch_scc0 .Lcpy1p_end
	s_mul_hi_u32 s81, s80, 0x2ad5802b
	s_lshr_b32 s81, s81, 8
	s_mul_i32 s82, s81, 0x5fa
	s_sub_i32 s82, s80, s82
	s_lshl_b32 s82, s82, 13
	s_and_b32 s83, s81, 31
	s_mul_i32 s83, s83, 0xc00000
	s_add_i32 s82, s82, s83
	s_cmp_lt_u32 s81, 32
	s_cselect_b32 s84, s92, s94
	s_cselect_b32 s85, s93, s95
	s_mov_b32 s83, 0x1f210000
	s_cselect_b32 s83, 0x7210000, s83
	s_add_u32 s84, s84, s82
	s_addc_u32 s85, s85, 0
	s_add_u32 s84, s84, 0xc000
	s_addc_u32 s85, s85, 0
	s_add_u32 s83, s83, s82
	s_add_u32 s86, s98, s83
	s_addc_u32 s87, s99, 0
	global_load_dwordx4 v[64:67], v22, s[84:85] nt
	global_load_dwordx4 v[68:71], v22, s[84:85] offset:1024 nt
	global_load_dwordx4 v[72:75], v22, s[84:85] offset:2048 nt
	global_load_dwordx4 v[76:79], v22, s[84:85] offset:3072 nt
	global_load_dwordx4 v[80:83], v23, s[84:85] nt
	global_load_dwordx4 v[84:87], v23, s[84:85] offset:1024 nt
	global_load_dwordx4 v[88:91], v23, s[84:85] offset:2048 nt
	global_load_dwordx4 v[92:95], v23, s[84:85] offset:3072 nt
	s_waitcnt vmcnt(7)
	global_store_dwordx4 v22, v[64:67], s[86:87] nt
	s_waitcnt vmcnt(7)
	global_store_dwordx4 v22, v[68:71], s[86:87] offset:1024 nt
	s_waitcnt vmcnt(7)
	global_store_dwordx4 v22, v[72:75], s[86:87] offset:2048 nt
	s_waitcnt vmcnt(7)
	global_store_dwordx4 v22, v[76:79], s[86:87] offset:3072 nt
	s_waitcnt vmcnt(7)
	global_store_dwordx4 v23, v[80:83], s[86:87] nt
	s_waitcnt vmcnt(7)
	global_store_dwordx4 v23, v[84:87], s[86:87] offset:1024 nt
	s_waitcnt vmcnt(7)
	global_store_dwordx4 v23, v[88:91], s[86:87] offset:2048 nt
	s_waitcnt vmcnt(7)
	global_store_dwordx4 v23, v[92:95], s[86:87] offset:3072 nt

.Lmg1_end:
	v_lshrrev_b32_e32 v21, 6, v174
	v_and_b32_e32 v22, 63, v174
	v_lshlrev_b32_e32 v22, 4, v22
	v_readfirstlane_b32 s80, v21
	v_add_u32_e32 v23, 0x1000, v22
	v_readfirstlane_b32 s92, v235
	v_readfirstlane_b32 s93, v236
	v_readfirstlane_b32 s94, v237
	v_readfirstlane_b32 s95, v238
	v_readfirstlane_b32 s98, v239
	v_readfirstlane_b32 s99, v240
	s_lshr_b32 s100, s33, 7
	s_lshl_b32 s100, s100, 3
	s_lshr_b32 s101, s33, 3
	s_and_b32 s101, s101, 7
	s_add_i32 s100, s100, s101
	s_lshl_b32 s100, s100, 3
	s_add_i32 s80, s80, s100
	s_add_i32 s80, s80, 0x31f4
	s_movk_i32 s100, 0x400
.Lcpy1_loop:
	s_add_i32 s101, s80, s100
	s_cmp_lt_u32 s101, 0x3830
	s_cbranch_scc0 .Lcpy1_tail
	s_mul_hi_u32 s81, s80, 0x2ad5802b
	s_lshr_b32 s81, s81, 8
	s_mul_i32 s82, s81, 0x5fa
	s_sub_i32 s82, s80, s82
	s_lshl_b32 s82, s82, 13
	s_and_b32 s83, s81, 31
	s_mul_i32 s83, s83, 0xc00000
	s_add_i32 s82, s82, s83
	s_cmp_lt_u32 s81, 32
	s_cselect_b32 s84, s92, s94
	s_cselect_b32 s85, s93, s95
	s_mov_b32 s83, 0x1f210000
	s_cselect_b32 s83, 0x7210000, s83
	s_add_u32 s84, s84, s82
	s_addc_u32 s85, s85, 0
	s_add_u32 s84, s84, 0xc000
	s_addc_u32 s85, s85, 0
	s_add_u32 s83, s83, s82
	s_add_u32 s86, s98, s83
	s_addc_u32 s87, s99, 0
	s_mul_hi_u32 s81, s101, 0x2ad5802b
	s_lshr_b32 s81, s81, 8
	s_mul_i32 s82, s81, 0x5fa
	s_sub_i32 s82, s101, s82
	s_lshl_b32 s82, s82, 13
	s_and_b32 s83, s81, 31
	s_mul_i32 s83, s83, 0xc00000
	s_add_i32 s82, s82, s83
	s_cmp_lt_u32 s81, 32
	s_cselect_b32 s88, s92, s94
	s_cselect_b32 s89, s93, s95
	s_mov_b32 s83, 0x1f210000
	s_cselect_b32 s83, 0x7210000, s83
	s_add_u32 s88, s88, s82
	s_addc_u32 s89, s89, 0
	s_add_u32 s88, s88, 0xc000
	s_addc_u32 s89, s89, 0
	s_add_u32 s83, s83, s82
	s_add_u32 s90, s98, s83
	s_addc_u32 s91, s99, 0
	global_load_dwordx4 v[64:67], v22, s[84:85] nt
	global_load_dwordx4 v[68:71], v22, s[84:85] offset:1024 nt
	global_load_dwordx4 v[72:75], v22, s[84:85] offset:2048 nt
	global_load_dwordx4 v[76:79], v22, s[84:85] offset:3072 nt
	global_load_dwordx4 v[80:83], v23, s[84:85] nt
	global_load_dwordx4 v[84:87], v23, s[84:85] offset:1024 nt
	global_load_dwordx4 v[88:91], v23, s[84:85] offset:2048 nt
	global_load_dwordx4 v[92:95], v23, s[84:85] offset:3072 nt
	global_load_dwordx4 v[96:99], v22, s[88:89] nt
	global_load_dwordx4 v[100:103], v22, s[88:89] offset:1024 nt
	global_load_dwordx4 v[104:107], v22, s[88:89] offset:2048 nt
	global_load_dwordx4 v[108:111], v22, s[88:89] offset:3072 nt
	global_load_dwordx4 v[112:115], v23, s[88:89] nt
	global_load_dwordx4 v[116:119], v23, s[88:89] offset:1024 nt
	global_load_dwordx4 v[120:123], v23, s[88:89] offset:2048 nt
	global_load_dwordx4 v[124:127], v23, s[88:89] offset:3072 nt
	s_waitcnt vmcnt(15)
	global_store_dwordx4 v22, v[64:67], s[86:87] nt
	s_waitcnt vmcnt(15)
	global_store_dwordx4 v22, v[68:71], s[86:87] offset:1024 nt
	s_waitcnt vmcnt(15)
	global_store_dwordx4 v22, v[72:75], s[86:87] offset:2048 nt
	s_waitcnt vmcnt(15)
	global_store_dwordx4 v22, v[76:79], s[86:87] offset:3072 nt
	s_waitcnt vmcnt(15)
	global_store_dwordx4 v23, v[80:83], s[86:87] nt
	s_waitcnt vmcnt(15)
	global_store_dwordx4 v23, v[84:87], s[86:87] offset:1024 nt
	s_waitcnt vmcnt(15)
	global_store_dwordx4 v23, v[88:91], s[86:87] offset:2048 nt
	s_waitcnt vmcnt(15)
	global_store_dwordx4 v23, v[92:95], s[86:87] offset:3072 nt
	s_waitcnt vmcnt(15)
	global_store_dwordx4 v22, v[96:99], s[90:91] nt
	s_waitcnt vmcnt(15)
	global_store_dwordx4 v22, v[100:103], s[90:91] offset:1024 nt
	s_waitcnt vmcnt(15)
	global_store_dwordx4 v22, v[104:107], s[90:91] offset:2048 nt
	s_waitcnt vmcnt(15)
	global_store_dwordx4 v22, v[108:111], s[90:91] offset:3072 nt
	s_waitcnt vmcnt(15)
	global_store_dwordx4 v23, v[112:115], s[90:91] nt
	s_waitcnt vmcnt(15)
	global_store_dwordx4 v23, v[116:119], s[90:91] offset:1024 nt
	s_waitcnt vmcnt(15)
	global_store_dwordx4 v23, v[120:123], s[90:91] offset:2048 nt
	s_waitcnt vmcnt(15)
	global_store_dwordx4 v23, v[124:127], s[90:91] offset:3072 nt
	s_add_i32 s80, s101, s100
	s_branch .Lcpy1_loop
.Lcpy1_tail:
	s_cmp_lt_u32 s80, 0x3830
	s_cbranch_scc0 .Lcpy1_end
	s_mul_hi_u32 s81, s80, 0x2ad5802b
	s_lshr_b32 s81, s81, 8
	s_mul_i32 s82, s81, 0x5fa
	s_sub_i32 s82, s80, s82
	s_lshl_b32 s82, s82, 13
	s_and_b32 s83, s81, 31
	s_mul_i32 s83, s83, 0xc00000
	s_add_i32 s82, s82, s83
	s_cmp_lt_u32 s81, 32
	s_cselect_b32 s84, s92, s94
	s_cselect_b32 s85, s93, s95
	s_mov_b32 s83, 0x1f210000
	s_cselect_b32 s83, 0x7210000, s83
	s_add_u32 s84, s84, s82
	s_addc_u32 s85, s85, 0
	s_add_u32 s84, s84, 0xc000
	s_addc_u32 s85, s85, 0
	s_add_u32 s83, s83, s82
	s_add_u32 s86, s98, s83
	s_addc_u32 s87, s99, 0
	global_load_dwordx4 v[64:67], v22, s[84:85] nt
	global_load_dwordx4 v[68:71], v22, s[84:85] offset:1024 nt
	global_load_dwordx4 v[72:75], v22, s[84:85] offset:2048 nt
	global_load_dwordx4 v[76:79], v22, s[84:85] offset:3072 nt
	global_load_dwordx4 v[80:83], v23, s[84:85] nt
	global_load_dwordx4 v[84:87], v23, s[84:85] offset:1024 nt
	global_load_dwordx4 v[88:91], v23, s[84:85] offset:2048 nt
	global_load_dwordx4 v[92:95], v23, s[84:85] offset:3072 nt
	s_waitcnt vmcnt(7)
	global_store_dwordx4 v22, v[64:67], s[86:87] nt
	s_waitcnt vmcnt(7)
	global_store_dwordx4 v22, v[68:71], s[86:87] offset:1024 nt
	s_waitcnt vmcnt(7)
	global_store_dwordx4 v22, v[72:75], s[86:87] offset:2048 nt
	s_waitcnt vmcnt(7)
	global_store_dwordx4 v22, v[76:79], s[86:87] offset:3072 nt
	s_waitcnt vmcnt(7)
	global_store_dwordx4 v23, v[80:83], s[86:87] nt
	s_waitcnt vmcnt(7)
	global_store_dwordx4 v23, v[84:87], s[86:87] offset:1024 nt
	s_waitcnt vmcnt(7)
	global_store_dwordx4 v23, v[88:91], s[86:87] offset:2048 nt
	s_waitcnt vmcnt(7)
	global_store_dwordx4 v23, v[92:95], s[86:87] offset:3072 nt

.LBB0_283:
	s_or_b64 exec, exec, s[6:7]
	s_add_u32 s10, s74, 0x12cd5c00
	s_addc_u32 s11, s75, 0
	s_add_u32 s24, s74, 0x12ce5c00
	s_addc_u32 s25, s75, 0
	s_add_u32 s26, s74, 0x12d25c00
	s_addc_u32 s27, s75, 0
	s_add_u32 s28, s74, 0x12da5c00
	s_addc_u32 s29, s75, 0
	v_mov_b32_e32 v116, v174
	s_cmpk_gt_i32 s2, 0x7ff
	s_barrier
	s_cbranch_scc1 .LBB0_300
	v_and_b32_e32 v196, 63, v174
	v_lshrrev_b32_e32 v197, 6, v174
	v_and_b32_e32 v198, 31, v196
	v_lshrrev_b32_e32 v199, 5, v196
	s_and_b32 s80, s2, 7
	v_lshl_add_u32 v200, s80, 3, v197
	v_lshl_add_u32 v201, v200, 6, v198
	v_lshlrev_b32_e32 v202, 6, v201
	v_lshl_add_u32 v202, v199, 5, v202
	global_load_dwordx4 v[24:27], v202, s[24:25] offset:0
	global_load_dwordx4 v[28:31], v202, s[24:25] offset:16
	global_load_dwordx4 v[40:43], v202, s[24:25] offset:2048
	global_load_dwordx4 v[44:47], v202, s[24:25] offset:2064
	global_load_dwordx4 v[32:35], v202, s[26:27] offset:0
	global_load_dwordx4 v[36:39], v202, s[26:27] offset:16
	global_load_dwordx4 v[48:51], v202, s[26:27] offset:2048
	global_load_dwordx4 v[52:55], v202, s[26:27] offset:2064
	v_lshlrev_b32_e32 v203, 3, v201
	s_lshl_b32 s81, s80, 7
	v_lshl_add_u32 v204, v197, 4, s81
	v_lshl_add_u32 v204, v199, 3, v204
	v_lshlrev_b32_e32 v204, 2, v204
	global_load_dwordx4 v[140:143], v204, s[42:43]
	global_load_dwordx4 v[144:147], v204, s[42:43] offset:16
	v_lshl_add_u32 v205, v198, 12, v204
	v_lshlrev_b32_e32 v206, 2, v198
	v_lshl_add_u32 v207, v200, 6, v196
	v_lshlrev_b32_e32 v207, 3, v207
	v_mov_b32_e32 v254, 0x358637bd
	s_mov_b32 s8, 0
	s_mov_b32 s9, -1
	global_load_dwordx2 v[0:1], v203, s[10:11]
	global_load_dwordx2 v[2:3], v203, s[10:11] offset:256
	s_waitcnt vmcnt(0)
	v_mul_f32_e32 v58, v1, v1
	v_mul_f32_e32 v59, v1, v0
	v_fma_f32 v4, v0, v0, -v58
	v_fma_f32 v5, v0, v1, v59
	v_mul_f32_e32 v128, v3, v3
	v_mul_f32_e32 v129, v3, v2
	v_fma_f32 v6, v2, v2, -v128
	v_fma_f32 v7, v2, v3, v129
	v_mul_f32_e32 v58, v5, v5
	v_mul_f32_e32 v59, v5, v4
	v_fma_f32 v8, v4, v4, -v58
	v_fma_f32 v9, v4, v5, v59
	v_mul_f32_e32 v128, v7, v7
	v_mul_f32_e32 v129, v7, v6
	v_fma_f32 v10, v6, v6, -v128
	v_fma_f32 v11, v6, v7, v129
	v_mul_f32_e32 v58, v9, v9
	v_mul_f32_e32 v59, v9, v8
	v_fma_f32 v14, v8, v8, -v58
	v_fma_f32 v15, v8, v9, v59
	v_mul_f32_e32 v128, v11, v11
	v_mul_f32_e32 v129, v11, v10
	v_fma_f32 v16, v10, v10, -v128
	v_fma_f32 v17, v10, v11, v129
	v_mul_f32_e32 v58, v15, v15
	v_mul_f32_e32 v59, v15, v14
	v_fma_f32 v156, v14, v14, -v58
	v_fma_f32 v157, v14, v15, v59
	v_mul_f32_e32 v128, v17, v17
	v_mul_f32_e32 v129, v17, v16
	v_fma_f32 v158, v16, v16, -v128
	v_fma_f32 v159, v16, v17, v129
	v_mul_f32_e32 v58, v157, v157
	v_mul_f32_e32 v59, v157, v156
	v_fma_f32 v160, v156, v156, -v58
	v_fma_f32 v161, v156, v157, v59
	v_mul_f32_e32 v128, v159, v159
	v_mul_f32_e32 v129, v159, v158
	v_fma_f32 v164, v158, v158, -v128
	v_fma_f32 v165, v158, v159, v129
	s_mov_b32 s82, s2
	s_lshr_b32 s4, s82, 10
	s_bfe_u32 s6, s82, 0x70003
	s_lshl_b32 s4, s4, 13
	s_lshl_b32 s6, s6, 6
	s_add_i32 s31, s4, s6
	s_lshl_b32 s6, s31, 12
	s_add_u32 s84, s38, s6
	s_addc_u32 s85, s39, 0
	s_add_u32 s88, s84, 0x20000
	s_addc_u32 s89, s85, 0
	s_lshl_b32 s6, s31, 2
	s_add_u32 s86, s22, s6
	s_addc_u32 s87, s23, 0
	global_load_dwordx4 v[178:181], v205, s[84:85]
	global_load_dwordx4 v[182:185], v205, s[84:85] offset:16
	global_load_dword v194, v206, s[86:87]
	global_load_dwordx4 v[186:189], v205, s[88:89]
	global_load_dwordx4 v[190:193], v205, s[88:89] offset:16
	global_load_dword v195, v206, s[86:87] offset:128
	v_lshlrev_b32_e32 v208, 4, v196
	v_add_u32_e32 v209, 0x1000, v208
	v_readfirstlane_b32 s67, v197
	s_lshl_b32 s35, s82, 3
	s_add_i32 s35, s35, s67
	s_add_i32 s35, s35, 0x13e80
	s_mul_hi_u32 s46, s35, 0x2ad5802b
	s_lshr_b32 s46, s46, 8
	s_mul_i32 s52, s46, 0x5fa
	s_sub_i32 s52, s35, s52
	s_lshl_b32 s52, s52, 13
	s_and_b32 s57, s46, 31
	s_mul_i32 s57, s57, 0xc00000
	s_add_i32 s52, s52, s57
	v_readfirstlane_b32 s98, v235
	v_readfirstlane_b32 s99, v236
	v_readfirstlane_b32 s65, v237
	v_readfirstlane_b32 s66, v238
	v_readfirstlane_b32 s100, v239
	v_readfirstlane_b32 s101, v240
	s_cmp_lt_u32 s46, 32
	s_cselect_b32 s98, s98, s65
	s_cselect_b32 s99, s99, s66
	s_mov_b32 s57, 0x1f210000
	s_cselect_b32 s57, 0x7210000, s57
	s_add_u32 s98, s98, s52
	s_addc_u32 s99, s99, 0
	s_add_u32 s98, s98, 0xc000
	s_addc_u32 s99, s99, 0
	s_add_u32 s57, s57, s52
	s_add_u32 s100, s100, s57
	s_addc_u32 s101, s101, 0
	global_load_dwordx4 v[210:213], v208, s[98:99] nt
	global_load_dwordx4 v[214:217], v208, s[98:99] offset:1024 nt
	global_load_dwordx4 v[218:221], v208, s[98:99] offset:2048 nt
	global_load_dwordx4 v[222:225], v208, s[98:99] offset:3072 nt
	global_load_dwordx4 v[226:229], v209, s[98:99] nt
	global_load_dwordx4 v[230:233], v209, s[98:99] offset:1024 nt
	global_load_dwordx4 v[242:245], v209, s[98:99] offset:2048 nt
	global_load_dwordx4 v[246:249], v209, s[98:99] offset:3072 nt
.Ls5a_item:
	s_waitcnt vmcnt(0)
	global_store_dwordx4 v208, v[210:213], s[100:101] nt
	global_store_dwordx4 v208, v[214:217], s[100:101] offset:1024 nt
	global_store_dwordx4 v208, v[218:221], s[100:101] offset:2048 nt
	global_store_dwordx4 v208, v[222:225], s[100:101] offset:3072 nt
	global_store_dwordx4 v209, v[226:229], s[100:101] nt
	global_store_dwordx4 v209, v[230:233], s[100:101] offset:1024 nt
	global_store_dwordx4 v209, v[242:245], s[100:101] offset:2048 nt
	global_store_dwordx4 v209, v[246:249], s[100:101] offset:3072 nt
	s_add_i32 s83, s82, 0x100
	s_cmpk_gt_i32 s83, 0x7ff
	s_cselect_b32 s83, s82, s83
	s_lshr_b32 s4, s83, 10
	s_bfe_u32 s6, s83, 0x70003
	s_lshl_b32 s4, s4, 13
	s_lshl_b32 s6, s6, 6
	s_add_i32 s32, s4, s6
	s_lshl_b32 s6, s32, 12
	s_add_u32 s90, s38, s6
	s_addc_u32 s91, s39, 0
	s_add_u32 s94, s90, 0x20000
	s_addc_u32 s95, s91, 0
	s_lshl_b32 s6, s32, 2
	s_add_u32 s92, s22, s6
	s_addc_u32 s93, s23, 0
	v_mov_b32_e32 v18, 0
	v_mov_b32_e32 v19, 0
	v_mov_b32_e32 v22, 0
	v_mov_b32_e32 v23, 0
	v_fmamk_f32 v56, v194, 0x3a800000, v254
	v_rsq_f32_e32 v56, v56
	s_nop 0
	v_pk_mul_f32 v[148:149], v[178:179], v[56:57] op_sel_hi:[1,0]
	v_pk_mul_f32 v[150:151], v[180:181], v[56:57] op_sel_hi:[1,0]
	v_pk_mul_f32 v[152:153], v[182:183], v[56:57] op_sel_hi:[1,0]
	v_pk_mul_f32 v[154:155], v[184:185], v[56:57] op_sel_hi:[1,0]
	v_pk_mul_f32 v[148:149], v[140:141], v[148:149]
	v_pk_mul_f32 v[150:151], v[142:143], v[150:151]
	v_pk_mul_f32 v[152:153], v[144:145], v[152:153]
	v_pk_mul_f32 v[154:155], v[146:147], v[154:155]
	global_load_dwordx4 v[178:181], v205, s[90:91]
	global_load_dwordx4 v[182:185], v205, s[90:91] offset:16
	global_load_dword v194, v206, s[92:93]
	s_nop 1
	v_mfma_f32_32x32x2_f32 v[64:79], v148, v24, 0
	v_mfma_f32_32x32x2_f32 v[80:95], v148, v32, 0
	v_mfma_f32_32x32x2_f32 v[96:111], v148, v40, 0
	v_mfma_f32_32x32x2_f32 v[112:127], v148, v48, 0
	v_mfma_f32_32x32x2_f32 v[64:79], v149, v25, v[64:79]
	v_mfma_f32_32x32x2_f32 v[80:95], v149, v33, v[80:95]
	v_mfma_f32_32x32x2_f32 v[96:111], v149, v41, v[96:111]
	v_mfma_f32_32x32x2_f32 v[112:127], v149, v49, v[112:127]
	v_mfma_f32_32x32x2_f32 v[64:79], v150, v26, v[64:79]
	v_mfma_f32_32x32x2_f32 v[80:95], v150, v34, v[80:95]
	v_mfma_f32_32x32x2_f32 v[96:111], v150, v42, v[96:111]
	v_mfma_f32_32x32x2_f32 v[112:127], v150, v50, v[112:127]
	v_mfma_f32_32x32x2_f32 v[64:79], v151, v27, v[64:79]
	v_mfma_f32_32x32x2_f32 v[80:95], v151, v35, v[80:95]
	v_mfma_f32_32x32x2_f32 v[96:111], v151, v43, v[96:111]
	v_mfma_f32_32x32x2_f32 v[112:127], v151, v51, v[112:127]
	v_mfma_f32_32x32x2_f32 v[64:79], v152, v28, v[64:79]
	v_mfma_f32_32x32x2_f32 v[80:95], v152, v36, v[80:95]
	v_mfma_f32_32x32x2_f32 v[96:111], v152, v44, v[96:111]
	v_mfma_f32_32x32x2_f32 v[112:127], v152, v52, v[112:127]
	v_mfma_f32_32x32x2_f32 v[64:79], v153, v29, v[64:79]
	v_mfma_f32_32x32x2_f32 v[80:95], v153, v37, v[80:95]
	v_mfma_f32_32x32x2_f32 v[96:111], v153, v45, v[96:111]
	v_mfma_f32_32x32x2_f32 v[112:127], v153, v53, v[112:127]
	v_mfma_f32_32x32x2_f32 v[64:79], v154, v30, v[64:79]
	v_mfma_f32_32x32x2_f32 v[80:95], v154, v38, v[80:95]
	v_mfma_f32_32x32x2_f32 v[96:111], v154, v46, v[96:111]
	v_mfma_f32_32x32x2_f32 v[112:127], v154, v54, v[112:127]
	v_mfma_f32_32x32x2_f32 v[64:79], v155, v31, v[64:79]
	v_mfma_f32_32x32x2_f32 v[80:95], v155, v39, v[80:95]
	v_mfma_f32_32x32x2_f32 v[96:111], v155, v47, v[96:111]
	v_mfma_f32_32x32x2_f32 v[112:127], v155, v55, v[112:127]
	s_nop 7
	s_nop 7
	s_nop 1
	v_fma_f32 v58, v64, v0, v65
	v_fma_f32 v59, v64, v1, v81
	v_fma_f32 v65, -v80, v1, v58
	v_fma_f32 v81, v80, v0, v59
	v_fma_f32 v128, v96, v2, v97
	v_fma_f32 v129, v96, v3, v113
	v_fma_f32 v97, -v112, v3, v128
	v_fma_f32 v113, v112, v2, v129
	v_fma_f32 v58, v68, v0, v69
	v_fma_f32 v59, v68, v1, v85
	v_fma_f32 v69, -v84, v1, v58
	v_fma_f32 v85, v84, v0, v59
	v_fma_f32 v128, v100, v2, v101
	v_fma_f32 v129, v100, v3, v117
	v_fma_f32 v101, -v116, v3, v128
	v_fma_f32 v117, v116, v2, v129
	v_fma_f32 v58, v72, v0, v73
	v_fma_f32 v59, v72, v1, v89
	v_fma_f32 v73, -v88, v1, v58
	v_fma_f32 v89, v88, v0, v59
	v_fma_f32 v128, v104, v2, v105
	v_fma_f32 v129, v104, v3, v121
	v_fma_f32 v105, -v120, v3, v128
	v_fma_f32 v121, v120, v2, v129
	v_fma_f32 v58, v76, v0, v77
	v_fma_f32 v59, v76, v1, v93
	v_fma_f32 v77, -v92, v1, v58
	v_fma_f32 v93, v92, v0, v59
	v_fma_f32 v128, v108, v2, v109
	v_fma_f32 v129, v108, v3, v125
	v_fma_f32 v109, -v124, v3, v128
	v_fma_f32 v125, v124, v2, v129
	v_fma_f32 v58, v65, v0, v66
	v_fma_f32 v59, v65, v1, v82
	v_fma_f32 v66, -v81, v1, v58
	v_fma_f32 v82, v81, v0, v59
	v_fma_f32 v128, v97, v2, v98
	v_fma_f32 v129, v97, v3, v114
	v_fma_f32 v98, -v113, v3, v128
	v_fma_f32 v114, v113, v2, v129
	v_fma_f32 v58, v69, v0, v70
	v_fma_f32 v59, v69, v1, v86
	v_fma_f32 v70, -v85, v1, v58
	v_fma_f32 v86, v85, v0, v59
	v_fma_f32 v128, v101, v2, v102
	v_fma_f32 v129, v101, v3, v118
	v_fma_f32 v102, -v117, v3, v128
	v_fma_f32 v118, v117, v2, v129
	v_fma_f32 v58, v73, v0, v74
	v_fma_f32 v59, v73, v1, v90
	v_fma_f32 v74, -v89, v1, v58
	v_fma_f32 v90, v89, v0, v59
	v_fma_f32 v128, v105, v2, v106
	v_fma_f32 v129, v105, v3, v122
	v_fma_f32 v106, -v121, v3, v128
	v_fma_f32 v122, v121, v2, v129
	v_fma_f32 v58, v77, v0, v78
	v_fma_f32 v59, v77, v1, v94
	v_fma_f32 v78, -v93, v1, v58
	v_fma_f32 v94, v93, v0, v59
	v_fma_f32 v128, v109, v2, v110
	v_fma_f32 v129, v109, v3, v126
	v_fma_f32 v110, -v125, v3, v128
	v_fma_f32 v126, v125, v2, v129
	v_fma_f32 v58, v66, v0, v67
	v_fma_f32 v59, v66, v1, v83
	v_fma_f32 v67, -v82, v1, v58
	v_fma_f32 v83, v82, v0, v59
	v_fma_f32 v128, v98, v2, v99
	v_fma_f32 v129, v98, v3, v115
	v_fma_f32 v99, -v114, v3, v128
	v_fma_f32 v115, v114, v2, v129
	v_fma_f32 v58, v70, v0, v71
	v_fma_f32 v59, v70, v1, v87
	v_fma_f32 v71, -v86, v1, v58
	v_fma_f32 v87, v86, v0, v59
	v_fma_f32 v128, v102, v2, v103
	v_fma_f32 v129, v102, v3, v119
	v_fma_f32 v103, -v118, v3, v128
	v_fma_f32 v119, v118, v2, v129
	v_fma_f32 v58, v74, v0, v75
	v_fma_f32 v59, v74, v1, v91
	v_fma_f32 v75, -v90, v1, v58
	v_fma_f32 v91, v90, v0, v59
	v_fma_f32 v128, v106, v2, v107
	v_fma_f32 v129, v106, v3, v123
	v_fma_f32 v107, -v122, v3, v128
	v_fma_f32 v123, v122, v2, v129
	v_fma_f32 v58, v78, v0, v79
	v_fma_f32 v59, v78, v1, v95
	v_fma_f32 v79, -v94, v1, v58
	v_fma_f32 v95, v94, v0, v59
	v_fma_f32 v128, v110, v2, v111
	v_fma_f32 v129, v110, v3, v127
	v_fma_f32 v111, -v126, v3, v128
	v_fma_f32 v127, v126, v2, v129
	v_fma_f32 v58, v18, v14, v67
	v_fma_f32 v59, v18, v15, v83
	v_fma_f32 v18, -v19, v15, v58
	v_fma_f32 v19, v19, v14, v59
	v_fma_f32 v128, v22, v16, v99
	v_fma_f32 v129, v22, v17, v115
	v_fma_f32 v22, -v23, v17, v128
	v_fma_f32 v23, v23, v16, v129
	v_fma_f32 v58, v18, v14, v71
	v_fma_f32 v59, v18, v15, v87
	v_fma_f32 v18, -v19, v15, v58
	v_fma_f32 v19, v19, v14, v59
	v_fma_f32 v128, v22, v16, v103
	v_fma_f32 v129, v22, v17, v119
	v_fma_f32 v22, -v23, v17, v128
	v_fma_f32 v23, v23, v16, v129
	v_fma_f32 v58, v18, v14, v75
	v_fma_f32 v59, v18, v15, v91
	v_fma_f32 v18, -v19, v15, v58
	v_fma_f32 v19, v19, v14, v59
	v_fma_f32 v128, v22, v16, v107
	v_fma_f32 v129, v22, v17, v123
	v_fma_f32 v22, -v23, v17, v128
	v_fma_f32 v23, v23, v16, v129
	v_fma_f32 v58, v18, v14, v79
	v_fma_f32 v59, v18, v15, v95
	v_fma_f32 v18, -v19, v15, v58
	v_fma_f32 v19, v19, v14, v59
	v_fma_f32 v128, v22, v16, v111
	v_fma_f32 v129, v22, v17, v127
	v_fma_f32 v22, -v23, v17, v128
	v_fma_f32 v23, v23, v16, v129
	s_cmp_eq_u32 s83, s82
	s_cbranch_scc1 .Ls5a_nocp
	s_lshl_b32 s35, s83, 3
	s_add_i32 s35, s35, s67
	s_add_i32 s35, s35, 0x13e80
	s_mul_hi_u32 s46, s35, 0x2ad5802b
	s_lshr_b32 s46, s46, 8
	s_mul_i32 s52, s46, 0x5fa
	s_sub_i32 s52, s35, s52
	s_lshl_b32 s52, s52, 13
	s_and_b32 s57, s46, 31
	s_mul_i32 s57, s57, 0xc00000
	s_add_i32 s52, s52, s57
	v_readfirstlane_b32 s98, v235
	v_readfirstlane_b32 s99, v236
	v_readfirstlane_b32 s65, v237
	v_readfirstlane_b32 s66, v238
	v_readfirstlane_b32 s100, v239
	v_readfirstlane_b32 s101, v240
	s_cmp_lt_u32 s46, 32
	s_cselect_b32 s98, s98, s65
	s_cselect_b32 s99, s99, s66
	s_mov_b32 s57, 0x1f210000
	s_cselect_b32 s57, 0x7210000, s57
	s_add_u32 s98, s98, s52
	s_addc_u32 s99, s99, 0
	s_add_u32 s98, s98, 0xc000
	s_addc_u32 s99, s99, 0
	s_add_u32 s57, s57, s52
	s_add_u32 s100, s100, s57
	s_addc_u32 s101, s101, 0
	global_load_dwordx4 v[210:213], v208, s[98:99] nt
	global_load_dwordx4 v[214:217], v208, s[98:99] offset:1024 nt
	global_load_dwordx4 v[218:221], v208, s[98:99] offset:2048 nt
	global_load_dwordx4 v[222:225], v208, s[98:99] offset:3072 nt
	global_load_dwordx4 v[226:229], v209, s[98:99] nt
	global_load_dwordx4 v[230:233], v209, s[98:99] offset:1024 nt
	global_load_dwordx4 v[242:245], v209, s[98:99] offset:2048 nt
	global_load_dwordx4 v[246:249], v209, s[98:99] offset:3072 nt
.Ls5a_nocp:
	v_fmamk_f32 v56, v195, 0x3a800000, v254
	v_rsq_f32_e32 v56, v56
	s_nop 0
	v_pk_mul_f32 v[148:149], v[186:187], v[56:57] op_sel_hi:[1,0]
	v_pk_mul_f32 v[150:151], v[188:189], v[56:57] op_sel_hi:[1,0]
	v_pk_mul_f32 v[152:153], v[190:191], v[56:57] op_sel_hi:[1,0]
	v_pk_mul_f32 v[154:155], v[192:193], v[56:57] op_sel_hi:[1,0]
	v_pk_mul_f32 v[148:149], v[140:141], v[148:149]
	v_pk_mul_f32 v[150:151], v[142:143], v[150:151]
	v_pk_mul_f32 v[152:153], v[144:145], v[152:153]
	v_pk_mul_f32 v[154:155], v[146:147], v[154:155]
	global_load_dwordx4 v[186:189], v205, s[94:95]
	global_load_dwordx4 v[190:193], v205, s[94:95] offset:16
	global_load_dword v195, v206, s[92:93] offset:128
	s_nop 1
	v_mfma_f32_32x32x2_f32 v[64:79], v148, v24, 0
	v_mfma_f32_32x32x2_f32 v[80:95], v148, v32, 0
	v_mfma_f32_32x32x2_f32 v[96:111], v148, v40, 0
	v_mfma_f32_32x32x2_f32 v[112:127], v148, v48, 0
	v_mfma_f32_32x32x2_f32 v[64:79], v149, v25, v[64:79]
	v_mfma_f32_32x32x2_f32 v[80:95], v149, v33, v[80:95]
	v_mfma_f32_32x32x2_f32 v[96:111], v149, v41, v[96:111]
	v_mfma_f32_32x32x2_f32 v[112:127], v149, v49, v[112:127]
	v_mfma_f32_32x32x2_f32 v[64:79], v150, v26, v[64:79]
	v_mfma_f32_32x32x2_f32 v[80:95], v150, v34, v[80:95]
	v_mfma_f32_32x32x2_f32 v[96:111], v150, v42, v[96:111]
	v_mfma_f32_32x32x2_f32 v[112:127], v150, v50, v[112:127]
	v_mfma_f32_32x32x2_f32 v[64:79], v151, v27, v[64:79]
	v_mfma_f32_32x32x2_f32 v[80:95], v151, v35, v[80:95]
	v_mfma_f32_32x32x2_f32 v[96:111], v151, v43, v[96:111]
	v_mfma_f32_32x32x2_f32 v[112:127], v151, v51, v[112:127]
	v_mfma_f32_32x32x2_f32 v[64:79], v152, v28, v[64:79]
	v_mfma_f32_32x32x2_f32 v[80:95], v152, v36, v[80:95]
	v_mfma_f32_32x32x2_f32 v[96:111], v152, v44, v[96:111]
	v_mfma_f32_32x32x2_f32 v[112:127], v152, v52, v[112:127]
	v_mfma_f32_32x32x2_f32 v[64:79], v153, v29, v[64:79]
	v_mfma_f32_32x32x2_f32 v[80:95], v153, v37, v[80:95]
	v_mfma_f32_32x32x2_f32 v[96:111], v153, v45, v[96:111]
	v_mfma_f32_32x32x2_f32 v[112:127], v153, v53, v[112:127]
	v_mfma_f32_32x32x2_f32 v[64:79], v154, v30, v[64:79]
	v_mfma_f32_32x32x2_f32 v[80:95], v154, v38, v[80:95]
	v_mfma_f32_32x32x2_f32 v[96:111], v154, v46, v[96:111]
	v_mfma_f32_32x32x2_f32 v[112:127], v154, v54, v[112:127]
	v_mfma_f32_32x32x2_f32 v[64:79], v155, v31, v[64:79]
	v_mfma_f32_32x32x2_f32 v[80:95], v155, v39, v[80:95]
	v_mfma_f32_32x32x2_f32 v[96:111], v155, v47, v[96:111]
	v_mfma_f32_32x32x2_f32 v[112:127], v155, v55, v[112:127]
	s_nop 7
	s_nop 7
	s_nop 1
	v_fma_f32 v58, v64, v0, v65
	v_fma_f32 v59, v64, v1, v81
	v_fma_f32 v65, -v80, v1, v58
	v_fma_f32 v81, v80, v0, v59
	v_fma_f32 v128, v96, v2, v97
	v_fma_f32 v129, v96, v3, v113
	v_fma_f32 v97, -v112, v3, v128
	v_fma_f32 v113, v112, v2, v129
	v_fma_f32 v58, v68, v0, v69
	v_fma_f32 v59, v68, v1, v85
	v_fma_f32 v69, -v84, v1, v58
	v_fma_f32 v85, v84, v0, v59
	v_fma_f32 v128, v100, v2, v101
	v_fma_f32 v129, v100, v3, v117
	v_fma_f32 v101, -v116, v3, v128
	v_fma_f32 v117, v116, v2, v129
	v_fma_f32 v58, v72, v0, v73
	v_fma_f32 v59, v72, v1, v89
	v_fma_f32 v73, -v88, v1, v58
	v_fma_f32 v89, v88, v0, v59
	v_fma_f32 v128, v104, v2, v105
	v_fma_f32 v129, v104, v3, v121
	v_fma_f32 v105, -v120, v3, v128
	v_fma_f32 v121, v120, v2, v129
	v_fma_f32 v58, v76, v0, v77
	v_fma_f32 v59, v76, v1, v93
	v_fma_f32 v77, -v92, v1, v58
	v_fma_f32 v93, v92, v0, v59
	v_fma_f32 v128, v108, v2, v109
	v_fma_f32 v129, v108, v3, v125
	v_fma_f32 v109, -v124, v3, v128
	v_fma_f32 v125, v124, v2, v129
	v_fma_f32 v58, v65, v0, v66
	v_fma_f32 v59, v65, v1, v82
	v_fma_f32 v66, -v81, v1, v58
	v_fma_f32 v82, v81, v0, v59
	v_fma_f32 v128, v97, v2, v98
	v_fma_f32 v129, v97, v3, v114
	v_fma_f32 v98, -v113, v3, v128
	v_fma_f32 v114, v113, v2, v129
	v_fma_f32 v58, v69, v0, v70
	v_fma_f32 v59, v69, v1, v86
	v_fma_f32 v70, -v85, v1, v58
	v_fma_f32 v86, v85, v0, v59
	v_fma_f32 v128, v101, v2, v102
	v_fma_f32 v129, v101, v3, v118
	v_fma_f32 v102, -v117, v3, v128
	v_fma_f32 v118, v117, v2, v129
	v_fma_f32 v58, v73, v0, v74
	v_fma_f32 v59, v73, v1, v90
	v_fma_f32 v74, -v89, v1, v58
	v_fma_f32 v90, v89, v0, v59
	v_fma_f32 v128, v105, v2, v106
	v_fma_f32 v129, v105, v3, v122
	v_fma_f32 v106, -v121, v3, v128
	v_fma_f32 v122, v121, v2, v129
	v_fma_f32 v58, v77, v0, v78
	v_fma_f32 v59, v77, v1, v94
	v_fma_f32 v78, -v93, v1, v58
	v_fma_f32 v94, v93, v0, v59
	v_fma_f32 v128, v109, v2, v110
	v_fma_f32 v129, v109, v3, v126
	v_fma_f32 v110, -v125, v3, v128
	v_fma_f32 v126, v125, v2, v129
	v_fma_f32 v58, v66, v0, v67
	v_fma_f32 v59, v66, v1, v83
	v_fma_f32 v67, -v82, v1, v58
	v_fma_f32 v83, v82, v0, v59
	v_fma_f32 v128, v98, v2, v99
	v_fma_f32 v129, v98, v3, v115
	v_fma_f32 v99, -v114, v3, v128
	v_fma_f32 v115, v114, v2, v129
	v_fma_f32 v58, v70, v0, v71
	v_fma_f32 v59, v70, v1, v87
	v_fma_f32 v71, -v86, v1, v58
	v_fma_f32 v87, v86, v0, v59
	v_fma_f32 v128, v102, v2, v103
	v_fma_f32 v129, v102, v3, v119
	v_fma_f32 v103, -v118, v3, v128
	v_fma_f32 v119, v118, v2, v129
	v_fma_f32 v58, v74, v0, v75
	v_fma_f32 v59, v74, v1, v91
	v_fma_f32 v75, -v90, v1, v58
	v_fma_f32 v91, v90, v0, v59
	v_fma_f32 v128, v106, v2, v107
	v_fma_f32 v129, v106, v3, v123
	v_fma_f32 v107, -v122, v3, v128
	v_fma_f32 v123, v122, v2, v129
	v_fma_f32 v58, v78, v0, v79
	v_fma_f32 v59, v78, v1, v95
	v_fma_f32 v79, -v94, v1, v58
	v_fma_f32 v95, v94, v0, v59
	v_fma_f32 v128, v110, v2, v111
	v_fma_f32 v129, v110, v3, v127
	v_fma_f32 v111, -v126, v3, v128
	v_fma_f32 v127, v126, v2, v129
	v_fma_f32 v58, v18, v14, v67
	v_fma_f32 v59, v18, v15, v83
	v_fma_f32 v18, -v19, v15, v58
	v_fma_f32 v19, v19, v14, v59
	v_fma_f32 v128, v22, v16, v99
	v_fma_f32 v129, v22, v17, v115
	v_fma_f32 v22, -v23, v17, v128
	v_fma_f32 v23, v23, v16, v129
	v_fma_f32 v58, v18, v14, v71
	v_fma_f32 v59, v18, v15, v87
	v_fma_f32 v18, -v19, v15, v58
	v_fma_f32 v19, v19, v14, v59
	v_fma_f32 v128, v22, v16, v103
	v_fma_f32 v129, v22, v17, v119
	v_fma_f32 v22, -v23, v17, v128
	v_fma_f32 v23, v23, v16, v129
	v_fma_f32 v58, v18, v14, v75
	v_fma_f32 v59, v18, v15, v91
	v_fma_f32 v18, -v19, v15, v58
	v_fma_f32 v19, v19, v14, v59
	v_fma_f32 v128, v22, v16, v107
	v_fma_f32 v129, v22, v17, v123
	v_fma_f32 v22, -v23, v17, v128
	v_fma_f32 v23, v23, v16, v129
	v_fma_f32 v58, v18, v14, v79
	v_fma_f32 v59, v18, v15, v95
	v_fma_f32 v18, -v19, v15, v58
	v_fma_f32 v19, v19, v14, v59
	v_fma_f32 v128, v22, v16, v111
	v_fma_f32 v129, v22, v17, v127
	v_fma_f32 v22, -v23, v17, v128
	v_fma_f32 v23, v23, v16, v129
	v_mov_b32_e32 v130, v18
	v_mov_b32_e32 v131, v19
	v_mov_b32_e32 v132, v22
	v_mov_b32_e32 v133, v23
	s_nop 1
	v_permlane32_swap_b32_e32 v18, v130
	v_permlane32_swap_b32_e32 v19, v131
	v_permlane32_swap_b32_e32 v22, v132
	v_permlane32_swap_b32_e32 v23, v133
	v_fma_f32 v58, v18, v8, v130
	v_fma_f32 v59, v18, v9, v131
	v_fma_f32 v134, -v19, v9, v58
	v_fma_f32 v135, v19, v8, v59
	v_fma_f32 v128, v22, v10, v132
	v_fma_f32 v129, v22, v11, v133
	v_fma_f32 v136, -v23, v11, v128
	v_fma_f32 v137, v23, v10, v129
	v_cndmask_b32_e64 v134, v134, v136, s[8:9]
	v_cndmask_b32_e64 v135, v135, v137, s[8:9]
	s_lshr_b32 s4, s82, 3
	s_lshl_b32 s4, s4, 15
	s_add_u32 s6, s28, s4
	s_addc_u32 s7, s29, 0
	global_store_dwordx2 v207, v[134:135], s[6:7]
	s_add_i32 s82, s82, 0x100
	s_cmpk_lt_i32 s82, 0x800
	s_cbranch_scc1 .Ls5a_item

.Ls5b_cin_done:
	s_nop 1
	v_permlane32_swap_b32_e32 v128, v130
	v_permlane32_swap_b32_e32 v129, v131
	s_waitcnt vmcnt(0)
	s_add_i32 s4, s31, 0
	s_lshl_b32 s4, s4, 11
	s_add_u32 s86, s12, s4
	s_addc_u32 s87, s13, 0
	s_add_u32 s88, s86, 0x8000
	s_addc_u32 s89, s87, 0
	v_fmamk_f32 v56, v194, 0x3a800000, v254
	v_rsq_f32_e32 v56, v56
	s_nop 0
	v_pk_mul_f32 v[148:149], v[178:179], v[56:57] op_sel_hi:[1,0]
	v_pk_mul_f32 v[150:151], v[180:181], v[56:57] op_sel_hi:[1,0]
	v_pk_mul_f32 v[152:153], v[182:183], v[56:57] op_sel_hi:[1,0]
	v_pk_mul_f32 v[154:155], v[184:185], v[56:57] op_sel_hi:[1,0]
	v_pk_mul_f32 v[148:149], v[140:141], v[148:149]
	v_pk_mul_f32 v[150:151], v[142:143], v[150:151]
	v_pk_mul_f32 v[152:153], v[144:145], v[152:153]
	v_pk_mul_f32 v[154:155], v[146:147], v[154:155]
	global_load_dwordx4 v[178:181], v227, s[90:91]
	global_load_dwordx4 v[182:185], v227, s[90:91] offset:16
	global_load_dword v194, v228, s[92:93]
	ds_write_b128 v231, v[148:151] offset:0
	ds_write_b128 v231, v[152:155] offset:16
	s_nop 1
	v_mfma_f32_32x32x2_f32 v[64:79], v148, v24, 0
	v_mfma_f32_32x32x2_f32 v[80:95], v148, v32, 0
	v_mfma_f32_32x32x2_f32 v[96:111], v148, v40, 0
	v_mfma_f32_32x32x2_f32 v[112:127], v148, v48, 0
	v_mfma_f32_32x32x2_f32 v[64:79], v149, v25, v[64:79]
	v_mfma_f32_32x32x2_f32 v[80:95], v149, v33, v[80:95]
	v_mfma_f32_32x32x2_f32 v[96:111], v149, v41, v[96:111]
	v_mfma_f32_32x32x2_f32 v[112:127], v149, v49, v[112:127]
	v_mfma_f32_32x32x2_f32 v[64:79], v150, v26, v[64:79]
	v_mfma_f32_32x32x2_f32 v[80:95], v150, v34, v[80:95]
	v_mfma_f32_32x32x2_f32 v[96:111], v150, v42, v[96:111]
	v_mfma_f32_32x32x2_f32 v[112:127], v150, v50, v[112:127]
	v_mfma_f32_32x32x2_f32 v[64:79], v151, v27, v[64:79]
	v_mfma_f32_32x32x2_f32 v[80:95], v151, v35, v[80:95]
	v_mfma_f32_32x32x2_f32 v[96:111], v151, v43, v[96:111]
	v_mfma_f32_32x32x2_f32 v[112:127], v151, v51, v[112:127]
	v_mfma_f32_32x32x2_f32 v[64:79], v152, v28, v[64:79]
	v_mfma_f32_32x32x2_f32 v[80:95], v152, v36, v[80:95]
	v_mfma_f32_32x32x2_f32 v[96:111], v152, v44, v[96:111]
	v_mfma_f32_32x32x2_f32 v[112:127], v152, v52, v[112:127]
	v_mfma_f32_32x32x2_f32 v[64:79], v153, v29, v[64:79]
	v_mfma_f32_32x32x2_f32 v[80:95], v153, v37, v[80:95]
	v_mfma_f32_32x32x2_f32 v[96:111], v153, v45, v[96:111]
	v_mfma_f32_32x32x2_f32 v[112:127], v153, v53, v[112:127]
	v_mfma_f32_32x32x2_f32 v[64:79], v154, v30, v[64:79]
	v_mfma_f32_32x32x2_f32 v[80:95], v154, v38, v[80:95]
	v_mfma_f32_32x32x2_f32 v[96:111], v154, v46, v[96:111]
	v_mfma_f32_32x32x2_f32 v[112:127], v154, v54, v[112:127]
	v_mfma_f32_32x32x2_f32 v[64:79], v155, v31, v[64:79]
	v_mfma_f32_32x32x2_f32 v[80:95], v155, v39, v[80:95]
	v_mfma_f32_32x32x2_f32 v[96:111], v155, v47, v[96:111]
	v_mfma_f32_32x32x2_f32 v[112:127], v155, v55, v[112:127]
	s_nop 7
	s_nop 7
	s_nop 1
	v_fmac_f32_e32 v65, v64, v0
	v_fmac_f32_e32 v97, v96, v8
	v_fmac_f32_e32 v69, v68, v0
	v_fmac_f32_e32 v101, v100, v8
	v_fmac_f32_e32 v73, v72, v0
	v_fmac_f32_e32 v105, v104, v8
	v_fmac_f32_e32 v77, v76, v0
	v_fmac_f32_e32 v109, v108, v8
	v_fmac_f32_e32 v81, v64, v4
	v_fmac_f32_e32 v113, v96, v14
	v_fmac_f32_e32 v85, v68, v4
	v_fmac_f32_e32 v117, v100, v14
	v_fmac_f32_e32 v89, v72, v4
	v_fmac_f32_e32 v121, v104, v14
	v_fmac_f32_e32 v93, v76, v4
	v_fmac_f32_e32 v125, v108, v14
	v_fma_f32 v65, -v80, v4, v65
	v_fma_f32 v97, -v112, v14, v97
	v_fma_f32 v69, -v84, v4, v69
	v_fma_f32 v101, -v116, v14, v101
	v_fma_f32 v73, -v88, v4, v73
	v_fma_f32 v105, -v120, v14, v105
	v_fma_f32 v77, -v92, v4, v77
	v_fma_f32 v109, -v124, v14, v109
	v_fmac_f32_e32 v81, v80, v0
	v_fmac_f32_e32 v113, v112, v8
	v_fmac_f32_e32 v85, v84, v0
	v_fmac_f32_e32 v117, v116, v8
	v_fmac_f32_e32 v89, v88, v0
	v_fmac_f32_e32 v121, v120, v8
	v_fmac_f32_e32 v93, v92, v0
	v_fmac_f32_e32 v125, v124, v8
	v_fmac_f32_e32 v66, v65, v0
	v_fmac_f32_e32 v98, v97, v8
	v_fmac_f32_e32 v70, v69, v0
	v_fmac_f32_e32 v102, v101, v8
	v_fmac_f32_e32 v74, v73, v0
	v_fmac_f32_e32 v106, v105, v8
	v_fmac_f32_e32 v78, v77, v0
	v_fmac_f32_e32 v110, v109, v8
	v_fmac_f32_e32 v82, v65, v4
	v_fmac_f32_e32 v114, v97, v14
	v_fmac_f32_e32 v86, v69, v4
	v_fmac_f32_e32 v118, v101, v14
	v_fmac_f32_e32 v90, v73, v4
	v_fmac_f32_e32 v122, v105, v14
	v_fmac_f32_e32 v94, v77, v4
	v_fmac_f32_e32 v126, v109, v14
	v_fma_f32 v66, -v81, v4, v66
	v_fma_f32 v98, -v113, v14, v98
	v_fma_f32 v70, -v85, v4, v70
	v_fma_f32 v102, -v117, v14, v102
	v_fma_f32 v74, -v89, v4, v74
	v_fma_f32 v106, -v121, v14, v106
	v_fma_f32 v78, -v93, v4, v78
	v_fma_f32 v110, -v125, v14, v110
	v_fmac_f32_e32 v82, v81, v0
	v_fmac_f32_e32 v114, v113, v8
	v_fmac_f32_e32 v86, v85, v0
	v_fmac_f32_e32 v118, v117, v8
	v_fmac_f32_e32 v90, v89, v0
	v_fmac_f32_e32 v122, v121, v8
	v_fmac_f32_e32 v94, v93, v0
	v_fmac_f32_e32 v126, v125, v8
	v_fmac_f32_e32 v67, v66, v0
	v_fmac_f32_e32 v99, v98, v8
	v_fmac_f32_e32 v71, v70, v0
	v_fmac_f32_e32 v103, v102, v8
	v_fmac_f32_e32 v75, v74, v0
	v_fmac_f32_e32 v107, v106, v8
	v_fmac_f32_e32 v79, v78, v0
	v_fmac_f32_e32 v111, v110, v8
	v_fmac_f32_e32 v83, v66, v4
	v_fmac_f32_e32 v115, v98, v14
	v_fmac_f32_e32 v87, v70, v4
	v_fmac_f32_e32 v119, v102, v14
	v_fmac_f32_e32 v91, v74, v4
	v_fmac_f32_e32 v123, v106, v14
	v_fmac_f32_e32 v95, v78, v4
	v_fmac_f32_e32 v127, v110, v14
	v_fma_f32 v67, -v82, v4, v67
	v_fma_f32 v99, -v114, v14, v99
	v_fma_f32 v71, -v86, v4, v71
	v_fma_f32 v103, -v118, v14, v103
	v_fma_f32 v75, -v90, v4, v75
	v_fma_f32 v107, -v122, v14, v107
	v_fma_f32 v79, -v94, v4, v79
	v_fma_f32 v111, -v126, v14, v111
	v_fmac_f32_e32 v83, v82, v0
	v_fmac_f32_e32 v115, v114, v8
	v_fmac_f32_e32 v87, v86, v0
	v_fmac_f32_e32 v119, v118, v8
	v_fmac_f32_e32 v91, v90, v0
	v_fmac_f32_e32 v123, v122, v8
	v_fmac_f32_e32 v95, v94, v0
	v_fmac_f32_e32 v127, v126, v8
	v_mov_b32_e32 v158, v67
	v_mov_b32_e32 v160, v67
	v_mov_b32_e32 v159, v83
	v_mov_b32_e32 v161, v83
	v_mov_b32_e32 v164, v99
	v_mov_b32_e32 v166, v99
	v_mov_b32_e32 v165, v115
	v_mov_b32_e32 v167, v115
	s_nop 1
	v_permlane32_swap_b32_e32 v158, v160
	v_permlane32_swap_b32_e32 v159, v161
	v_permlane32_swap_b32_e32 v164, v166
	v_permlane32_swap_b32_e32 v165, v167
	v_fma_f32 v168, v128, v3, v158
	v_fma_f32 v170, v130, v11, v164
	v_fma_f32 v169, v128, v7, v159
	v_fma_f32 v171, v130, v17, v165
	v_fma_f32 v132, -v129, v7, v168
	v_fma_f32 v134, -v131, v17, v170
	v_fma_f32 v133, v129, v3, v169
	v_fma_f32 v135, v131, v11, v171
	v_cndmask_b32_e64 v136, v128, v132, s[8:9]
	v_cndmask_b32_e64 v137, v129, v133, s[8:9]
	v_cndmask_b32_e64 v156, v130, v134, s[8:9]
	v_cndmask_b32_e64 v157, v131, v135, s[8:9]
	v_fma_f32 v168, v132, v3, v160
	v_fma_f32 v170, v134, v11, v166
	v_fma_f32 v169, v132, v7, v161
	v_fma_f32 v171, v134, v17, v167
	v_fma_f32 v128, -v133, v7, v168
	v_fma_f32 v130, -v135, v17, v170
	v_fma_f32 v129, v133, v3, v169
	v_fma_f32 v131, v135, v11, v171
	v_mov_b32_e32 v246, v128
	v_mov_b32_e32 v247, v129
	v_mov_b32_e32 v248, v130
	v_mov_b32_e32 v249, v131
	v_pk_fma_f32 v[64:65], v[0:1], v[136:137], v[64:65] op_sel_hi:[1,0,1]
	v_mov_b32_e32 v158, v71
	v_pk_fma_f32 v[80:81], v[0:1], v[136:137], v[80:81] op_sel:[0,1,0]
	v_mov_b32_e32 v160, v71
	v_pk_fma_f32 v[66:67], v[2:3], v[136:137], v[66:67] op_sel_hi:[1,0,1]
	v_mov_b32_e32 v159, v87
	v_pk_fma_f32 v[82:83], v[2:3], v[136:137], v[82:83] op_sel:[0,1,0]
	v_mov_b32_e32 v161, v87
	v_pk_fma_f32 v[96:97], v[8:9], v[156:157], v[96:97] op_sel_hi:[1,0,1]
	v_mov_b32_e32 v164, v103
	v_pk_fma_f32 v[112:113], v[8:9], v[156:157], v[112:113] op_sel:[0,1,0]
	v_mov_b32_e32 v166, v103
	v_pk_fma_f32 v[98:99], v[10:11], v[156:157], v[98:99] op_sel_hi:[1,0,1]
	v_mov_b32_e32 v165, v119
	v_pk_fma_f32 v[114:115], v[10:11], v[156:157], v[114:115] op_sel:[0,1,0]
	v_mov_b32_e32 v167, v119
	v_pk_fma_f32 v[64:65], v[4:5], v[136:137], v[64:65] op_sel:[0,1,0] neg_lo:[1,0,0] neg_hi:[1,0,0]
	s_nop 1
	v_pk_fma_f32 v[80:81], v[4:5], v[136:137], v[80:81] op_sel_hi:[1,0,1]
	v_permlane32_swap_b32_e32 v158, v160
	v_pk_fma_f32 v[66:67], v[6:7], v[136:137], v[66:67] op_sel:[0,1,0] neg_lo:[1,0,0] neg_hi:[1,0,0]
	v_permlane32_swap_b32_e32 v159, v161
	v_pk_fma_f32 v[82:83], v[6:7], v[136:137], v[82:83] op_sel_hi:[1,0,1]
	v_permlane32_swap_b32_e32 v164, v166
	v_pk_fma_f32 v[96:97], v[14:15], v[156:157], v[96:97] op_sel:[0,1,0] neg_lo:[1,0,0] neg_hi:[1,0,0]
	v_permlane32_swap_b32_e32 v165, v167
	v_pk_fma_f32 v[112:113], v[14:15], v[156:157], v[112:113] op_sel_hi:[1,0,1]
	v_fma_f32 v168, v128, v3, v158
	v_pk_fma_f32 v[98:99], v[16:17], v[156:157], v[98:99] op_sel:[0,1,0] neg_lo:[1,0,0] neg_hi:[1,0,0]
	v_fma_f32 v170, v130, v11, v164
	v_pk_fma_f32 v[114:115], v[16:17], v[156:157], v[114:115] op_sel_hi:[1,0,1]
	v_fma_f32 v169, v128, v7, v159
	v_fma_f32 v171, v130, v17, v165
	v_fma_f32 v132, -v129, v7, v168
	v_fma_f32 v134, -v131, v17, v170
	v_fma_f32 v133, v129, v3, v169
	v_fma_f32 v135, v131, v11, v171
	v_cndmask_b32_e64 v172, v128, v132, s[8:9]
	v_cndmask_b32_e64 v173, v129, v133, s[8:9]
	v_cndmask_b32_e64 v244, v130, v134, s[8:9]
	v_cndmask_b32_e64 v245, v131, v135, s[8:9]
	v_fma_f32 v168, v132, v3, v160
	v_fma_f32 v170, v134, v11, v166
	v_fma_f32 v169, v132, v7, v161
	v_fma_f32 v171, v134, v17, v167
	v_fma_f32 v128, -v133, v7, v168
	v_fma_f32 v130, -v135, v17, v170
	v_fma_f32 v129, v133, v3, v169
	v_fma_f32 v131, v135, v11, v171
	v_pk_fma_f32 v[68:69], v[0:1], v[172:173], v[68:69] op_sel_hi:[1,0,1]
	v_mov_b32_e32 v158, v75
	v_pk_fma_f32 v[84:85], v[0:1], v[172:173], v[84:85] op_sel:[0,1,0]
	v_mov_b32_e32 v160, v75
	v_pk_fma_f32 v[70:71], v[2:3], v[172:173], v[70:71] op_sel_hi:[1,0,1]
	v_mov_b32_e32 v159, v91
	v_pk_fma_f32 v[86:87], v[2:3], v[172:173], v[86:87] op_sel:[0,1,0]
	v_mov_b32_e32 v161, v91
	v_pk_fma_f32 v[100:101], v[8:9], v[244:245], v[100:101] op_sel_hi:[1,0,1]
	v_mov_b32_e32 v164, v107
	v_pk_fma_f32 v[116:117], v[8:9], v[244:245], v[116:117] op_sel:[0,1,0]
	v_mov_b32_e32 v166, v107
	v_pk_fma_f32 v[102:103], v[10:11], v[244:245], v[102:103] op_sel_hi:[1,0,1]
	v_mov_b32_e32 v165, v123
	v_pk_fma_f32 v[118:119], v[10:11], v[244:245], v[118:119] op_sel:[0,1,0]
	v_mov_b32_e32 v167, v123
	v_pk_fma_f32 v[68:69], v[4:5], v[172:173], v[68:69] op_sel:[0,1,0] neg_lo:[1,0,0] neg_hi:[1,0,0]
	s_nop 1
	v_pk_fma_f32 v[84:85], v[4:5], v[172:173], v[84:85] op_sel_hi:[1,0,1]
	v_permlane32_swap_b32_e32 v158, v160
	v_pk_fma_f32 v[70:71], v[6:7], v[172:173], v[70:71] op_sel:[0,1,0] neg_lo:[1,0,0] neg_hi:[1,0,0]
	v_permlane32_swap_b32_e32 v159, v161
	v_pk_fma_f32 v[86:87], v[6:7], v[172:173], v[86:87] op_sel_hi:[1,0,1]
	v_permlane32_swap_b32_e32 v164, v166
	v_pk_fma_f32 v[100:101], v[14:15], v[244:245], v[100:101] op_sel:[0,1,0] neg_lo:[1,0,0] neg_hi:[1,0,0]
	v_permlane32_swap_b32_e32 v165, v167
	v_pk_fma_f32 v[116:117], v[14:15], v[244:245], v[116:117] op_sel_hi:[1,0,1]
	v_fma_f32 v168, v128, v3, v158
	v_pk_fma_f32 v[102:103], v[16:17], v[244:245], v[102:103] op_sel:[0,1,0] neg_lo:[1,0,0] neg_hi:[1,0,0]
	v_fma_f32 v170, v130, v11, v164
	v_pk_fma_f32 v[118:119], v[16:17], v[244:245], v[118:119] op_sel_hi:[1,0,1]
	v_fma_f32 v169, v128, v7, v159
	v_fma_f32 v171, v130, v17, v165
	v_fma_f32 v132, -v129, v7, v168
	v_fma_f32 v134, -v131, v17, v170
	v_fma_f32 v133, v129, v3, v169
	v_fma_f32 v135, v131, v11, v171
	v_cndmask_b32_e64 v136, v128, v132, s[8:9]
	v_cndmask_b32_e64 v137, v129, v133, s[8:9]
	v_cndmask_b32_e64 v156, v130, v134, s[8:9]
	v_cndmask_b32_e64 v157, v131, v135, s[8:9]
	v_fma_f32 v168, v132, v3, v160
	v_fma_f32 v170, v134, v11, v166
	v_fma_f32 v169, v132, v7, v161
	v_fma_f32 v171, v134, v17, v167
	v_fma_f32 v128, -v133, v7, v168
	v_fma_f32 v130, -v135, v17, v170
	v_fma_f32 v129, v133, v3, v169
	v_fma_f32 v131, v135, v11, v171
	v_pk_fma_f32 v[72:73], v[0:1], v[136:137], v[72:73] op_sel_hi:[1,0,1]
	v_mov_b32_e32 v158, v79
	v_pk_fma_f32 v[88:89], v[0:1], v[136:137], v[88:89] op_sel:[0,1,0]
	v_mov_b32_e32 v160, v79
	v_pk_fma_f32 v[74:75], v[2:3], v[136:137], v[74:75] op_sel_hi:[1,0,1]
	v_mov_b32_e32 v159, v95
	v_pk_fma_f32 v[90:91], v[2:3], v[136:137], v[90:91] op_sel:[0,1,0]
	v_mov_b32_e32 v161, v95
	v_pk_fma_f32 v[104:105], v[8:9], v[156:157], v[104:105] op_sel_hi:[1,0,1]
	v_mov_b32_e32 v164, v111
	v_pk_fma_f32 v[120:121], v[8:9], v[156:157], v[120:121] op_sel:[0,1,0]
	v_mov_b32_e32 v166, v111
	v_pk_fma_f32 v[106:107], v[10:11], v[156:157], v[106:107] op_sel_hi:[1,0,1]
	v_mov_b32_e32 v165, v127
	v_pk_fma_f32 v[122:123], v[10:11], v[156:157], v[122:123] op_sel:[0,1,0]
	v_mov_b32_e32 v167, v127
	v_pk_fma_f32 v[72:73], v[4:5], v[136:137], v[72:73] op_sel:[0,1,0] neg_lo:[1,0,0] neg_hi:[1,0,0]
	s_nop 1
	v_pk_fma_f32 v[88:89], v[4:5], v[136:137], v[88:89] op_sel_hi:[1,0,1]
	v_permlane32_swap_b32_e32 v158, v160
	v_pk_fma_f32 v[74:75], v[6:7], v[136:137], v[74:75] op_sel:[0,1,0] neg_lo:[1,0,0] neg_hi:[1,0,0]
	v_permlane32_swap_b32_e32 v159, v161
	v_pk_fma_f32 v[90:91], v[6:7], v[136:137], v[90:91] op_sel_hi:[1,0,1]
	v_permlane32_swap_b32_e32 v164, v166
	v_pk_fma_f32 v[104:105], v[14:15], v[156:157], v[104:105] op_sel:[0,1,0] neg_lo:[1,0,0] neg_hi:[1,0,0]
	v_permlane32_swap_b32_e32 v165, v167
	v_pk_fma_f32 v[120:121], v[14:15], v[156:157], v[120:121] op_sel_hi:[1,0,1]
	v_fma_f32 v168, v128, v3, v158
	v_pk_fma_f32 v[106:107], v[16:17], v[156:157], v[106:107] op_sel:[0,1,0] neg_lo:[1,0,0] neg_hi:[1,0,0]
	v_fma_f32 v170, v130, v11, v164
	v_pk_fma_f32 v[122:123], v[16:17], v[156:157], v[122:123] op_sel_hi:[1,0,1]
	v_fma_f32 v169, v128, v7, v159
	v_fma_f32 v171, v130, v17, v165
	v_fma_f32 v132, -v129, v7, v168
	v_fma_f32 v134, -v131, v17, v170
	v_fma_f32 v133, v129, v3, v169
	v_fma_f32 v135, v131, v11, v171
	v_cndmask_b32_e64 v172, v128, v132, s[8:9]
	v_cndmask_b32_e64 v173, v129, v133, s[8:9]
	v_cndmask_b32_e64 v244, v130, v134, s[8:9]
	v_cndmask_b32_e64 v245, v131, v135, s[8:9]
	v_fma_f32 v168, v132, v3, v160
	v_fma_f32 v170, v134, v11, v166
	v_fma_f32 v169, v132, v7, v161
	v_fma_f32 v171, v134, v17, v167
	v_fma_f32 v128, -v133, v7, v168
	v_fma_f32 v130, -v135, v17, v170
	v_fma_f32 v129, v133, v3, v169
	v_fma_f32 v131, v135, v11, v171
	v_pk_fma_f32 v[76:77], v[0:1], v[172:173], v[76:77] op_sel_hi:[1,0,1]
	v_pk_fma_f32 v[92:93], v[0:1], v[172:173], v[92:93] op_sel:[0,1,0]
	v_pk_fma_f32 v[78:79], v[2:3], v[172:173], v[78:79] op_sel_hi:[1,0,1]
	v_pk_fma_f32 v[94:95], v[2:3], v[172:173], v[94:95] op_sel:[0,1,0]
	v_pk_fma_f32 v[108:109], v[8:9], v[244:245], v[108:109] op_sel_hi:[1,0,1]
	v_pk_fma_f32 v[124:125], v[8:9], v[244:245], v[124:125] op_sel:[0,1,0]
	v_pk_fma_f32 v[110:111], v[10:11], v[244:245], v[110:111] op_sel_hi:[1,0,1]
	v_pk_fma_f32 v[126:127], v[10:11], v[244:245], v[126:127] op_sel:[0,1,0]
	v_pk_fma_f32 v[76:77], v[4:5], v[172:173], v[76:77] op_sel:[0,1,0] neg_lo:[1,0,0] neg_hi:[1,0,0]
	v_pk_fma_f32 v[92:93], v[4:5], v[172:173], v[92:93] op_sel_hi:[1,0,1]
	v_pk_fma_f32 v[78:79], v[6:7], v[172:173], v[78:79] op_sel:[0,1,0] neg_lo:[1,0,0] neg_hi:[1,0,0]
	v_pk_fma_f32 v[94:95], v[6:7], v[172:173], v[94:95] op_sel_hi:[1,0,1]
	v_pk_fma_f32 v[108:109], v[14:15], v[244:245], v[108:109] op_sel:[0,1,0] neg_lo:[1,0,0] neg_hi:[1,0,0]
	v_pk_fma_f32 v[124:125], v[14:15], v[244:245], v[124:125] op_sel_hi:[1,0,1]
	v_pk_fma_f32 v[110:111], v[16:17], v[244:245], v[110:111] op_sel:[0,1,0] neg_lo:[1,0,0] neg_hi:[1,0,0]
	v_pk_fma_f32 v[126:127], v[16:17], v[244:245], v[126:127] op_sel_hi:[1,0,1]
	v_cvt_pk_bf16_f32 v56, v64, v80
	ds_write_b32 v229, v56 offset:0
	v_cvt_pk_bf16_f32 v57, v96, v112
	ds_write_b32 v229, v57 offset:128
	v_cvt_pk_bf16_f32 v58, v65, v81
	ds_write_b32 v229, v58 offset:272
	v_cvt_pk_bf16_f32 v59, v97, v113
	ds_write_b32 v229, v59 offset:400
	v_cvt_pk_bf16_f32 v56, v66, v82
	ds_write_b32 v229, v56 offset:544
	v_cvt_pk_bf16_f32 v57, v98, v114
	ds_write_b32 v229, v57 offset:672
	v_cvt_pk_bf16_f32 v58, v67, v83
	ds_write_b32 v229, v58 offset:816
	v_cvt_pk_bf16_f32 v59, v99, v115
	ds_write_b32 v229, v59 offset:944
	v_cvt_pk_bf16_f32 v56, v68, v84
	ds_write_b32 v229, v56 offset:2176
	v_cvt_pk_bf16_f32 v57, v100, v116
	ds_write_b32 v229, v57 offset:2304
	v_cvt_pk_bf16_f32 v58, v69, v85
	ds_write_b32 v229, v58 offset:2448
	v_cvt_pk_bf16_f32 v59, v101, v117
	ds_write_b32 v229, v59 offset:2576
	v_cvt_pk_bf16_f32 v56, v70, v86
	ds_write_b32 v229, v56 offset:2720
	v_cvt_pk_bf16_f32 v57, v102, v118
	ds_write_b32 v229, v57 offset:2848
	v_cvt_pk_bf16_f32 v58, v71, v87
	ds_write_b32 v229, v58 offset:2992
	v_cvt_pk_bf16_f32 v59, v103, v119
	ds_write_b32 v229, v59 offset:3120
	v_cvt_pk_bf16_f32 v56, v72, v88
	ds_write_b32 v229, v56 offset:4352
	v_cvt_pk_bf16_f32 v57, v104, v120
	ds_write_b32 v229, v57 offset:4480
	v_cvt_pk_bf16_f32 v58, v73, v89
	ds_write_b32 v229, v58 offset:4624
	v_cvt_pk_bf16_f32 v59, v105, v121
	ds_write_b32 v229, v59 offset:4752
	v_cvt_pk_bf16_f32 v56, v74, v90
	ds_write_b32 v229, v56 offset:4896
	v_cvt_pk_bf16_f32 v57, v106, v122
	ds_write_b32 v229, v57 offset:5024
	v_cvt_pk_bf16_f32 v58, v75, v91
	ds_write_b32 v229, v58 offset:5168
	v_cvt_pk_bf16_f32 v59, v107, v123
	ds_write_b32 v229, v59 offset:5296
	v_cvt_pk_bf16_f32 v56, v76, v92
	ds_write_b32 v229, v56 offset:6528
	v_cvt_pk_bf16_f32 v57, v108, v124
	ds_write_b32 v229, v57 offset:6656
	v_cvt_pk_bf16_f32 v58, v77, v93
	ds_write_b32 v229, v58 offset:6800
	v_cvt_pk_bf16_f32 v59, v109, v125
	ds_write_b32 v229, v59 offset:6928
	v_cvt_pk_bf16_f32 v56, v78, v94
	ds_write_b32 v229, v56 offset:7072
	v_cvt_pk_bf16_f32 v57, v110, v126
	ds_write_b32 v229, v57 offset:7200
	v_cvt_pk_bf16_f32 v58, v79, v95
	ds_write_b32 v229, v58 offset:7344
	v_cvt_pk_bf16_f32 v59, v111, v127
	ds_write_b32 v229, v59 offset:7472
	ds_read_b128 v[164:167], v230 offset:0
	ds_read_b128 v[168:171], v230 offset:64
	ds_read_b128 v[156:159], v230 offset:128
	ds_read_b128 v[132:135], v230 offset:192
	ds_read_b32 v56, v232 offset:0
	ds_read_b32 v57, v232 offset:64
	ds_read_b32 v58, v232 offset:128
	ds_read_b32 v59, v232 offset:192
	s_waitcnt lgkmcnt(7)
	v_mfma_f32_16x16x32_bf16 v[250:253], v[164:167], v[208:211], 0
	s_waitcnt lgkmcnt(6)
	v_mfma_f32_16x16x32_bf16 v[250:253], v[168:171], v[212:215], v[250:253]
	s_waitcnt lgkmcnt(5)
	v_mfma_f32_16x16x32_bf16 v[250:253], v[156:159], v[216:219], v[250:253]
	s_waitcnt lgkmcnt(4)
	v_mfma_f32_16x16x32_bf16 v[250:253], v[132:135], v[220:223], v[250:253]
	s_waitcnt lgkmcnt(0)
	s_nop 7
	s_nop 1
	v_fma_f32 v250, v224, v56, v250
	v_fma_f32 v251, v224, v57, v251
	v_fma_f32 v252, v224, v58, v252
	v_fma_f32 v253, v224, v59, v253
	v_mul_f32_e32 v60, 0x3d372713, v250
	v_mul_f32_e32 v172, 0x3d372713, v251
	v_mul_f32_e32 v173, 0x3d372713, v252
	v_mul_f32_e32 v245, 0x3d372713, v253
	v_mul_f32_e32 v60, v250, v60
	v_mul_f32_e32 v172, v251, v172
	v_mul_f32_e32 v173, v252, v173
	v_mul_f32_e32 v245, v253, v245
	v_fma_f32 v60, v250, v60, v250
	v_fma_f32 v172, v251, v172, v251
	v_fma_f32 v173, v252, v173, v252
	v_fma_f32 v245, v253, v245, v253
	v_mul_f32_e32 v60, 0x3f4c422a, v60
	v_mul_f32_e32 v172, 0x3f4c422a, v172
	v_mul_f32_e32 v173, 0x3f4c422a, v173
	v_mul_f32_e32 v245, 0x3f4c422a, v245
	v_add_f32_e32 v60, v60, v60
	v_add_f32_e32 v172, v172, v172
	v_add_f32_e32 v173, v173, v173
	v_add_f32_e32 v245, v245, v245
	v_mul_f32_e32 v60, 0x3fb8aa3b, v60
	v_mul_f32_e32 v172, 0x3fb8aa3b, v172
	v_mul_f32_e32 v173, 0x3fb8aa3b, v173
	v_mul_f32_e32 v245, 0x3fb8aa3b, v245
	v_exp_f32_e32 v60, v60
	v_exp_f32_e32 v172, v172
	v_exp_f32_e32 v173, v173
	v_exp_f32_e32 v245, v245
	v_mul_f32_e32 v250, 0.5, v250
	v_mul_f32_e32 v251, 0.5, v251
	v_mul_f32_e32 v252, 0.5, v252
	v_mul_f32_e32 v253, 0.5, v253
	v_add_f32_e32 v60, 1.0, v60
	v_add_f32_e32 v172, 1.0, v172
	v_add_f32_e32 v173, 1.0, v173
	v_add_f32_e32 v245, 1.0, v245
	v_rcp_f32_e32 v60, v60
	v_rcp_f32_e32 v172, v172
	v_rcp_f32_e32 v173, v173
	v_rcp_f32_e32 v245, v245
	s_nop 0
	v_fma_f32 v60, v60, -2.0, 1.0
	v_fma_f32 v172, v172, -2.0, 1.0
	v_fma_f32 v173, v173, -2.0, 1.0
	v_fma_f32 v245, v245, -2.0, 1.0
	v_add_f32_e32 v60, 1.0, v60
	v_add_f32_e32 v172, 1.0, v172
	v_add_f32_e32 v173, 1.0, v173
	v_add_f32_e32 v245, 1.0, v245
	v_mul_f32_e32 v250, v250, v60
	v_mul_f32_e32 v251, v251, v172
	v_mul_f32_e32 v252, v252, v173
	v_mul_f32_e32 v253, v253, v245
	v_cvt_pk_bf16_f32 v250, v250, 0
	v_cvt_pk_bf16_f32 v251, v251, 0
	v_cvt_pk_bf16_f32 v252, v252, 0
	v_cvt_pk_bf16_f32 v253, v253, 0
	s_cmp_lg_u32 s35, 0
	s_cselect_b32 s4, 0, -1
	s_mov_b32 exec_hi, s4
	global_store_short v233, v250, s[86:87]
	global_store_short v241, v251, s[86:87]
	global_store_short v242, v252, s[86:87]
	global_store_short v243, v253, s[86:87]
	s_mov_b32 exec_hi, -1
	s_cmp_lg_u32 s35, 0
	s_cbranch_scc1 .Ls5b_ep_skip0
	ds_read_b128 v[164:167], v230 offset:4352
	ds_read_b128 v[168:171], v230 offset:4416
	ds_read_b128 v[156:159], v230 offset:4480
	ds_read_b128 v[132:135], v230 offset:4544
	ds_read_b32 v56, v232 offset:1024
	ds_read_b32 v57, v232 offset:1088
	ds_read_b32 v58, v232 offset:1152
	ds_read_b32 v59, v232 offset:1216
	s_waitcnt lgkmcnt(7)
	v_mfma_f32_16x16x32_bf16 v[250:253], v[164:167], v[208:211], 0
	s_waitcnt lgkmcnt(6)
	v_mfma_f32_16x16x32_bf16 v[250:253], v[168:171], v[212:215], v[250:253]
	s_waitcnt lgkmcnt(5)
	v_mfma_f32_16x16x32_bf16 v[250:253], v[156:159], v[216:219], v[250:253]
	s_waitcnt lgkmcnt(4)
	v_mfma_f32_16x16x32_bf16 v[250:253], v[132:135], v[220:223], v[250:253]
	s_waitcnt lgkmcnt(0)
	s_nop 7
	s_nop 1
	v_fma_f32 v250, v224, v56, v250
	v_fma_f32 v251, v224, v57, v251
	v_fma_f32 v252, v224, v58, v252
	v_fma_f32 v253, v224, v59, v253
	v_mul_f32_e32 v60, 0x3d372713, v250
	v_mul_f32_e32 v172, 0x3d372713, v251
	v_mul_f32_e32 v173, 0x3d372713, v252
	v_mul_f32_e32 v245, 0x3d372713, v253
	v_mul_f32_e32 v60, v250, v60
	v_mul_f32_e32 v172, v251, v172
	v_mul_f32_e32 v173, v252, v173
	v_mul_f32_e32 v245, v253, v245
	v_fma_f32 v60, v250, v60, v250
	v_fma_f32 v172, v251, v172, v251
	v_fma_f32 v173, v252, v173, v252
	v_fma_f32 v245, v253, v245, v253
	v_mul_f32_e32 v60, 0x3f4c422a, v60
	v_mul_f32_e32 v172, 0x3f4c422a, v172
	v_mul_f32_e32 v173, 0x3f4c422a, v173
	v_mul_f32_e32 v245, 0x3f4c422a, v245
	v_add_f32_e32 v60, v60, v60
	v_add_f32_e32 v172, v172, v172
	v_add_f32_e32 v173, v173, v173
	v_add_f32_e32 v245, v245, v245
	v_mul_f32_e32 v60, 0x3fb8aa3b, v60
	v_mul_f32_e32 v172, 0x3fb8aa3b, v172
	v_mul_f32_e32 v173, 0x3fb8aa3b, v173
	v_mul_f32_e32 v245, 0x3fb8aa3b, v245
	v_exp_f32_e32 v60, v60
	v_exp_f32_e32 v172, v172
	v_exp_f32_e32 v173, v173
	v_exp_f32_e32 v245, v245
	v_mul_f32_e32 v250, 0.5, v250
	v_mul_f32_e32 v251, 0.5, v251
	v_mul_f32_e32 v252, 0.5, v252
	v_mul_f32_e32 v253, 0.5, v253
	v_add_f32_e32 v60, 1.0, v60
	v_add_f32_e32 v172, 1.0, v172
	v_add_f32_e32 v173, 1.0, v173
	v_add_f32_e32 v245, 1.0, v245
	v_rcp_f32_e32 v60, v60
	v_rcp_f32_e32 v172, v172
	v_rcp_f32_e32 v173, v173
	v_rcp_f32_e32 v245, v245
	s_nop 0
	v_fma_f32 v60, v60, -2.0, 1.0
	v_fma_f32 v172, v172, -2.0, 1.0
	v_fma_f32 v173, v173, -2.0, 1.0
	v_fma_f32 v245, v245, -2.0, 1.0
	v_add_f32_e32 v60, 1.0, v60
	v_add_f32_e32 v172, 1.0, v172
	v_add_f32_e32 v173, 1.0, v173
	v_add_f32_e32 v245, 1.0, v245
	v_mul_f32_e32 v250, v250, v60
	v_mul_f32_e32 v251, v251, v172
	v_mul_f32_e32 v252, v252, v173
	v_mul_f32_e32 v253, v253, v245
	v_cvt_pk_bf16_f32 v250, v250, 0
	v_cvt_pk_bf16_f32 v251, v251, 0
	v_cvt_pk_bf16_f32 v252, v252, 0
	v_cvt_pk_bf16_f32 v253, v253, 0
	global_store_short v233, v250, s[88:89]
	global_store_short v241, v251, s[88:89]
	global_store_short v242, v252, s[88:89]
	global_store_short v243, v253, s[88:89]

.Ls5b_nopf:
	ds_read_b128 v[164:167], v230 offset:0
	ds_read_b128 v[168:171], v230 offset:64
	ds_read_b128 v[156:159], v230 offset:128
	ds_read_b128 v[132:135], v230 offset:192
	ds_read_b32 v56, v232 offset:0
	ds_read_b32 v57, v232 offset:64
	ds_read_b32 v58, v232 offset:128
	ds_read_b32 v59, v232 offset:192
	s_waitcnt lgkmcnt(7)
	v_mfma_f32_16x16x32_bf16 v[250:253], v[164:167], v[208:211], 0
	s_waitcnt lgkmcnt(6)
	v_mfma_f32_16x16x32_bf16 v[250:253], v[168:171], v[212:215], v[250:253]
	s_waitcnt lgkmcnt(5)
	v_mfma_f32_16x16x32_bf16 v[250:253], v[156:159], v[216:219], v[250:253]
	s_waitcnt lgkmcnt(4)
	v_mfma_f32_16x16x32_bf16 v[250:253], v[132:135], v[220:223], v[250:253]
	s_waitcnt lgkmcnt(0)
	s_nop 7
	s_nop 1
	v_fma_f32 v250, v224, v56, v250
	v_fma_f32 v251, v224, v57, v251
	v_fma_f32 v252, v224, v58, v252
	v_fma_f32 v253, v224, v59, v253
	v_mul_f32_e32 v60, 0x3d372713, v250
	v_mul_f32_e32 v172, 0x3d372713, v251
	v_mul_f32_e32 v173, 0x3d372713, v252
	v_mul_f32_e32 v245, 0x3d372713, v253
	v_mul_f32_e32 v60, v250, v60
	v_mul_f32_e32 v172, v251, v172
	v_mul_f32_e32 v173, v252, v173
	v_mul_f32_e32 v245, v253, v245
	v_fma_f32 v60, v250, v60, v250
	v_fma_f32 v172, v251, v172, v251
	v_fma_f32 v173, v252, v173, v252
	v_fma_f32 v245, v253, v245, v253
	v_mul_f32_e32 v60, 0x3f4c422a, v60
	v_mul_f32_e32 v172, 0x3f4c422a, v172
	v_mul_f32_e32 v173, 0x3f4c422a, v173
	v_mul_f32_e32 v245, 0x3f4c422a, v245
	v_add_f32_e32 v60, v60, v60
	v_add_f32_e32 v172, v172, v172
	v_add_f32_e32 v173, v173, v173
	v_add_f32_e32 v245, v245, v245
	v_mul_f32_e32 v60, 0x3fb8aa3b, v60
	v_mul_f32_e32 v172, 0x3fb8aa3b, v172
	v_mul_f32_e32 v173, 0x3fb8aa3b, v173
	v_mul_f32_e32 v245, 0x3fb8aa3b, v245
	v_exp_f32_e32 v60, v60
	v_exp_f32_e32 v172, v172
	v_exp_f32_e32 v173, v173
	v_exp_f32_e32 v245, v245
	v_mul_f32_e32 v250, 0.5, v250
	v_mul_f32_e32 v251, 0.5, v251
	v_mul_f32_e32 v252, 0.5, v252
	v_mul_f32_e32 v253, 0.5, v253
	v_add_f32_e32 v60, 1.0, v60
	v_add_f32_e32 v172, 1.0, v172
	v_add_f32_e32 v173, 1.0, v173
	v_add_f32_e32 v245, 1.0, v245
	v_rcp_f32_e32 v60, v60
	v_rcp_f32_e32 v172, v172
	v_rcp_f32_e32 v173, v173
	v_rcp_f32_e32 v245, v245
	s_nop 0
	v_fma_f32 v60, v60, -2.0, 1.0
	v_fma_f32 v172, v172, -2.0, 1.0
	v_fma_f32 v173, v173, -2.0, 1.0
	v_fma_f32 v245, v245, -2.0, 1.0
	v_add_f32_e32 v60, 1.0, v60
	v_add_f32_e32 v172, 1.0, v172
	v_add_f32_e32 v173, 1.0, v173
	v_add_f32_e32 v245, 1.0, v245
	v_mul_f32_e32 v250, v250, v60
	v_mul_f32_e32 v251, v251, v172
	v_mul_f32_e32 v252, v252, v173
	v_mul_f32_e32 v253, v253, v245
	v_cvt_pk_bf16_f32 v250, v250, 0
	v_cvt_pk_bf16_f32 v251, v251, 0
	v_cvt_pk_bf16_f32 v252, v252, 0
	v_cvt_pk_bf16_f32 v253, v253, 0
	s_cmp_lg_u32 s35, 0
	s_cselect_b32 s4, 0, -1
	s_mov_b32 exec_hi, s4
	global_store_short v233, v250, s[86:87]
	global_store_short v241, v251, s[86:87]
	global_store_short v242, v252, s[86:87]
	global_store_short v243, v253, s[86:87]
	s_mov_b32 exec_hi, -1
	s_cmp_lg_u32 s35, 0
	s_cbranch_scc1 .Ls5b_ep_skip1
	ds_read_b128 v[164:167], v230 offset:4352
	ds_read_b128 v[168:171], v230 offset:4416
	ds_read_b128 v[156:159], v230 offset:4480
	ds_read_b128 v[132:135], v230 offset:4544
	ds_read_b32 v56, v232 offset:1024
	ds_read_b32 v57, v232 offset:1088
	ds_read_b32 v58, v232 offset:1152
	ds_read_b32 v59, v232 offset:1216
	s_waitcnt lgkmcnt(7)
	v_mfma_f32_16x16x32_bf16 v[250:253], v[164:167], v[208:211], 0
	s_waitcnt lgkmcnt(6)
	v_mfma_f32_16x16x32_bf16 v[250:253], v[168:171], v[212:215], v[250:253]
	s_waitcnt lgkmcnt(5)
	v_mfma_f32_16x16x32_bf16 v[250:253], v[156:159], v[216:219], v[250:253]
	s_waitcnt lgkmcnt(4)
	v_mfma_f32_16x16x32_bf16 v[250:253], v[132:135], v[220:223], v[250:253]
	s_waitcnt lgkmcnt(0)
	s_nop 7
	s_nop 1
	v_fma_f32 v250, v224, v56, v250
	v_fma_f32 v251, v224, v57, v251
	v_fma_f32 v252, v224, v58, v252
	v_fma_f32 v253, v224, v59, v253
	v_mul_f32_e32 v60, 0x3d372713, v250
	v_mul_f32_e32 v172, 0x3d372713, v251
	v_mul_f32_e32 v173, 0x3d372713, v252
	v_mul_f32_e32 v245, 0x3d372713, v253
	v_mul_f32_e32 v60, v250, v60
	v_mul_f32_e32 v172, v251, v172
	v_mul_f32_e32 v173, v252, v173
	v_mul_f32_e32 v245, v253, v245
	v_fma_f32 v60, v250, v60, v250
	v_fma_f32 v172, v251, v172, v251
	v_fma_f32 v173, v252, v173, v252
	v_fma_f32 v245, v253, v245, v253
	v_mul_f32_e32 v60, 0x3f4c422a, v60
	v_mul_f32_e32 v172, 0x3f4c422a, v172
	v_mul_f32_e32 v173, 0x3f4c422a, v173
	v_mul_f32_e32 v245, 0x3f4c422a, v245
	v_add_f32_e32 v60, v60, v60
	v_add_f32_e32 v172, v172, v172
	v_add_f32_e32 v173, v173, v173
	v_add_f32_e32 v245, v245, v245
	v_mul_f32_e32 v60, 0x3fb8aa3b, v60
	v_mul_f32_e32 v172, 0x3fb8aa3b, v172
	v_mul_f32_e32 v173, 0x3fb8aa3b, v173
	v_mul_f32_e32 v245, 0x3fb8aa3b, v245
	v_exp_f32_e32 v60, v60
	v_exp_f32_e32 v172, v172
	v_exp_f32_e32 v173, v173
	v_exp_f32_e32 v245, v245
	v_mul_f32_e32 v250, 0.5, v250
	v_mul_f32_e32 v251, 0.5, v251
	v_mul_f32_e32 v252, 0.5, v252
	v_mul_f32_e32 v253, 0.5, v253
	v_add_f32_e32 v60, 1.0, v60
	v_add_f32_e32 v172, 1.0, v172
	v_add_f32_e32 v173, 1.0, v173
	v_add_f32_e32 v245, 1.0, v245
	v_rcp_f32_e32 v60, v60
	v_rcp_f32_e32 v172, v172
	v_rcp_f32_e32 v173, v173
	v_rcp_f32_e32 v245, v245
	s_nop 0
	v_fma_f32 v60, v60, -2.0, 1.0
	v_fma_f32 v172, v172, -2.0, 1.0
	v_fma_f32 v173, v173, -2.0, 1.0
	v_fma_f32 v245, v245, -2.0, 1.0
	v_add_f32_e32 v60, 1.0, v60
	v_add_f32_e32 v172, 1.0, v172
	v_add_f32_e32 v173, 1.0, v173
	v_add_f32_e32 v245, 1.0, v245
	v_mul_f32_e32 v250, v250, v60
	v_mul_f32_e32 v251, v251, v172
	v_mul_f32_e32 v252, v252, v173
	v_mul_f32_e32 v253, v253, v245
	v_cvt_pk_bf16_f32 v250, v250, 0
	v_cvt_pk_bf16_f32 v251, v251, 0
	v_cvt_pk_bf16_f32 v252, v252, 0
	v_cvt_pk_bf16_f32 v253, v253, 0
	global_store_short v233, v250, s[88:89]
	global_store_short v241, v251, s[88:89]
	global_store_short v242, v252, s[88:89]
	global_store_short v243, v253, s[88:89]

.LBB0_412:
	s_cmp_lt_u32 s33, 64
	s_cbranch_scc1 .Lcpyb_end
	v_lshrrev_b32_e32 v21, 6, v174
	v_and_b32_e32 v22, 63, v174
	v_lshlrev_b32_e32 v22, 4, v22
	v_readfirstlane_b32 s80, v21
	v_add_u32_e32 v23, 0x1000, v22
	v_readfirstlane_b32 s92, v235
	v_readfirstlane_b32 s93, v236
	v_readfirstlane_b32 s94, v237
	v_readfirstlane_b32 s95, v238
	v_readfirstlane_b32 s98, v239
	v_readfirstlane_b32 s99, v240
	s_add_i32 s80, s80, s33
	s_add_i32 s80, s80, 0x37f0
	s_sub_i32 s100, s78, 8
	s_lshl_b32 s100, s100, 3
.Lcpyb_loop:
	s_add_i32 s101, s80, s100
	s_cmp_lt_u32 s101, 0x6710
	s_cbranch_scc0 .Lcpyb_tail
	s_mul_hi_u32 s81, s80, 0x2ad5802b
	s_lshr_b32 s81, s81, 8
	s_mul_i32 s82, s81, 0x5fa
	s_sub_i32 s82, s80, s82
	s_lshl_b32 s82, s82, 13
	s_and_b32 s83, s81, 31
	s_mul_i32 s83, s83, 0xc00000
	s_add_i32 s82, s82, s83
	s_cmp_lt_u32 s81, 32
	s_cselect_b32 s84, s92, s94
	s_cselect_b32 s85, s93, s95
	s_mov_b32 s83, 0x1f210000
	s_cselect_b32 s83, 0x7210000, s83
	s_add_u32 s84, s84, s82
	s_addc_u32 s85, s85, 0
	s_add_u32 s84, s84, 0xc000
	s_addc_u32 s85, s85, 0
	s_add_u32 s83, s83, s82
	s_add_u32 s86, s98, s83
	s_addc_u32 s87, s99, 0
	s_mul_hi_u32 s81, s101, 0x2ad5802b
	s_lshr_b32 s81, s81, 8
	s_mul_i32 s82, s81, 0x5fa
	s_sub_i32 s82, s101, s82
	s_lshl_b32 s82, s82, 13
	s_and_b32 s83, s81, 31
	s_mul_i32 s83, s83, 0xc00000
	s_add_i32 s82, s82, s83
	s_cmp_lt_u32 s81, 32
	s_cselect_b32 s88, s92, s94
	s_cselect_b32 s89, s93, s95
	s_mov_b32 s83, 0x1f210000
	s_cselect_b32 s83, 0x7210000, s83
	s_add_u32 s88, s88, s82
	s_addc_u32 s89, s89, 0
	s_add_u32 s88, s88, 0xc000
	s_addc_u32 s89, s89, 0
	s_add_u32 s83, s83, s82
	s_add_u32 s90, s98, s83
	s_addc_u32 s91, s99, 0
	global_load_dwordx4 v[64:67], v22, s[84:85] nt
	global_load_dwordx4 v[68:71], v22, s[84:85] offset:1024 nt
	global_load_dwordx4 v[72:75], v22, s[84:85] offset:2048 nt
	global_load_dwordx4 v[76:79], v22, s[84:85] offset:3072 nt
	global_load_dwordx4 v[80:83], v23, s[84:85] nt
	global_load_dwordx4 v[84:87], v23, s[84:85] offset:1024 nt
	global_load_dwordx4 v[88:91], v23, s[84:85] offset:2048 nt
	global_load_dwordx4 v[92:95], v23, s[84:85] offset:3072 nt
	global_load_dwordx4 v[96:99], v22, s[88:89] nt
	global_load_dwordx4 v[100:103], v22, s[88:89] offset:1024 nt
	global_load_dwordx4 v[104:107], v22, s[88:89] offset:2048 nt
	global_load_dwordx4 v[108:111], v22, s[88:89] offset:3072 nt
	global_load_dwordx4 v[112:115], v23, s[88:89] nt
	global_load_dwordx4 v[116:119], v23, s[88:89] offset:1024 nt
	global_load_dwordx4 v[120:123], v23, s[88:89] offset:2048 nt
	global_load_dwordx4 v[124:127], v23, s[88:89] offset:3072 nt
	s_waitcnt vmcnt(15)
	global_store_dwordx4 v22, v[64:67], s[86:87] nt
	s_waitcnt vmcnt(15)
	global_store_dwordx4 v22, v[68:71], s[86:87] offset:1024 nt
	s_waitcnt vmcnt(15)
	global_store_dwordx4 v22, v[72:75], s[86:87] offset:2048 nt
	s_waitcnt vmcnt(15)
	global_store_dwordx4 v22, v[76:79], s[86:87] offset:3072 nt
	s_waitcnt vmcnt(15)
	global_store_dwordx4 v23, v[80:83], s[86:87] nt
	s_waitcnt vmcnt(15)
	global_store_dwordx4 v23, v[84:87], s[86:87] offset:1024 nt
	s_waitcnt vmcnt(15)
	global_store_dwordx4 v23, v[88:91], s[86:87] offset:2048 nt
	s_waitcnt vmcnt(15)
	global_store_dwordx4 v23, v[92:95], s[86:87] offset:3072 nt
	s_waitcnt vmcnt(15)
	global_store_dwordx4 v22, v[96:99], s[90:91] nt
	s_waitcnt vmcnt(15)
	global_store_dwordx4 v22, v[100:103], s[90:91] offset:1024 nt
	s_waitcnt vmcnt(15)
	global_store_dwordx4 v22, v[104:107], s[90:91] offset:2048 nt
	s_waitcnt vmcnt(15)
	global_store_dwordx4 v22, v[108:111], s[90:91] offset:3072 nt
	s_waitcnt vmcnt(15)
	global_store_dwordx4 v23, v[112:115], s[90:91] nt
	s_waitcnt vmcnt(15)
	global_store_dwordx4 v23, v[116:119], s[90:91] offset:1024 nt
	s_waitcnt vmcnt(15)
	global_store_dwordx4 v23, v[120:123], s[90:91] offset:2048 nt
	s_waitcnt vmcnt(15)
	global_store_dwordx4 v23, v[124:127], s[90:91] offset:3072 nt
	s_add_i32 s80, s101, s100
	s_branch .Lcpyb_loop
.Lcpyb_tail:
	s_cmp_lt_u32 s80, 0x6710
	s_cbranch_scc0 .Lcpyb_end
	s_mul_hi_u32 s81, s80, 0x2ad5802b
	s_lshr_b32 s81, s81, 8
	s_mul_i32 s82, s81, 0x5fa
	s_sub_i32 s82, s80, s82
	s_lshl_b32 s82, s82, 13
	s_and_b32 s83, s81, 31
	s_mul_i32 s83, s83, 0xc00000
	s_add_i32 s82, s82, s83
	s_cmp_lt_u32 s81, 32
	s_cselect_b32 s84, s92, s94
	s_cselect_b32 s85, s93, s95
	s_mov_b32 s83, 0x1f210000
	s_cselect_b32 s83, 0x7210000, s83
	s_add_u32 s84, s84, s82
	s_addc_u32 s85, s85, 0
	s_add_u32 s84, s84, 0xc000
	s_addc_u32 s85, s85, 0
	s_add_u32 s83, s83, s82
	s_add_u32 s86, s98, s83
	s_addc_u32 s87, s99, 0
	global_load_dwordx4 v[64:67], v22, s[84:85] nt
	global_load_dwordx4 v[68:71], v22, s[84:85] offset:1024 nt
	global_load_dwordx4 v[72:75], v22, s[84:85] offset:2048 nt
	global_load_dwordx4 v[76:79], v22, s[84:85] offset:3072 nt
	global_load_dwordx4 v[80:83], v23, s[84:85] nt
	global_load_dwordx4 v[84:87], v23, s[84:85] offset:1024 nt
	global_load_dwordx4 v[88:91], v23, s[84:85] offset:2048 nt
	global_load_dwordx4 v[92:95], v23, s[84:85] offset:3072 nt
	s_waitcnt vmcnt(7)
	global_store_dwordx4 v22, v[64:67], s[86:87] nt
	s_waitcnt vmcnt(7)
	global_store_dwordx4 v22, v[68:71], s[86:87] offset:1024 nt
	s_waitcnt vmcnt(7)
	global_store_dwordx4 v22, v[72:75], s[86:87] offset:2048 nt
	s_waitcnt vmcnt(7)
	global_store_dwordx4 v22, v[76:79], s[86:87] offset:3072 nt
	s_waitcnt vmcnt(7)
	global_store_dwordx4 v23, v[80:83], s[86:87] nt
	s_waitcnt vmcnt(7)
	global_store_dwordx4 v23, v[84:87], s[86:87] offset:1024 nt
	s_waitcnt vmcnt(7)
	global_store_dwordx4 v23, v[88:91], s[86:87] offset:2048 nt
	s_waitcnt vmcnt(7)
	global_store_dwordx4 v23, v[92:95], s[86:87] offset:3072 nt

.LBB0_452:
	s_cmp_lt_u32 s33, 1200
	s_cbranch_scc1 .Lcpyc_end
	v_lshrrev_b32_e32 v21, 6, v174
	v_and_b32_e32 v22, 63, v174
	v_lshlrev_b32_e32 v22, 4, v22
	v_readfirstlane_b32 s80, v21
	v_add_u32_e32 v23, 0x1000, v22
	v_readfirstlane_b32 s92, v235
	v_readfirstlane_b32 s93, v236
	v_readfirstlane_b32 s94, v237
	v_readfirstlane_b32 s95, v238
	v_readfirstlane_b32 s98, v239
	v_readfirstlane_b32 s99, v240
	s_add_i32 s80, s80, s33
	s_add_i32 s80, s80, 0x6260
	s_sub_i32 s100, s78, 150
	s_lshl_b32 s100, s100, 3
.Lcpyc_loop:
	s_add_i32 s101, s80, s100
	s_cmp_lt_u32 s101, 0x8650
	s_cbranch_scc0 .Lcpyc_tail
	s_mul_hi_u32 s81, s80, 0x2ad5802b
	s_lshr_b32 s81, s81, 8
	s_mul_i32 s82, s81, 0x5fa
	s_sub_i32 s82, s80, s82
	s_lshl_b32 s82, s82, 13
	s_and_b32 s83, s81, 31
	s_mul_i32 s83, s83, 0xc00000
	s_add_i32 s82, s82, s83
	s_cmp_lt_u32 s81, 32
	s_cselect_b32 s84, s92, s94
	s_cselect_b32 s85, s93, s95
	s_mov_b32 s83, 0x1f210000
	s_cselect_b32 s83, 0x7210000, s83
	s_add_u32 s84, s84, s82
	s_addc_u32 s85, s85, 0
	s_add_u32 s84, s84, 0xc000
	s_addc_u32 s85, s85, 0
	s_add_u32 s83, s83, s82
	s_add_u32 s86, s98, s83
	s_addc_u32 s87, s99, 0
	s_mul_hi_u32 s81, s101, 0x2ad5802b
	s_lshr_b32 s81, s81, 8
	s_mul_i32 s82, s81, 0x5fa
	s_sub_i32 s82, s101, s82
	s_lshl_b32 s82, s82, 13
	s_and_b32 s83, s81, 31
	s_mul_i32 s83, s83, 0xc00000
	s_add_i32 s82, s82, s83
	s_cmp_lt_u32 s81, 32
	s_cselect_b32 s88, s92, s94
	s_cselect_b32 s89, s93, s95
	s_mov_b32 s83, 0x1f210000
	s_cselect_b32 s83, 0x7210000, s83
	s_add_u32 s88, s88, s82
	s_addc_u32 s89, s89, 0
	s_add_u32 s88, s88, 0xc000
	s_addc_u32 s89, s89, 0
	s_add_u32 s83, s83, s82
	s_add_u32 s90, s98, s83
	s_addc_u32 s91, s99, 0
	global_load_dwordx4 v[64:67], v22, s[84:85] nt
	global_load_dwordx4 v[68:71], v22, s[84:85] offset:1024 nt
	global_load_dwordx4 v[72:75], v22, s[84:85] offset:2048 nt
	global_load_dwordx4 v[76:79], v22, s[84:85] offset:3072 nt
	global_load_dwordx4 v[80:83], v23, s[84:85] nt
	global_load_dwordx4 v[84:87], v23, s[84:85] offset:1024 nt
	global_load_dwordx4 v[88:91], v23, s[84:85] offset:2048 nt
	global_load_dwordx4 v[92:95], v23, s[84:85] offset:3072 nt
	global_load_dwordx4 v[96:99], v22, s[88:89] nt
	global_load_dwordx4 v[100:103], v22, s[88:89] offset:1024 nt
	global_load_dwordx4 v[104:107], v22, s[88:89] offset:2048 nt
	global_load_dwordx4 v[108:111], v22, s[88:89] offset:3072 nt
	global_load_dwordx4 v[112:115], v23, s[88:89] nt
	global_load_dwordx4 v[116:119], v23, s[88:89] offset:1024 nt
	global_load_dwordx4 v[120:123], v23, s[88:89] offset:2048 nt
	global_load_dwordx4 v[124:127], v23, s[88:89] offset:3072 nt
	s_waitcnt vmcnt(15)
	global_store_dwordx4 v22, v[64:67], s[86:87] nt
	s_waitcnt vmcnt(15)
	global_store_dwordx4 v22, v[68:71], s[86:87] offset:1024 nt
	s_waitcnt vmcnt(15)
	global_store_dwordx4 v22, v[72:75], s[86:87] offset:2048 nt
	s_waitcnt vmcnt(15)
	global_store_dwordx4 v22, v[76:79], s[86:87] offset:3072 nt
	s_waitcnt vmcnt(15)
	global_store_dwordx4 v23, v[80:83], s[86:87] nt
	s_waitcnt vmcnt(15)
	global_store_dwordx4 v23, v[84:87], s[86:87] offset:1024 nt
	s_waitcnt vmcnt(15)
	global_store_dwordx4 v23, v[88:91], s[86:87] offset:2048 nt
	s_waitcnt vmcnt(15)
	global_store_dwordx4 v23, v[92:95], s[86:87] offset:3072 nt
	s_waitcnt vmcnt(15)
	global_store_dwordx4 v22, v[96:99], s[90:91] nt
	s_waitcnt vmcnt(15)
	global_store_dwordx4 v22, v[100:103], s[90:91] offset:1024 nt
	s_waitcnt vmcnt(15)
	global_store_dwordx4 v22, v[104:107], s[90:91] offset:2048 nt
	s_waitcnt vmcnt(15)
	global_store_dwordx4 v22, v[108:111], s[90:91] offset:3072 nt
	s_waitcnt vmcnt(15)
	global_store_dwordx4 v23, v[112:115], s[90:91] nt
	s_waitcnt vmcnt(15)
	global_store_dwordx4 v23, v[116:119], s[90:91] offset:1024 nt
	s_waitcnt vmcnt(15)
	global_store_dwordx4 v23, v[120:123], s[90:91] offset:2048 nt
	s_waitcnt vmcnt(15)
	global_store_dwordx4 v23, v[124:127], s[90:91] offset:3072 nt
	s_add_i32 s80, s101, s100
	s_branch .Lcpyc_loop
.Lcpyc_tail:
	s_cmp_lt_u32 s80, 0x8650
	s_cbranch_scc0 .Lcpyc_end
	s_mul_hi_u32 s81, s80, 0x2ad5802b
	s_lshr_b32 s81, s81, 8
	s_mul_i32 s82, s81, 0x5fa
	s_sub_i32 s82, s80, s82
	s_lshl_b32 s82, s82, 13
	s_and_b32 s83, s81, 31
	s_mul_i32 s83, s83, 0xc00000
	s_add_i32 s82, s82, s83
	s_cmp_lt_u32 s81, 32
	s_cselect_b32 s84, s92, s94
	s_cselect_b32 s85, s93, s95
	s_mov_b32 s83, 0x1f210000
	s_cselect_b32 s83, 0x7210000, s83
	s_add_u32 s84, s84, s82
	s_addc_u32 s85, s85, 0
	s_add_u32 s84, s84, 0xc000
	s_addc_u32 s85, s85, 0
	s_add_u32 s83, s83, s82
	s_add_u32 s86, s98, s83
	s_addc_u32 s87, s99, 0
	global_load_dwordx4 v[64:67], v22, s[84:85] nt
	global_load_dwordx4 v[68:71], v22, s[84:85] offset:1024 nt
	global_load_dwordx4 v[72:75], v22, s[84:85] offset:2048 nt
	global_load_dwordx4 v[76:79], v22, s[84:85] offset:3072 nt
	global_load_dwordx4 v[80:83], v23, s[84:85] nt
	global_load_dwordx4 v[84:87], v23, s[84:85] offset:1024 nt
	global_load_dwordx4 v[88:91], v23, s[84:85] offset:2048 nt
	global_load_dwordx4 v[92:95], v23, s[84:85] offset:3072 nt
	s_waitcnt vmcnt(7)
	global_store_dwordx4 v22, v[64:67], s[86:87] nt
	s_waitcnt vmcnt(7)
	global_store_dwordx4 v22, v[68:71], s[86:87] offset:1024 nt
	s_waitcnt vmcnt(7)
	global_store_dwordx4 v22, v[72:75], s[86:87] offset:2048 nt
	s_waitcnt vmcnt(7)
	global_store_dwordx4 v22, v[76:79], s[86:87] offset:3072 nt
	s_waitcnt vmcnt(7)
	global_store_dwordx4 v23, v[80:83], s[86:87] nt
	s_waitcnt vmcnt(7)
	global_store_dwordx4 v23, v[84:87], s[86:87] offset:1024 nt
	s_waitcnt vmcnt(7)
	global_store_dwordx4 v23, v[88:91], s[86:87] offset:2048 nt
	s_waitcnt vmcnt(7)
	global_store_dwordx4 v23, v[92:95], s[86:87] offset:3072 nt

.LBB0_472:
	s_or_b64 exec, exec, s[8:9]
	v_readlane_b32 s4, v234, 2
	v_mov_b32_e32 v8, v174
	v_readlane_b32 s5, v234, 3
	s_barrier
	s_and_b32 s80, s33, 64
	s_cmp_eq_u32 s80, 0
	s_cbranch_scc1 .Lpre2_skip
	v_lshrrev_b32_e32 v21, 6, v174
	v_and_b32_e32 v22, 63, v174
	v_lshlrev_b32_e32 v22, 4, v22
	v_readfirstlane_b32 s80, v21
	v_add_u32_e32 v23, 0x1000, v22
	v_readfirstlane_b32 s92, v235
	v_readfirstlane_b32 s93, v236
	v_readfirstlane_b32 s94, v237
	v_readfirstlane_b32 s95, v238
	v_readfirstlane_b32 s98, v239
	v_readfirstlane_b32 s99, v240
	s_lshr_b32 s100, s33, 7
	s_lshl_b32 s100, s100, 3
	s_lshr_b32 s101, s33, 3
	s_and_b32 s101, s101, 7
	s_add_i32 s100, s100, s101
	s_lshl_b32 s100, s100, 3
	s_add_i32 s80, s80, s100
	s_add_i32 s80, s80, 0x8650
	s_movk_i32 s100, 0x400
.Lcpy2p_loop:
	s_add_i32 s101, s80, s100
	s_cmp_lt_u32 s101, 0x9904
	s_cbranch_scc0 .Lcpy2p_tail
	s_mul_hi_u32 s81, s80, 0x2ad5802b
	s_lshr_b32 s81, s81, 8
	s_mul_i32 s82, s81, 0x5fa
	s_sub_i32 s82, s80, s82
	s_lshl_b32 s82, s82, 13
	s_and_b32 s83, s81, 31
	s_mul_i32 s83, s83, 0xc00000
	s_add_i32 s82, s82, s83
	s_cmp_lt_u32 s81, 32
	s_cselect_b32 s84, s92, s94
	s_cselect_b32 s85, s93, s95
	s_mov_b32 s83, 0x1f210000
	s_cselect_b32 s83, 0x7210000, s83
	s_add_u32 s84, s84, s82
	s_addc_u32 s85, s85, 0
	s_add_u32 s84, s84, 0xc000
	s_addc_u32 s85, s85, 0
	s_add_u32 s83, s83, s82
	s_add_u32 s86, s98, s83
	s_addc_u32 s87, s99, 0
	s_mul_hi_u32 s81, s101, 0x2ad5802b
	s_lshr_b32 s81, s81, 8
	s_mul_i32 s82, s81, 0x5fa
	s_sub_i32 s82, s101, s82
	s_lshl_b32 s82, s82, 13
	s_and_b32 s83, s81, 31
	s_mul_i32 s83, s83, 0xc00000
	s_add_i32 s82, s82, s83
	s_cmp_lt_u32 s81, 32
	s_cselect_b32 s88, s92, s94
	s_cselect_b32 s89, s93, s95
	s_mov_b32 s83, 0x1f210000
	s_cselect_b32 s83, 0x7210000, s83
	s_add_u32 s88, s88, s82
	s_addc_u32 s89, s89, 0
	s_add_u32 s88, s88, 0xc000
	s_addc_u32 s89, s89, 0
	s_add_u32 s83, s83, s82
	s_add_u32 s90, s98, s83
	s_addc_u32 s91, s99, 0
	global_load_dwordx4 v[64:67], v22, s[84:85] nt
	global_load_dwordx4 v[68:71], v22, s[84:85] offset:1024 nt
	global_load_dwordx4 v[72:75], v22, s[84:85] offset:2048 nt
	global_load_dwordx4 v[76:79], v22, s[84:85] offset:3072 nt
	global_load_dwordx4 v[80:83], v23, s[84:85] nt
	global_load_dwordx4 v[84:87], v23, s[84:85] offset:1024 nt
	global_load_dwordx4 v[88:91], v23, s[84:85] offset:2048 nt
	global_load_dwordx4 v[92:95], v23, s[84:85] offset:3072 nt
	global_load_dwordx4 v[96:99], v22, s[88:89] nt
	global_load_dwordx4 v[100:103], v22, s[88:89] offset:1024 nt
	global_load_dwordx4 v[104:107], v22, s[88:89] offset:2048 nt
	global_load_dwordx4 v[108:111], v22, s[88:89] offset:3072 nt
	global_load_dwordx4 v[112:115], v23, s[88:89] nt
	global_load_dwordx4 v[116:119], v23, s[88:89] offset:1024 nt
	global_load_dwordx4 v[120:123], v23, s[88:89] offset:2048 nt
	global_load_dwordx4 v[124:127], v23, s[88:89] offset:3072 nt
	s_waitcnt vmcnt(15)
	global_store_dwordx4 v22, v[64:67], s[86:87] nt
	s_waitcnt vmcnt(15)
	global_store_dwordx4 v22, v[68:71], s[86:87] offset:1024 nt
	s_waitcnt vmcnt(15)
	global_store_dwordx4 v22, v[72:75], s[86:87] offset:2048 nt
	s_waitcnt vmcnt(15)
	global_store_dwordx4 v22, v[76:79], s[86:87] offset:3072 nt
	s_waitcnt vmcnt(15)
	global_store_dwordx4 v23, v[80:83], s[86:87] nt
	s_waitcnt vmcnt(15)
	global_store_dwordx4 v23, v[84:87], s[86:87] offset:1024 nt
	s_waitcnt vmcnt(15)
	global_store_dwordx4 v23, v[88:91], s[86:87] offset:2048 nt
	s_waitcnt vmcnt(15)
	global_store_dwordx4 v23, v[92:95], s[86:87] offset:3072 nt
	s_waitcnt vmcnt(15)
	global_store_dwordx4 v22, v[96:99], s[90:91] nt
	s_waitcnt vmcnt(15)
	global_store_dwordx4 v22, v[100:103], s[90:91] offset:1024 nt
	s_waitcnt vmcnt(15)
	global_store_dwordx4 v22, v[104:107], s[90:91] offset:2048 nt
	s_waitcnt vmcnt(15)
	global_store_dwordx4 v22, v[108:111], s[90:91] offset:3072 nt
	s_waitcnt vmcnt(15)
	global_store_dwordx4 v23, v[112:115], s[90:91] nt
	s_waitcnt vmcnt(15)
	global_store_dwordx4 v23, v[116:119], s[90:91] offset:1024 nt
	s_waitcnt vmcnt(15)
	global_store_dwordx4 v23, v[120:123], s[90:91] offset:2048 nt
	s_waitcnt vmcnt(15)
	global_store_dwordx4 v23, v[124:127], s[90:91] offset:3072 nt
	s_add_i32 s80, s101, s100
	s_branch .Lcpy2p_loop
.Lcpy2p_tail:
	s_cmp_lt_u32 s80, 0x9904
	s_cbranch_scc0 .Lcpy2p_end
	s_mul_hi_u32 s81, s80, 0x2ad5802b
	s_lshr_b32 s81, s81, 8
	s_mul_i32 s82, s81, 0x5fa
	s_sub_i32 s82, s80, s82
	s_lshl_b32 s82, s82, 13
	s_and_b32 s83, s81, 31
	s_mul_i32 s83, s83, 0xc00000
	s_add_i32 s82, s82, s83
	s_cmp_lt_u32 s81, 32
	s_cselect_b32 s84, s92, s94
	s_cselect_b32 s85, s93, s95
	s_mov_b32 s83, 0x1f210000
	s_cselect_b32 s83, 0x7210000, s83
	s_add_u32 s84, s84, s82
	s_addc_u32 s85, s85, 0
	s_add_u32 s84, s84, 0xc000
	s_addc_u32 s85, s85, 0
	s_add_u32 s83, s83, s82
	s_add_u32 s86, s98, s83
	s_addc_u32 s87, s99, 0
	global_load_dwordx4 v[64:67], v22, s[84:85] nt
	global_load_dwordx4 v[68:71], v22, s[84:85] offset:1024 nt
	global_load_dwordx4 v[72:75], v22, s[84:85] offset:2048 nt
	global_load_dwordx4 v[76:79], v22, s[84:85] offset:3072 nt
	global_load_dwordx4 v[80:83], v23, s[84:85] nt
	global_load_dwordx4 v[84:87], v23, s[84:85] offset:1024 nt
	global_load_dwordx4 v[88:91], v23, s[84:85] offset:2048 nt
	global_load_dwordx4 v[92:95], v23, s[84:85] offset:3072 nt
	s_waitcnt vmcnt(7)
	global_store_dwordx4 v22, v[64:67], s[86:87] nt
	s_waitcnt vmcnt(7)
	global_store_dwordx4 v22, v[68:71], s[86:87] offset:1024 nt
	s_waitcnt vmcnt(7)
	global_store_dwordx4 v22, v[72:75], s[86:87] offset:2048 nt
	s_waitcnt vmcnt(7)
	global_store_dwordx4 v22, v[76:79], s[86:87] offset:3072 nt
	s_waitcnt vmcnt(7)
	global_store_dwordx4 v23, v[80:83], s[86:87] nt
	s_waitcnt vmcnt(7)
	global_store_dwordx4 v23, v[84:87], s[86:87] offset:1024 nt
	s_waitcnt vmcnt(7)
	global_store_dwordx4 v23, v[88:91], s[86:87] offset:2048 nt
	s_waitcnt vmcnt(7)
	global_store_dwordx4 v23, v[92:95], s[86:87] offset:3072 nt

.Lmg2_end:
	v_lshrrev_b32_e32 v21, 6, v174
	v_and_b32_e32 v22, 63, v174
	v_lshlrev_b32_e32 v22, 4, v22
	v_readfirstlane_b32 s80, v21
	v_add_u32_e32 v23, 0x1000, v22
	v_readfirstlane_b32 s92, v235
	v_readfirstlane_b32 s93, v236
	v_readfirstlane_b32 s94, v237
	v_readfirstlane_b32 s95, v238
	v_readfirstlane_b32 s98, v239
	v_readfirstlane_b32 s99, v240
	s_lshr_b32 s100, s33, 7
	s_lshl_b32 s100, s100, 3
	s_lshr_b32 s101, s33, 3
	s_and_b32 s101, s101, 7
	s_add_i32 s100, s100, s101
	s_lshl_b32 s100, s100, 3
	s_add_i32 s80, s80, s100
	s_add_i32 s80, s80, 0x9904
	s_movk_i32 s100, 0x400
.Lcpy2_loop:
	s_add_i32 s101, s80, s100
	s_cmp_lt_u32 s101, 0x9f40
	s_cbranch_scc0 .Lcpy2_tail
	s_mul_hi_u32 s81, s80, 0x2ad5802b
	s_lshr_b32 s81, s81, 8
	s_mul_i32 s82, s81, 0x5fa
	s_sub_i32 s82, s80, s82
	s_lshl_b32 s82, s82, 13
	s_and_b32 s83, s81, 31
	s_mul_i32 s83, s83, 0xc00000
	s_add_i32 s82, s82, s83
	s_cmp_lt_u32 s81, 32
	s_cselect_b32 s84, s92, s94
	s_cselect_b32 s85, s93, s95
	s_mov_b32 s83, 0x1f210000
	s_cselect_b32 s83, 0x7210000, s83
	s_add_u32 s84, s84, s82
	s_addc_u32 s85, s85, 0
	s_add_u32 s84, s84, 0xc000
	s_addc_u32 s85, s85, 0
	s_add_u32 s83, s83, s82
	s_add_u32 s86, s98, s83
	s_addc_u32 s87, s99, 0
	s_mul_hi_u32 s81, s101, 0x2ad5802b
	s_lshr_b32 s81, s81, 8
	s_mul_i32 s82, s81, 0x5fa
	s_sub_i32 s82, s101, s82
	s_lshl_b32 s82, s82, 13
	s_and_b32 s83, s81, 31
	s_mul_i32 s83, s83, 0xc00000
	s_add_i32 s82, s82, s83
	s_cmp_lt_u32 s81, 32
	s_cselect_b32 s88, s92, s94
	s_cselect_b32 s89, s93, s95
	s_mov_b32 s83, 0x1f210000
	s_cselect_b32 s83, 0x7210000, s83
	s_add_u32 s88, s88, s82
	s_addc_u32 s89, s89, 0
	s_add_u32 s88, s88, 0xc000
	s_addc_u32 s89, s89, 0
	s_add_u32 s83, s83, s82
	s_add_u32 s90, s98, s83
	s_addc_u32 s91, s99, 0
	global_load_dwordx4 v[64:67], v22, s[84:85] nt
	global_load_dwordx4 v[68:71], v22, s[84:85] offset:1024 nt
	global_load_dwordx4 v[72:75], v22, s[84:85] offset:2048 nt
	global_load_dwordx4 v[76:79], v22, s[84:85] offset:3072 nt
	global_load_dwordx4 v[80:83], v23, s[84:85] nt
	global_load_dwordx4 v[84:87], v23, s[84:85] offset:1024 nt
	global_load_dwordx4 v[88:91], v23, s[84:85] offset:2048 nt
	global_load_dwordx4 v[92:95], v23, s[84:85] offset:3072 nt
	global_load_dwordx4 v[96:99], v22, s[88:89] nt
	global_load_dwordx4 v[100:103], v22, s[88:89] offset:1024 nt
	global_load_dwordx4 v[104:107], v22, s[88:89] offset:2048 nt
	global_load_dwordx4 v[108:111], v22, s[88:89] offset:3072 nt
	global_load_dwordx4 v[112:115], v23, s[88:89] nt
	global_load_dwordx4 v[116:119], v23, s[88:89] offset:1024 nt
	global_load_dwordx4 v[120:123], v23, s[88:89] offset:2048 nt
	global_load_dwordx4 v[124:127], v23, s[88:89] offset:3072 nt
	s_waitcnt vmcnt(15)
	global_store_dwordx4 v22, v[64:67], s[86:87] nt
	s_waitcnt vmcnt(15)
	global_store_dwordx4 v22, v[68:71], s[86:87] offset:1024 nt
	s_waitcnt vmcnt(15)
	global_store_dwordx4 v22, v[72:75], s[86:87] offset:2048 nt
	s_waitcnt vmcnt(15)
	global_store_dwordx4 v22, v[76:79], s[86:87] offset:3072 nt
	s_waitcnt vmcnt(15)
	global_store_dwordx4 v23, v[80:83], s[86:87] nt
	s_waitcnt vmcnt(15)
	global_store_dwordx4 v23, v[84:87], s[86:87] offset:1024 nt
	s_waitcnt vmcnt(15)
	global_store_dwordx4 v23, v[88:91], s[86:87] offset:2048 nt
	s_waitcnt vmcnt(15)
	global_store_dwordx4 v23, v[92:95], s[86:87] offset:3072 nt
	s_waitcnt vmcnt(15)
	global_store_dwordx4 v22, v[96:99], s[90:91] nt
	s_waitcnt vmcnt(15)
	global_store_dwordx4 v22, v[100:103], s[90:91] offset:1024 nt
	s_waitcnt vmcnt(15)
	global_store_dwordx4 v22, v[104:107], s[90:91] offset:2048 nt
	s_waitcnt vmcnt(15)
	global_store_dwordx4 v22, v[108:111], s[90:91] offset:3072 nt
	s_waitcnt vmcnt(15)
	global_store_dwordx4 v23, v[112:115], s[90:91] nt
	s_waitcnt vmcnt(15)
	global_store_dwordx4 v23, v[116:119], s[90:91] offset:1024 nt
	s_waitcnt vmcnt(15)
	global_store_dwordx4 v23, v[120:123], s[90:91] offset:2048 nt
	s_waitcnt vmcnt(15)
	global_store_dwordx4 v23, v[124:127], s[90:91] offset:3072 nt
	s_add_i32 s80, s101, s100
	s_branch .Lcpy2_loop
.Lcpy2_tail:
	s_cmp_lt_u32 s80, 0x9f40
	s_cbranch_scc0 .Lcpy2_end
	s_mul_hi_u32 s81, s80, 0x2ad5802b
	s_lshr_b32 s81, s81, 8
	s_mul_i32 s82, s81, 0x5fa
	s_sub_i32 s82, s80, s82
	s_lshl_b32 s82, s82, 13
	s_and_b32 s83, s81, 31
	s_mul_i32 s83, s83, 0xc00000
	s_add_i32 s82, s82, s83
	s_cmp_lt_u32 s81, 32
	s_cselect_b32 s84, s92, s94
	s_cselect_b32 s85, s93, s95
	s_mov_b32 s83, 0x1f210000
	s_cselect_b32 s83, 0x7210000, s83
	s_add_u32 s84, s84, s82
	s_addc_u32 s85, s85, 0
	s_add_u32 s84, s84, 0xc000
	s_addc_u32 s85, s85, 0
	s_add_u32 s83, s83, s82
	s_add_u32 s86, s98, s83
	s_addc_u32 s87, s99, 0
	global_load_dwordx4 v[64:67], v22, s[84:85] nt
	global_load_dwordx4 v[68:71], v22, s[84:85] offset:1024 nt
	global_load_dwordx4 v[72:75], v22, s[84:85] offset:2048 nt
	global_load_dwordx4 v[76:79], v22, s[84:85] offset:3072 nt
	global_load_dwordx4 v[80:83], v23, s[84:85] nt
	global_load_dwordx4 v[84:87], v23, s[84:85] offset:1024 nt
	global_load_dwordx4 v[88:91], v23, s[84:85] offset:2048 nt
	global_load_dwordx4 v[92:95], v23, s[84:85] offset:3072 nt
	s_waitcnt vmcnt(7)
	global_store_dwordx4 v22, v[64:67], s[86:87] nt
	s_waitcnt vmcnt(7)
	global_store_dwordx4 v22, v[68:71], s[86:87] offset:1024 nt
	s_waitcnt vmcnt(7)
	global_store_dwordx4 v22, v[72:75], s[86:87] offset:2048 nt
	s_waitcnt vmcnt(7)
	global_store_dwordx4 v22, v[76:79], s[86:87] offset:3072 nt
	s_waitcnt vmcnt(7)
	global_store_dwordx4 v23, v[80:83], s[86:87] nt
	s_waitcnt vmcnt(7)
	global_store_dwordx4 v23, v[84:87], s[86:87] offset:1024 nt
	s_waitcnt vmcnt(7)
	global_store_dwordx4 v23, v[88:91], s[86:87] offset:2048 nt
	s_waitcnt vmcnt(7)
	global_store_dwordx4 v23, v[92:95], s[86:87] offset:3072 nt

.LBB0_960:
	s_cmp_lt_u32 s33, 96
	s_cbranch_scc1 .Lcpyd_end
	s_cmp_ge_u32 s33, 848
	s_cbranch_scc1 .Lcpyd_end
	v_lshrrev_b32_e32 v21, 6, v174
	v_and_b32_e32 v22, 63, v174
	v_lshlrev_b32_e32 v22, 4, v22
	v_readfirstlane_b32 s80, v21
	v_add_u32_e32 v23, 0x1000, v22
	v_readfirstlane_b32 s92, v235
	v_readfirstlane_b32 s93, v236
	v_readfirstlane_b32 s94, v237
	v_readfirstlane_b32 s95, v238
	v_readfirstlane_b32 s98, v239
	v_readfirstlane_b32 s99, v240
	s_add_i32 s80, s80, s33
	s_add_i32 s80, s80, 0x9ee0
	s_movk_i32 s100, 752
.Lcpyd_loop:
	s_add_i32 s101, s80, s100
	s_cmp_lt_u32 s101, 0xba98
	s_cbranch_scc0 .Lcpyd_tail
	s_mul_hi_u32 s81, s80, 0x2ad5802b
	s_lshr_b32 s81, s81, 8
	s_mul_i32 s82, s81, 0x5fa
	s_sub_i32 s82, s80, s82
	s_lshl_b32 s82, s82, 13
	s_and_b32 s83, s81, 31
	s_mul_i32 s83, s83, 0xc00000
	s_add_i32 s82, s82, s83
	s_cmp_lt_u32 s81, 32
	s_cselect_b32 s84, s92, s94
	s_cselect_b32 s85, s93, s95
	s_mov_b32 s83, 0x1f210000
	s_cselect_b32 s83, 0x7210000, s83
	s_add_u32 s84, s84, s82
	s_addc_u32 s85, s85, 0
	s_add_u32 s84, s84, 0xc000
	s_addc_u32 s85, s85, 0
	s_add_u32 s83, s83, s82
	s_add_u32 s86, s98, s83
	s_addc_u32 s87, s99, 0
	s_mul_hi_u32 s81, s101, 0x2ad5802b
	s_lshr_b32 s81, s81, 8
	s_mul_i32 s82, s81, 0x5fa
	s_sub_i32 s82, s101, s82
	s_lshl_b32 s82, s82, 13
	s_and_b32 s83, s81, 31
	s_mul_i32 s83, s83, 0xc00000
	s_add_i32 s82, s82, s83
	s_cmp_lt_u32 s81, 32
	s_cselect_b32 s88, s92, s94
	s_cselect_b32 s89, s93, s95
	s_mov_b32 s83, 0x1f210000
	s_cselect_b32 s83, 0x7210000, s83
	s_add_u32 s88, s88, s82
	s_addc_u32 s89, s89, 0
	s_add_u32 s88, s88, 0xc000
	s_addc_u32 s89, s89, 0
	s_add_u32 s83, s83, s82
	s_add_u32 s90, s98, s83
	s_addc_u32 s91, s99, 0
	global_load_dwordx4 v[64:67], v22, s[84:85] nt
	global_load_dwordx4 v[68:71], v22, s[84:85] offset:1024 nt
	global_load_dwordx4 v[72:75], v22, s[84:85] offset:2048 nt
	global_load_dwordx4 v[76:79], v22, s[84:85] offset:3072 nt
	global_load_dwordx4 v[80:83], v23, s[84:85] nt
	global_load_dwordx4 v[84:87], v23, s[84:85] offset:1024 nt
	global_load_dwordx4 v[88:91], v23, s[84:85] offset:2048 nt
	global_load_dwordx4 v[92:95], v23, s[84:85] offset:3072 nt
	global_load_dwordx4 v[96:99], v22, s[88:89] nt
	global_load_dwordx4 v[100:103], v22, s[88:89] offset:1024 nt
	global_load_dwordx4 v[104:107], v22, s[88:89] offset:2048 nt
	global_load_dwordx4 v[108:111], v22, s[88:89] offset:3072 nt
	global_load_dwordx4 v[112:115], v23, s[88:89] nt
	global_load_dwordx4 v[116:119], v23, s[88:89] offset:1024 nt
	global_load_dwordx4 v[120:123], v23, s[88:89] offset:2048 nt
	global_load_dwordx4 v[124:127], v23, s[88:89] offset:3072 nt
	s_waitcnt vmcnt(15)
	global_store_dwordx4 v22, v[64:67], s[86:87] nt
	s_waitcnt vmcnt(15)
	global_store_dwordx4 v22, v[68:71], s[86:87] offset:1024 nt
	s_waitcnt vmcnt(15)
	global_store_dwordx4 v22, v[72:75], s[86:87] offset:2048 nt
	s_waitcnt vmcnt(15)
	global_store_dwordx4 v22, v[76:79], s[86:87] offset:3072 nt
	s_waitcnt vmcnt(15)
	global_store_dwordx4 v23, v[80:83], s[86:87] nt
	s_waitcnt vmcnt(15)
	global_store_dwordx4 v23, v[84:87], s[86:87] offset:1024 nt
	s_waitcnt vmcnt(15)
	global_store_dwordx4 v23, v[88:91], s[86:87] offset:2048 nt
	s_waitcnt vmcnt(15)
	global_store_dwordx4 v23, v[92:95], s[86:87] offset:3072 nt
	s_waitcnt vmcnt(15)
	global_store_dwordx4 v22, v[96:99], s[90:91] nt
	s_waitcnt vmcnt(15)
	global_store_dwordx4 v22, v[100:103], s[90:91] offset:1024 nt
	s_waitcnt vmcnt(15)
	global_store_dwordx4 v22, v[104:107], s[90:91] offset:2048 nt
	s_waitcnt vmcnt(15)
	global_store_dwordx4 v22, v[108:111], s[90:91] offset:3072 nt
	s_waitcnt vmcnt(15)
	global_store_dwordx4 v23, v[112:115], s[90:91] nt
	s_waitcnt vmcnt(15)
	global_store_dwordx4 v23, v[116:119], s[90:91] offset:1024 nt
	s_waitcnt vmcnt(15)
	global_store_dwordx4 v23, v[120:123], s[90:91] offset:2048 nt
	s_waitcnt vmcnt(15)
	global_store_dwordx4 v23, v[124:127], s[90:91] offset:3072 nt
	s_add_i32 s80, s101, s100
	s_branch .Lcpyd_loop
.Lcpyd_tail:
	s_cmp_lt_u32 s80, 0xba98
	s_cbranch_scc0 .Lcpyd_end
	s_mul_hi_u32 s81, s80, 0x2ad5802b
	s_lshr_b32 s81, s81, 8
	s_mul_i32 s82, s81, 0x5fa
	s_sub_i32 s82, s80, s82
	s_lshl_b32 s82, s82, 13
	s_and_b32 s83, s81, 31
	s_mul_i32 s83, s83, 0xc00000
	s_add_i32 s82, s82, s83
	s_cmp_lt_u32 s81, 32
	s_cselect_b32 s84, s92, s94
	s_cselect_b32 s85, s93, s95
	s_mov_b32 s83, 0x1f210000
	s_cselect_b32 s83, 0x7210000, s83
	s_add_u32 s84, s84, s82
	s_addc_u32 s85, s85, 0
	s_add_u32 s84, s84, 0xc000
	s_addc_u32 s85, s85, 0
	s_add_u32 s83, s83, s82
	s_add_u32 s86, s98, s83
	s_addc_u32 s87, s99, 0
	global_load_dwordx4 v[64:67], v22, s[84:85] nt
	global_load_dwordx4 v[68:71], v22, s[84:85] offset:1024 nt
	global_load_dwordx4 v[72:75], v22, s[84:85] offset:2048 nt
	global_load_dwordx4 v[76:79], v22, s[84:85] offset:3072 nt
	global_load_dwordx4 v[80:83], v23, s[84:85] nt
	global_load_dwordx4 v[84:87], v23, s[84:85] offset:1024 nt
	global_load_dwordx4 v[88:91], v23, s[84:85] offset:2048 nt
	global_load_dwordx4 v[92:95], v23, s[84:85] offset:3072 nt
	s_waitcnt vmcnt(7)
	global_store_dwordx4 v22, v[64:67], s[86:87] nt
	s_waitcnt vmcnt(7)
	global_store_dwordx4 v22, v[68:71], s[86:87] offset:1024 nt
	s_waitcnt vmcnt(7)
	global_store_dwordx4 v22, v[72:75], s[86:87] offset:2048 nt
	s_waitcnt vmcnt(7)
	global_store_dwordx4 v22, v[76:79], s[86:87] offset:3072 nt
	s_waitcnt vmcnt(7)
	global_store_dwordx4 v23, v[80:83], s[86:87] nt
	s_waitcnt vmcnt(7)
	global_store_dwordx4 v23, v[84:87], s[86:87] offset:1024 nt
	s_waitcnt vmcnt(7)
	global_store_dwordx4 v23, v[88:91], s[86:87] offset:2048 nt
	s_waitcnt vmcnt(7)
	global_store_dwordx4 v23, v[92:95], s[86:87] offset:3072 nt

.LBB0_980:
	s_or_b64 exec, exec, s[8:9]
	v_readlane_b32 s4, v234, 2
	v_mov_b32_e32 v8, v174
	v_readlane_b32 s5, v234, 3
	s_barrier
	s_and_b32 s80, s33, 64
	s_cmp_eq_u32 s80, 0
	s_cbranch_scc1 .Lpre3_skip
	v_lshrrev_b32_e32 v21, 6, v174
	v_and_b32_e32 v22, 63, v174
	v_lshlrev_b32_e32 v22, 4, v22
	v_readfirstlane_b32 s80, v21
	v_add_u32_e32 v23, 0x1000, v22
	v_readfirstlane_b32 s92, v235
	v_readfirstlane_b32 s93, v236
	v_readfirstlane_b32 s94, v237
	v_readfirstlane_b32 s95, v238
	v_readfirstlane_b32 s98, v239
	v_readfirstlane_b32 s99, v240
	s_lshr_b32 s100, s33, 7
	s_lshl_b32 s100, s100, 3
	s_lshr_b32 s101, s33, 3
	s_and_b32 s101, s101, 7
	s_add_i32 s100, s100, s101
	s_lshl_b32 s100, s100, 3
	s_add_i32 s80, s80, s100
	s_add_i32 s80, s80, 0xba98
	s_movk_i32 s100, 0x400
.Lcpy3p_loop:
	s_add_i32 s101, s80, s100
	s_cmp_lt_u32 s101, 0xcd4c
	s_cbranch_scc0 .Lcpy3p_tail
	s_mul_hi_u32 s81, s80, 0x2ad5802b
	s_lshr_b32 s81, s81, 8
	s_mul_i32 s82, s81, 0x5fa
	s_sub_i32 s82, s80, s82
	s_lshl_b32 s82, s82, 13
	s_and_b32 s83, s81, 31
	s_mul_i32 s83, s83, 0xc00000
	s_add_i32 s82, s82, s83
	s_cmp_lt_u32 s81, 32
	s_cselect_b32 s84, s92, s94
	s_cselect_b32 s85, s93, s95
	s_mov_b32 s83, 0x1f210000
	s_cselect_b32 s83, 0x7210000, s83
	s_add_u32 s84, s84, s82
	s_addc_u32 s85, s85, 0
	s_add_u32 s84, s84, 0xc000
	s_addc_u32 s85, s85, 0
	s_add_u32 s83, s83, s82
	s_add_u32 s86, s98, s83
	s_addc_u32 s87, s99, 0
	s_mul_hi_u32 s81, s101, 0x2ad5802b
	s_lshr_b32 s81, s81, 8
	s_mul_i32 s82, s81, 0x5fa
	s_sub_i32 s82, s101, s82
	s_lshl_b32 s82, s82, 13
	s_and_b32 s83, s81, 31
	s_mul_i32 s83, s83, 0xc00000
	s_add_i32 s82, s82, s83
	s_cmp_lt_u32 s81, 32
	s_cselect_b32 s88, s92, s94
	s_cselect_b32 s89, s93, s95
	s_mov_b32 s83, 0x1f210000
	s_cselect_b32 s83, 0x7210000, s83
	s_add_u32 s88, s88, s82
	s_addc_u32 s89, s89, 0
	s_add_u32 s88, s88, 0xc000
	s_addc_u32 s89, s89, 0
	s_add_u32 s83, s83, s82
	s_add_u32 s90, s98, s83
	s_addc_u32 s91, s99, 0
	global_load_dwordx4 v[64:67], v22, s[84:85] nt
	global_load_dwordx4 v[68:71], v22, s[84:85] offset:1024 nt
	global_load_dwordx4 v[72:75], v22, s[84:85] offset:2048 nt
	global_load_dwordx4 v[76:79], v22, s[84:85] offset:3072 nt
	global_load_dwordx4 v[80:83], v23, s[84:85] nt
	global_load_dwordx4 v[84:87], v23, s[84:85] offset:1024 nt
	global_load_dwordx4 v[88:91], v23, s[84:85] offset:2048 nt
	global_load_dwordx4 v[92:95], v23, s[84:85] offset:3072 nt
	global_load_dwordx4 v[96:99], v22, s[88:89] nt
	global_load_dwordx4 v[100:103], v22, s[88:89] offset:1024 nt
	global_load_dwordx4 v[104:107], v22, s[88:89] offset:2048 nt
	global_load_dwordx4 v[108:111], v22, s[88:89] offset:3072 nt
	global_load_dwordx4 v[112:115], v23, s[88:89] nt
	global_load_dwordx4 v[116:119], v23, s[88:89] offset:1024 nt
	global_load_dwordx4 v[120:123], v23, s[88:89] offset:2048 nt
	global_load_dwordx4 v[124:127], v23, s[88:89] offset:3072 nt
	s_waitcnt vmcnt(15)
	global_store_dwordx4 v22, v[64:67], s[86:87] nt
	s_waitcnt vmcnt(15)
	global_store_dwordx4 v22, v[68:71], s[86:87] offset:1024 nt
	s_waitcnt vmcnt(15)
	global_store_dwordx4 v22, v[72:75], s[86:87] offset:2048 nt
	s_waitcnt vmcnt(15)
	global_store_dwordx4 v22, v[76:79], s[86:87] offset:3072 nt
	s_waitcnt vmcnt(15)
	global_store_dwordx4 v23, v[80:83], s[86:87] nt
	s_waitcnt vmcnt(15)
	global_store_dwordx4 v23, v[84:87], s[86:87] offset:1024 nt
	s_waitcnt vmcnt(15)
	global_store_dwordx4 v23, v[88:91], s[86:87] offset:2048 nt
	s_waitcnt vmcnt(15)
	global_store_dwordx4 v23, v[92:95], s[86:87] offset:3072 nt
	s_waitcnt vmcnt(15)
	global_store_dwordx4 v22, v[96:99], s[90:91] nt
	s_waitcnt vmcnt(15)
	global_store_dwordx4 v22, v[100:103], s[90:91] offset:1024 nt
	s_waitcnt vmcnt(15)
	global_store_dwordx4 v22, v[104:107], s[90:91] offset:2048 nt
	s_waitcnt vmcnt(15)
	global_store_dwordx4 v22, v[108:111], s[90:91] offset:3072 nt
	s_waitcnt vmcnt(15)
	global_store_dwordx4 v23, v[112:115], s[90:91] nt
	s_waitcnt vmcnt(15)
	global_store_dwordx4 v23, v[116:119], s[90:91] offset:1024 nt
	s_waitcnt vmcnt(15)
	global_store_dwordx4 v23, v[120:123], s[90:91] offset:2048 nt
	s_waitcnt vmcnt(15)
	global_store_dwordx4 v23, v[124:127], s[90:91] offset:3072 nt
	s_add_i32 s80, s101, s100
	s_branch .Lcpy3p_loop
.Lcpy3p_tail:
	s_cmp_lt_u32 s80, 0xcd4c
	s_cbranch_scc0 .Lcpy3p_end
	s_mul_hi_u32 s81, s80, 0x2ad5802b
	s_lshr_b32 s81, s81, 8
	s_mul_i32 s82, s81, 0x5fa
	s_sub_i32 s82, s80, s82
	s_lshl_b32 s82, s82, 13
	s_and_b32 s83, s81, 31
	s_mul_i32 s83, s83, 0xc00000
	s_add_i32 s82, s82, s83
	s_cmp_lt_u32 s81, 32
	s_cselect_b32 s84, s92, s94
	s_cselect_b32 s85, s93, s95
	s_mov_b32 s83, 0x1f210000
	s_cselect_b32 s83, 0x7210000, s83
	s_add_u32 s84, s84, s82
	s_addc_u32 s85, s85, 0
	s_add_u32 s84, s84, 0xc000
	s_addc_u32 s85, s85, 0
	s_add_u32 s83, s83, s82
	s_add_u32 s86, s98, s83
	s_addc_u32 s87, s99, 0
	global_load_dwordx4 v[64:67], v22, s[84:85] nt
	global_load_dwordx4 v[68:71], v22, s[84:85] offset:1024 nt
	global_load_dwordx4 v[72:75], v22, s[84:85] offset:2048 nt
	global_load_dwordx4 v[76:79], v22, s[84:85] offset:3072 nt
	global_load_dwordx4 v[80:83], v23, s[84:85] nt
	global_load_dwordx4 v[84:87], v23, s[84:85] offset:1024 nt
	global_load_dwordx4 v[88:91], v23, s[84:85] offset:2048 nt
	global_load_dwordx4 v[92:95], v23, s[84:85] offset:3072 nt
	s_waitcnt vmcnt(7)
	global_store_dwordx4 v22, v[64:67], s[86:87] nt
	s_waitcnt vmcnt(7)
	global_store_dwordx4 v22, v[68:71], s[86:87] offset:1024 nt
	s_waitcnt vmcnt(7)
	global_store_dwordx4 v22, v[72:75], s[86:87] offset:2048 nt
	s_waitcnt vmcnt(7)
	global_store_dwordx4 v22, v[76:79], s[86:87] offset:3072 nt
	s_waitcnt vmcnt(7)
	global_store_dwordx4 v23, v[80:83], s[86:87] nt
	s_waitcnt vmcnt(7)
	global_store_dwordx4 v23, v[84:87], s[86:87] offset:1024 nt
	s_waitcnt vmcnt(7)
	global_store_dwordx4 v23, v[88:91], s[86:87] offset:2048 nt
	s_waitcnt vmcnt(7)
	global_store_dwordx4 v23, v[92:95], s[86:87] offset:3072 nt

.Lmg3_end:
	v_lshrrev_b32_e32 v21, 6, v174
	v_and_b32_e32 v22, 63, v174
	v_lshlrev_b32_e32 v22, 4, v22
	v_readfirstlane_b32 s80, v21
	v_add_u32_e32 v23, 0x1000, v22
	v_readfirstlane_b32 s92, v235
	v_readfirstlane_b32 s93, v236
	v_readfirstlane_b32 s94, v237
	v_readfirstlane_b32 s95, v238
	v_readfirstlane_b32 s98, v239
	v_readfirstlane_b32 s99, v240
	s_lshr_b32 s100, s33, 7
	s_lshl_b32 s100, s100, 3
	s_lshr_b32 s101, s33, 3
	s_and_b32 s101, s101, 7
	s_add_i32 s100, s100, s101
	s_lshl_b32 s100, s100, 3
	s_add_i32 s80, s80, s100
	s_add_i32 s80, s80, 0xcd4c
	s_movk_i32 s100, 0x400
.Lcpy3_loop:
	s_add_i32 s101, s80, s100
	s_cmp_lt_u32 s101, 0xd388
	s_cbranch_scc0 .Lcpy3_tail
	s_mul_hi_u32 s81, s80, 0x2ad5802b
	s_lshr_b32 s81, s81, 8
	s_mul_i32 s82, s81, 0x5fa
	s_sub_i32 s82, s80, s82
	s_lshl_b32 s82, s82, 13
	s_and_b32 s83, s81, 31
	s_mul_i32 s83, s83, 0xc00000
	s_add_i32 s82, s82, s83
	s_cmp_lt_u32 s81, 32
	s_cselect_b32 s84, s92, s94
	s_cselect_b32 s85, s93, s95
	s_mov_b32 s83, 0x1f210000
	s_cselect_b32 s83, 0x7210000, s83
	s_add_u32 s84, s84, s82
	s_addc_u32 s85, s85, 0
	s_add_u32 s84, s84, 0xc000
	s_addc_u32 s85, s85, 0
	s_add_u32 s83, s83, s82
	s_add_u32 s86, s98, s83
	s_addc_u32 s87, s99, 0
	s_mul_hi_u32 s81, s101, 0x2ad5802b
	s_lshr_b32 s81, s81, 8
	s_mul_i32 s82, s81, 0x5fa
	s_sub_i32 s82, s101, s82
	s_lshl_b32 s82, s82, 13
	s_and_b32 s83, s81, 31
	s_mul_i32 s83, s83, 0xc00000
	s_add_i32 s82, s82, s83
	s_cmp_lt_u32 s81, 32
	s_cselect_b32 s88, s92, s94
	s_cselect_b32 s89, s93, s95
	s_mov_b32 s83, 0x1f210000
	s_cselect_b32 s83, 0x7210000, s83
	s_add_u32 s88, s88, s82
	s_addc_u32 s89, s89, 0
	s_add_u32 s88, s88, 0xc000
	s_addc_u32 s89, s89, 0
	s_add_u32 s83, s83, s82
	s_add_u32 s90, s98, s83
	s_addc_u32 s91, s99, 0
	global_load_dwordx4 v[64:67], v22, s[84:85] nt
	global_load_dwordx4 v[68:71], v22, s[84:85] offset:1024 nt
	global_load_dwordx4 v[72:75], v22, s[84:85] offset:2048 nt
	global_load_dwordx4 v[76:79], v22, s[84:85] offset:3072 nt
	global_load_dwordx4 v[80:83], v23, s[84:85] nt
	global_load_dwordx4 v[84:87], v23, s[84:85] offset:1024 nt
	global_load_dwordx4 v[88:91], v23, s[84:85] offset:2048 nt
	global_load_dwordx4 v[92:95], v23, s[84:85] offset:3072 nt
	global_load_dwordx4 v[96:99], v22, s[88:89] nt
	global_load_dwordx4 v[100:103], v22, s[88:89] offset:1024 nt
	global_load_dwordx4 v[104:107], v22, s[88:89] offset:2048 nt
	global_load_dwordx4 v[108:111], v22, s[88:89] offset:3072 nt
	global_load_dwordx4 v[112:115], v23, s[88:89] nt
	global_load_dwordx4 v[116:119], v23, s[88:89] offset:1024 nt
	global_load_dwordx4 v[120:123], v23, s[88:89] offset:2048 nt
	global_load_dwordx4 v[124:127], v23, s[88:89] offset:3072 nt
	s_waitcnt vmcnt(15)
	global_store_dwordx4 v22, v[64:67], s[86:87] nt
	s_waitcnt vmcnt(15)
	global_store_dwordx4 v22, v[68:71], s[86:87] offset:1024 nt
	s_waitcnt vmcnt(15)
	global_store_dwordx4 v22, v[72:75], s[86:87] offset:2048 nt
	s_waitcnt vmcnt(15)
	global_store_dwordx4 v22, v[76:79], s[86:87] offset:3072 nt
	s_waitcnt vmcnt(15)
	global_store_dwordx4 v23, v[80:83], s[86:87] nt
	s_waitcnt vmcnt(15)
	global_store_dwordx4 v23, v[84:87], s[86:87] offset:1024 nt
	s_waitcnt vmcnt(15)
	global_store_dwordx4 v23, v[88:91], s[86:87] offset:2048 nt
	s_waitcnt vmcnt(15)
	global_store_dwordx4 v23, v[92:95], s[86:87] offset:3072 nt
	s_waitcnt vmcnt(15)
	global_store_dwordx4 v22, v[96:99], s[90:91] nt
	s_waitcnt vmcnt(15)
	global_store_dwordx4 v22, v[100:103], s[90:91] offset:1024 nt
	s_waitcnt vmcnt(15)
	global_store_dwordx4 v22, v[104:107], s[90:91] offset:2048 nt
	s_waitcnt vmcnt(15)
	global_store_dwordx4 v22, v[108:111], s[90:91] offset:3072 nt
	s_waitcnt vmcnt(15)
	global_store_dwordx4 v23, v[112:115], s[90:91] nt
	s_waitcnt vmcnt(15)
	global_store_dwordx4 v23, v[116:119], s[90:91] offset:1024 nt
	s_waitcnt vmcnt(15)
	global_store_dwordx4 v23, v[120:123], s[90:91] offset:2048 nt
	s_waitcnt vmcnt(15)
	global_store_dwordx4 v23, v[124:127], s[90:91] offset:3072 nt
	s_add_i32 s80, s101, s100
	s_branch .Lcpy3_loop
.Lcpy3_tail:
	s_cmp_lt_u32 s80, 0xd388
	s_cbranch_scc0 .Lcpy3_end
	s_mul_hi_u32 s81, s80, 0x2ad5802b
	s_lshr_b32 s81, s81, 8
	s_mul_i32 s82, s81, 0x5fa
	s_sub_i32 s82, s80, s82
	s_lshl_b32 s82, s82, 13
	s_and_b32 s83, s81, 31
	s_mul_i32 s83, s83, 0xc00000
	s_add_i32 s82, s82, s83
	s_cmp_lt_u32 s81, 32
	s_cselect_b32 s84, s92, s94
	s_cselect_b32 s85, s93, s95
	s_mov_b32 s83, 0x1f210000
	s_cselect_b32 s83, 0x7210000, s83
	s_add_u32 s84, s84, s82
	s_addc_u32 s85, s85, 0
	s_add_u32 s84, s84, 0xc000
	s_addc_u32 s85, s85, 0
	s_add_u32 s83, s83, s82
	s_add_u32 s86, s98, s83
	s_addc_u32 s87, s99, 0
	global_load_dwordx4 v[64:67], v22, s[84:85] nt
	global_load_dwordx4 v[68:71], v22, s[84:85] offset:1024 nt
	global_load_dwordx4 v[72:75], v22, s[84:85] offset:2048 nt
	global_load_dwordx4 v[76:79], v22, s[84:85] offset:3072 nt
	global_load_dwordx4 v[80:83], v23, s[84:85] nt
	global_load_dwordx4 v[84:87], v23, s[84:85] offset:1024 nt
	global_load_dwordx4 v[88:91], v23, s[84:85] offset:2048 nt
	global_load_dwordx4 v[92:95], v23, s[84:85] offset:3072 nt
	s_waitcnt vmcnt(7)
	global_store_dwordx4 v22, v[64:67], s[86:87] nt
	s_waitcnt vmcnt(7)
	global_store_dwordx4 v22, v[68:71], s[86:87] offset:1024 nt
	s_waitcnt vmcnt(7)
	global_store_dwordx4 v22, v[72:75], s[86:87] offset:2048 nt
	s_waitcnt vmcnt(7)
	global_store_dwordx4 v22, v[76:79], s[86:87] offset:3072 nt
	s_waitcnt vmcnt(7)
	global_store_dwordx4 v23, v[80:83], s[86:87] nt
	s_waitcnt vmcnt(7)
	global_store_dwordx4 v23, v[84:87], s[86:87] offset:1024 nt
	s_waitcnt vmcnt(7)
	global_store_dwordx4 v23, v[88:91], s[86:87] offset:2048 nt
	s_waitcnt vmcnt(7)
	global_store_dwordx4 v23, v[92:95], s[86:87] offset:3072 nt

.LBB0_1288:
	s_cmp_lt_u32 s33, 1072
	s_cbranch_scc1 .Lcpye_end
	v_lshrrev_b32_e32 v21, 6, v174
	v_and_b32_e32 v22, 63, v174
	v_lshlrev_b32_e32 v22, 4, v22
	v_readfirstlane_b32 s80, v21
	v_add_u32_e32 v23, 0x1000, v22
	v_readfirstlane_b32 s92, v235
	v_readfirstlane_b32 s93, v236
	v_readfirstlane_b32 s94, v237
	v_readfirstlane_b32 s95, v238
	v_readfirstlane_b32 s98, v239
	v_readfirstlane_b32 s99, v240
	s_add_i32 s80, s80, s33
	s_add_i32 s80, s80, 0xcf58
	s_sub_i32 s100, s78, 134
	s_lshl_b32 s100, s100, 3
.Lcpye_loop:
	s_add_i32 s101, s80, s100
	s_cmp_lt_u32 s101, 0xf2c8
	s_cbranch_scc0 .Lcpye_tail
	s_mul_hi_u32 s81, s80, 0x2ad5802b
	s_lshr_b32 s81, s81, 8
	s_mul_i32 s82, s81, 0x5fa
	s_sub_i32 s82, s80, s82
	s_lshl_b32 s82, s82, 13
	s_and_b32 s83, s81, 31
	s_mul_i32 s83, s83, 0xc00000
	s_add_i32 s82, s82, s83
	s_cmp_lt_u32 s81, 32
	s_cselect_b32 s84, s92, s94
	s_cselect_b32 s85, s93, s95
	s_mov_b32 s83, 0x1f210000
	s_cselect_b32 s83, 0x7210000, s83
	s_add_u32 s84, s84, s82
	s_addc_u32 s85, s85, 0
	s_add_u32 s84, s84, 0xc000
	s_addc_u32 s85, s85, 0
	s_add_u32 s83, s83, s82
	s_add_u32 s86, s98, s83
	s_addc_u32 s87, s99, 0
	s_mul_hi_u32 s81, s101, 0x2ad5802b
	s_lshr_b32 s81, s81, 8
	s_mul_i32 s82, s81, 0x5fa
	s_sub_i32 s82, s101, s82
	s_lshl_b32 s82, s82, 13
	s_and_b32 s83, s81, 31
	s_mul_i32 s83, s83, 0xc00000
	s_add_i32 s82, s82, s83
	s_cmp_lt_u32 s81, 32
	s_cselect_b32 s88, s92, s94
	s_cselect_b32 s89, s93, s95
	s_mov_b32 s83, 0x1f210000
	s_cselect_b32 s83, 0x7210000, s83
	s_add_u32 s88, s88, s82
	s_addc_u32 s89, s89, 0
	s_add_u32 s88, s88, 0xc000
	s_addc_u32 s89, s89, 0
	s_add_u32 s83, s83, s82
	s_add_u32 s90, s98, s83
	s_addc_u32 s91, s99, 0
	global_load_dwordx4 v[64:67], v22, s[84:85] nt
	global_load_dwordx4 v[68:71], v22, s[84:85] offset:1024 nt
	global_load_dwordx4 v[72:75], v22, s[84:85] offset:2048 nt
	global_load_dwordx4 v[76:79], v22, s[84:85] offset:3072 nt
	global_load_dwordx4 v[80:83], v23, s[84:85] nt
	global_load_dwordx4 v[84:87], v23, s[84:85] offset:1024 nt
	global_load_dwordx4 v[88:91], v23, s[84:85] offset:2048 nt
	global_load_dwordx4 v[92:95], v23, s[84:85] offset:3072 nt
	global_load_dwordx4 v[96:99], v22, s[88:89] nt
	global_load_dwordx4 v[100:103], v22, s[88:89] offset:1024 nt
	global_load_dwordx4 v[104:107], v22, s[88:89] offset:2048 nt
	global_load_dwordx4 v[108:111], v22, s[88:89] offset:3072 nt
	global_load_dwordx4 v[112:115], v23, s[88:89] nt
	global_load_dwordx4 v[116:119], v23, s[88:89] offset:1024 nt
	global_load_dwordx4 v[120:123], v23, s[88:89] offset:2048 nt
	global_load_dwordx4 v[124:127], v23, s[88:89] offset:3072 nt
	s_waitcnt vmcnt(15)
	global_store_dwordx4 v22, v[64:67], s[86:87] nt
	s_waitcnt vmcnt(15)
	global_store_dwordx4 v22, v[68:71], s[86:87] offset:1024 nt
	s_waitcnt vmcnt(15)
	global_store_dwordx4 v22, v[72:75], s[86:87] offset:2048 nt
	s_waitcnt vmcnt(15)
	global_store_dwordx4 v22, v[76:79], s[86:87] offset:3072 nt
	s_waitcnt vmcnt(15)
	global_store_dwordx4 v23, v[80:83], s[86:87] nt
	s_waitcnt vmcnt(15)
	global_store_dwordx4 v23, v[84:87], s[86:87] offset:1024 nt
	s_waitcnt vmcnt(15)
	global_store_dwordx4 v23, v[88:91], s[86:87] offset:2048 nt
	s_waitcnt vmcnt(15)
	global_store_dwordx4 v23, v[92:95], s[86:87] offset:3072 nt
	s_waitcnt vmcnt(15)
	global_store_dwordx4 v22, v[96:99], s[90:91] nt
	s_waitcnt vmcnt(15)
	global_store_dwordx4 v22, v[100:103], s[90:91] offset:1024 nt
	s_waitcnt vmcnt(15)
	global_store_dwordx4 v22, v[104:107], s[90:91] offset:2048 nt
	s_waitcnt vmcnt(15)
	global_store_dwordx4 v22, v[108:111], s[90:91] offset:3072 nt
	s_waitcnt vmcnt(15)
	global_store_dwordx4 v23, v[112:115], s[90:91] nt
	s_waitcnt vmcnt(15)
	global_store_dwordx4 v23, v[116:119], s[90:91] offset:1024 nt
	s_waitcnt vmcnt(15)
	global_store_dwordx4 v23, v[120:123], s[90:91] offset:2048 nt
	s_waitcnt vmcnt(15)
	global_store_dwordx4 v23, v[124:127], s[90:91] offset:3072 nt
	s_add_i32 s80, s101, s100
	s_branch .Lcpye_loop
.Lcpye_tail:
	s_cmp_lt_u32 s80, 0xf2c8
	s_cbranch_scc0 .Lcpye_end
	s_mul_hi_u32 s81, s80, 0x2ad5802b
	s_lshr_b32 s81, s81, 8
	s_mul_i32 s82, s81, 0x5fa
	s_sub_i32 s82, s80, s82
	s_lshl_b32 s82, s82, 13
	s_and_b32 s83, s81, 31
	s_mul_i32 s83, s83, 0xc00000
	s_add_i32 s82, s82, s83
	s_cmp_lt_u32 s81, 32
	s_cselect_b32 s84, s92, s94
	s_cselect_b32 s85, s93, s95
	s_mov_b32 s83, 0x1f210000
	s_cselect_b32 s83, 0x7210000, s83
	s_add_u32 s84, s84, s82
	s_addc_u32 s85, s85, 0
	s_add_u32 s84, s84, 0xc000
	s_addc_u32 s85, s85, 0
	s_add_u32 s83, s83, s82
	s_add_u32 s86, s98, s83
	s_addc_u32 s87, s99, 0
	global_load_dwordx4 v[64:67], v22, s[84:85] nt
	global_load_dwordx4 v[68:71], v22, s[84:85] offset:1024 nt
	global_load_dwordx4 v[72:75], v22, s[84:85] offset:2048 nt
	global_load_dwordx4 v[76:79], v22, s[84:85] offset:3072 nt
	global_load_dwordx4 v[80:83], v23, s[84:85] nt
	global_load_dwordx4 v[84:87], v23, s[84:85] offset:1024 nt
	global_load_dwordx4 v[88:91], v23, s[84:85] offset:2048 nt
	global_load_dwordx4 v[92:95], v23, s[84:85] offset:3072 nt
	s_waitcnt vmcnt(7)
	global_store_dwordx4 v22, v[64:67], s[86:87] nt
	s_waitcnt vmcnt(7)
	global_store_dwordx4 v22, v[68:71], s[86:87] offset:1024 nt
	s_waitcnt vmcnt(7)
	global_store_dwordx4 v22, v[72:75], s[86:87] offset:2048 nt
	s_waitcnt vmcnt(7)
	global_store_dwordx4 v22, v[76:79], s[86:87] offset:3072 nt
	s_waitcnt vmcnt(7)
	global_store_dwordx4 v23, v[80:83], s[86:87] nt
	s_waitcnt vmcnt(7)
	global_store_dwordx4 v23, v[84:87], s[86:87] offset:1024 nt
	s_waitcnt vmcnt(7)
	global_store_dwordx4 v23, v[88:91], s[86:87] offset:2048 nt
	s_waitcnt vmcnt(7)
	global_store_dwordx4 v23, v[92:95], s[86:87] offset:3072 nt

.LBB0_1383:
	s_or_b64 exec, exec, s[8:9]
	v_readlane_b32 s4, v234, 2
	v_mov_b32_e32 v8, v174
	v_readlane_b32 s5, v234, 3
	s_barrier
	s_and_b32 s80, s33, 64
	s_cmp_eq_u32 s80, 0
	s_cbranch_scc1 .Lpref_skip
	v_lshrrev_b32_e32 v21, 6, v174
	v_and_b32_e32 v22, 63, v174
	v_lshlrev_b32_e32 v22, 4, v22
	v_readfirstlane_b32 s80, v21
	v_add_u32_e32 v23, 0x1000, v22
	v_readfirstlane_b32 s92, v235
	v_readfirstlane_b32 s93, v236
	v_readfirstlane_b32 s94, v237
	v_readfirstlane_b32 s95, v238
	v_readfirstlane_b32 s98, v239
	v_readfirstlane_b32 s99, v240
	s_lshr_b32 s100, s33, 7
	s_lshl_b32 s100, s100, 3
	s_lshr_b32 s101, s33, 3
	s_and_b32 s101, s101, 7
	s_add_i32 s100, s100, s101
	s_lshl_b32 s100, s100, 3
	s_add_i32 s80, s80, s100
	s_add_i32 s80, s80, 0xf2c8
	s_movk_i32 s100, 0x400
.Lcpyfp_loop:
	s_add_i32 s101, s80, s100
	s_cmp_lt_u32 s101, 0x1016e
	s_cbranch_scc0 .Lcpyfp_tail
	s_mul_hi_u32 s81, s80, 0x2ad5802b
	s_lshr_b32 s81, s81, 8
	s_mul_i32 s82, s81, 0x5fa
	s_sub_i32 s82, s80, s82
	s_lshl_b32 s82, s82, 13
	s_and_b32 s83, s81, 31
	s_mul_i32 s83, s83, 0xc00000
	s_add_i32 s82, s82, s83
	s_cmp_lt_u32 s81, 32
	s_cselect_b32 s84, s92, s94
	s_cselect_b32 s85, s93, s95
	s_mov_b32 s83, 0x1f210000
	s_cselect_b32 s83, 0x7210000, s83
	s_add_u32 s84, s84, s82
	s_addc_u32 s85, s85, 0
	s_add_u32 s84, s84, 0xc000
	s_addc_u32 s85, s85, 0
	s_add_u32 s83, s83, s82
	s_add_u32 s86, s98, s83
	s_addc_u32 s87, s99, 0
	s_mul_hi_u32 s81, s101, 0x2ad5802b
	s_lshr_b32 s81, s81, 8
	s_mul_i32 s82, s81, 0x5fa
	s_sub_i32 s82, s101, s82
	s_lshl_b32 s82, s82, 13
	s_and_b32 s83, s81, 31
	s_mul_i32 s83, s83, 0xc00000
	s_add_i32 s82, s82, s83
	s_cmp_lt_u32 s81, 32
	s_cselect_b32 s88, s92, s94
	s_cselect_b32 s89, s93, s95
	s_mov_b32 s83, 0x1f210000
	s_cselect_b32 s83, 0x7210000, s83
	s_add_u32 s88, s88, s82
	s_addc_u32 s89, s89, 0
	s_add_u32 s88, s88, 0xc000
	s_addc_u32 s89, s89, 0
	s_add_u32 s83, s83, s82
	s_add_u32 s90, s98, s83
	s_addc_u32 s91, s99, 0
	global_load_dwordx4 v[64:67], v22, s[84:85] nt
	global_load_dwordx4 v[68:71], v22, s[84:85] offset:1024 nt
	global_load_dwordx4 v[72:75], v22, s[84:85] offset:2048 nt
	global_load_dwordx4 v[76:79], v22, s[84:85] offset:3072 nt
	global_load_dwordx4 v[80:83], v23, s[84:85] nt
	global_load_dwordx4 v[84:87], v23, s[84:85] offset:1024 nt
	global_load_dwordx4 v[88:91], v23, s[84:85] offset:2048 nt
	global_load_dwordx4 v[92:95], v23, s[84:85] offset:3072 nt
	global_load_dwordx4 v[96:99], v22, s[88:89] nt
	global_load_dwordx4 v[100:103], v22, s[88:89] offset:1024 nt
	global_load_dwordx4 v[104:107], v22, s[88:89] offset:2048 nt
	global_load_dwordx4 v[108:111], v22, s[88:89] offset:3072 nt
	global_load_dwordx4 v[112:115], v23, s[88:89] nt
	global_load_dwordx4 v[116:119], v23, s[88:89] offset:1024 nt
	global_load_dwordx4 v[120:123], v23, s[88:89] offset:2048 nt
	global_load_dwordx4 v[124:127], v23, s[88:89] offset:3072 nt
	s_waitcnt vmcnt(15)
	global_store_dwordx4 v22, v[64:67], s[86:87] nt
	s_waitcnt vmcnt(15)
	global_store_dwordx4 v22, v[68:71], s[86:87] offset:1024 nt
	s_waitcnt vmcnt(15)
	global_store_dwordx4 v22, v[72:75], s[86:87] offset:2048 nt
	s_waitcnt vmcnt(15)
	global_store_dwordx4 v22, v[76:79], s[86:87] offset:3072 nt
	s_waitcnt vmcnt(15)
	global_store_dwordx4 v23, v[80:83], s[86:87] nt
	s_waitcnt vmcnt(15)
	global_store_dwordx4 v23, v[84:87], s[86:87] offset:1024 nt
	s_waitcnt vmcnt(15)
	global_store_dwordx4 v23, v[88:91], s[86:87] offset:2048 nt
	s_waitcnt vmcnt(15)
	global_store_dwordx4 v23, v[92:95], s[86:87] offset:3072 nt
	s_waitcnt vmcnt(15)
	global_store_dwordx4 v22, v[96:99], s[90:91] nt
	s_waitcnt vmcnt(15)
	global_store_dwordx4 v22, v[100:103], s[90:91] offset:1024 nt
	s_waitcnt vmcnt(15)
	global_store_dwordx4 v22, v[104:107], s[90:91] offset:2048 nt
	s_waitcnt vmcnt(15)
	global_store_dwordx4 v22, v[108:111], s[90:91] offset:3072 nt
	s_waitcnt vmcnt(15)
	global_store_dwordx4 v23, v[112:115], s[90:91] nt
	s_waitcnt vmcnt(15)
	global_store_dwordx4 v23, v[116:119], s[90:91] offset:1024 nt
	s_waitcnt vmcnt(15)
	global_store_dwordx4 v23, v[120:123], s[90:91] offset:2048 nt
	s_waitcnt vmcnt(15)
	global_store_dwordx4 v23, v[124:127], s[90:91] offset:3072 nt
	s_add_i32 s80, s101, s100
	s_branch .Lcpyfp_loop
.Lcpyfp_tail:
	s_cmp_lt_u32 s80, 0x1016e
	s_cbranch_scc0 .Lcpyfp_end
	s_mul_hi_u32 s81, s80, 0x2ad5802b
	s_lshr_b32 s81, s81, 8
	s_mul_i32 s82, s81, 0x5fa
	s_sub_i32 s82, s80, s82
	s_lshl_b32 s82, s82, 13
	s_and_b32 s83, s81, 31
	s_mul_i32 s83, s83, 0xc00000
	s_add_i32 s82, s82, s83
	s_cmp_lt_u32 s81, 32
	s_cselect_b32 s84, s92, s94
	s_cselect_b32 s85, s93, s95
	s_mov_b32 s83, 0x1f210000
	s_cselect_b32 s83, 0x7210000, s83
	s_add_u32 s84, s84, s82
	s_addc_u32 s85, s85, 0
	s_add_u32 s84, s84, 0xc000
	s_addc_u32 s85, s85, 0
	s_add_u32 s83, s83, s82
	s_add_u32 s86, s98, s83
	s_addc_u32 s87, s99, 0
	global_load_dwordx4 v[64:67], v22, s[84:85] nt
	global_load_dwordx4 v[68:71], v22, s[84:85] offset:1024 nt
	global_load_dwordx4 v[72:75], v22, s[84:85] offset:2048 nt
	global_load_dwordx4 v[76:79], v22, s[84:85] offset:3072 nt
	global_load_dwordx4 v[80:83], v23, s[84:85] nt
	global_load_dwordx4 v[84:87], v23, s[84:85] offset:1024 nt
	global_load_dwordx4 v[88:91], v23, s[84:85] offset:2048 nt
	global_load_dwordx4 v[92:95], v23, s[84:85] offset:3072 nt
	s_waitcnt vmcnt(7)
	global_store_dwordx4 v22, v[64:67], s[86:87] nt
	s_waitcnt vmcnt(7)
	global_store_dwordx4 v22, v[68:71], s[86:87] offset:1024 nt
	s_waitcnt vmcnt(7)
	global_store_dwordx4 v22, v[72:75], s[86:87] offset:2048 nt
	s_waitcnt vmcnt(7)
	global_store_dwordx4 v22, v[76:79], s[86:87] offset:3072 nt
	s_waitcnt vmcnt(7)
	global_store_dwordx4 v23, v[80:83], s[86:87] nt
	s_waitcnt vmcnt(7)
	global_store_dwordx4 v23, v[84:87], s[86:87] offset:1024 nt
	s_waitcnt vmcnt(7)
	global_store_dwordx4 v23, v[88:91], s[86:87] offset:2048 nt
	s_waitcnt vmcnt(7)
	global_store_dwordx4 v23, v[92:95], s[86:87] offset:3072 nt

.Lmgf_end:
	v_lshrrev_b32_e32 v21, 6, v174
	v_and_b32_e32 v22, 63, v174
	v_lshlrev_b32_e32 v22, 4, v22
	v_readfirstlane_b32 s80, v21
	v_add_u32_e32 v23, 0x1000, v22
	v_readfirstlane_b32 s92, v235
	v_readfirstlane_b32 s93, v236
	v_readfirstlane_b32 s94, v237
	v_readfirstlane_b32 s95, v238
	v_readfirstlane_b32 s98, v239
	v_readfirstlane_b32 s99, v240
	s_lshr_b32 s100, s33, 7
	s_lshl_b32 s100, s100, 3
	s_lshr_b32 s101, s33, 3
	s_and_b32 s101, s101, 7
	s_add_i32 s100, s100, s101
	s_lshl_b32 s100, s100, 3
	s_add_i32 s80, s80, s100
	s_add_i32 s80, s80, 0x1016e
	s_movk_i32 s100, 0x400
.Lcpyf_loop:
	s_add_i32 s101, s80, s100
	s_cmp_lt_u32 s101, 0x10650
	s_cbranch_scc0 .Lcpyf_tail
	s_mul_hi_u32 s81, s80, 0x2ad5802b
	s_lshr_b32 s81, s81, 8
	s_mul_i32 s82, s81, 0x5fa
	s_sub_i32 s82, s80, s82
	s_lshl_b32 s82, s82, 13
	s_and_b32 s83, s81, 31
	s_mul_i32 s83, s83, 0xc00000
	s_add_i32 s82, s82, s83
	s_cmp_lt_u32 s81, 32
	s_cselect_b32 s84, s92, s94
	s_cselect_b32 s85, s93, s95
	s_mov_b32 s83, 0x1f210000
	s_cselect_b32 s83, 0x7210000, s83
	s_add_u32 s84, s84, s82
	s_addc_u32 s85, s85, 0
	s_add_u32 s84, s84, 0xc000
	s_addc_u32 s85, s85, 0
	s_add_u32 s83, s83, s82
	s_add_u32 s86, s98, s83
	s_addc_u32 s87, s99, 0
	s_mul_hi_u32 s81, s101, 0x2ad5802b
	s_lshr_b32 s81, s81, 8
	s_mul_i32 s82, s81, 0x5fa
	s_sub_i32 s82, s101, s82
	s_lshl_b32 s82, s82, 13
	s_and_b32 s83, s81, 31
	s_mul_i32 s83, s83, 0xc00000
	s_add_i32 s82, s82, s83
	s_cmp_lt_u32 s81, 32
	s_cselect_b32 s88, s92, s94
	s_cselect_b32 s89, s93, s95
	s_mov_b32 s83, 0x1f210000
	s_cselect_b32 s83, 0x7210000, s83
	s_add_u32 s88, s88, s82
	s_addc_u32 s89, s89, 0
	s_add_u32 s88, s88, 0xc000
	s_addc_u32 s89, s89, 0
	s_add_u32 s83, s83, s82
	s_add_u32 s90, s98, s83
	s_addc_u32 s91, s99, 0
	global_load_dwordx4 v[64:67], v22, s[84:85] nt
	global_load_dwordx4 v[68:71], v22, s[84:85] offset:1024 nt
	global_load_dwordx4 v[72:75], v22, s[84:85] offset:2048 nt
	global_load_dwordx4 v[76:79], v22, s[84:85] offset:3072 nt
	global_load_dwordx4 v[80:83], v23, s[84:85] nt
	global_load_dwordx4 v[84:87], v23, s[84:85] offset:1024 nt
	global_load_dwordx4 v[88:91], v23, s[84:85] offset:2048 nt
	global_load_dwordx4 v[92:95], v23, s[84:85] offset:3072 nt
	global_load_dwordx4 v[96:99], v22, s[88:89] nt
	global_load_dwordx4 v[100:103], v22, s[88:89] offset:1024 nt
	global_load_dwordx4 v[104:107], v22, s[88:89] offset:2048 nt
	global_load_dwordx4 v[108:111], v22, s[88:89] offset:3072 nt
	global_load_dwordx4 v[112:115], v23, s[88:89] nt
	global_load_dwordx4 v[116:119], v23, s[88:89] offset:1024 nt
	global_load_dwordx4 v[120:123], v23, s[88:89] offset:2048 nt
	global_load_dwordx4 v[124:127], v23, s[88:89] offset:3072 nt
	s_waitcnt vmcnt(15)
	global_store_dwordx4 v22, v[64:67], s[86:87] nt
	s_waitcnt vmcnt(15)
	global_store_dwordx4 v22, v[68:71], s[86:87] offset:1024 nt
	s_waitcnt vmcnt(15)
	global_store_dwordx4 v22, v[72:75], s[86:87] offset:2048 nt
	s_waitcnt vmcnt(15)
	global_store_dwordx4 v22, v[76:79], s[86:87] offset:3072 nt
	s_waitcnt vmcnt(15)
	global_store_dwordx4 v23, v[80:83], s[86:87] nt
	s_waitcnt vmcnt(15)
	global_store_dwordx4 v23, v[84:87], s[86:87] offset:1024 nt
	s_waitcnt vmcnt(15)
	global_store_dwordx4 v23, v[88:91], s[86:87] offset:2048 nt
	s_waitcnt vmcnt(15)
	global_store_dwordx4 v23, v[92:95], s[86:87] offset:3072 nt
	s_waitcnt vmcnt(15)
	global_store_dwordx4 v22, v[96:99], s[90:91] nt
	s_waitcnt vmcnt(15)
	global_store_dwordx4 v22, v[100:103], s[90:91] offset:1024 nt
	s_waitcnt vmcnt(15)
	global_store_dwordx4 v22, v[104:107], s[90:91] offset:2048 nt
	s_waitcnt vmcnt(15)
	global_store_dwordx4 v22, v[108:111], s[90:91] offset:3072 nt
	s_waitcnt vmcnt(15)
	global_store_dwordx4 v23, v[112:115], s[90:91] nt
	s_waitcnt vmcnt(15)
	global_store_dwordx4 v23, v[116:119], s[90:91] offset:1024 nt
	s_waitcnt vmcnt(15)
	global_store_dwordx4 v23, v[120:123], s[90:91] offset:2048 nt
	s_waitcnt vmcnt(15)
	global_store_dwordx4 v23, v[124:127], s[90:91] offset:3072 nt
	s_add_i32 s80, s101, s100
	s_branch .Lcpyf_loop
.Lcpyf_tail:
	s_cmp_lt_u32 s80, 0x10650
	s_cbranch_scc0 .Lcpyf_end
	s_mul_hi_u32 s81, s80, 0x2ad5802b
	s_lshr_b32 s81, s81, 8
	s_mul_i32 s82, s81, 0x5fa
	s_sub_i32 s82, s80, s82
	s_lshl_b32 s82, s82, 13
	s_and_b32 s83, s81, 31
	s_mul_i32 s83, s83, 0xc00000
	s_add_i32 s82, s82, s83
	s_cmp_lt_u32 s81, 32
	s_cselect_b32 s84, s92, s94
	s_cselect_b32 s85, s93, s95
	s_mov_b32 s83, 0x1f210000
	s_cselect_b32 s83, 0x7210000, s83
	s_add_u32 s84, s84, s82
	s_addc_u32 s85, s85, 0
	s_add_u32 s84, s84, 0xc000
	s_addc_u32 s85, s85, 0
	s_add_u32 s83, s83, s82
	s_add_u32 s86, s98, s83
	s_addc_u32 s87, s99, 0
	global_load_dwordx4 v[64:67], v22, s[84:85] nt
	global_load_dwordx4 v[68:71], v22, s[84:85] offset:1024 nt
	global_load_dwordx4 v[72:75], v22, s[84:85] offset:2048 nt
	global_load_dwordx4 v[76:79], v22, s[84:85] offset:3072 nt
	global_load_dwordx4 v[80:83], v23, s[84:85] nt
	global_load_dwordx4 v[84:87], v23, s[84:85] offset:1024 nt
	global_load_dwordx4 v[88:91], v23, s[84:85] offset:2048 nt
	global_load_dwordx4 v[92:95], v23, s[84:85] offset:3072 nt
	s_waitcnt vmcnt(7)
	global_store_dwordx4 v22, v[64:67], s[86:87] nt
	s_waitcnt vmcnt(7)
	global_store_dwordx4 v22, v[68:71], s[86:87] offset:1024 nt
	s_waitcnt vmcnt(7)
	global_store_dwordx4 v22, v[72:75], s[86:87] offset:2048 nt
	s_waitcnt vmcnt(7)
	global_store_dwordx4 v22, v[76:79], s[86:87] offset:3072 nt
	s_waitcnt vmcnt(7)
	global_store_dwordx4 v23, v[80:83], s[86:87] nt
	s_waitcnt vmcnt(7)
	global_store_dwordx4 v23, v[84:87], s[86:87] offset:1024 nt
	s_waitcnt vmcnt(7)
	global_store_dwordx4 v23, v[88:91], s[86:87] offset:2048 nt
	s_waitcnt vmcnt(7)
	global_store_dwordx4 v23, v[92:95], s[86:87] offset:3072 nt

.LBB0_1461:
	s_cmp_lt_u32 s33, 1200
	s_cbranch_scc1 .Lcpyg_end
	v_lshrrev_b32_e32 v21, 6, v174
	v_and_b32_e32 v22, 63, v174
	v_lshlrev_b32_e32 v22, 4, v22
	v_readfirstlane_b32 s80, v21
	v_add_u32_e32 v23, 0x1000, v22
	v_readfirstlane_b32 s92, v235
	v_readfirstlane_b32 s93, v236
	v_readfirstlane_b32 s94, v237
	v_readfirstlane_b32 s95, v238
	v_readfirstlane_b32 s98, v239
	v_readfirstlane_b32 s99, v240
	s_add_i32 s80, s80, s33
	s_add_i32 s80, s80, 0x101a0
	s_sub_i32 s100, s78, 150
	s_lshl_b32 s100, s100, 3
.Lcpyg_loop:
	s_add_i32 s101, s80, s100
	s_cmp_lt_u32 s101, 0x12590
	s_cbranch_scc0 .Lcpyg_tail
	s_mul_hi_u32 s81, s80, 0x2ad5802b
	s_lshr_b32 s81, s81, 8
	s_mul_i32 s82, s81, 0x5fa
	s_sub_i32 s82, s80, s82
	s_lshl_b32 s82, s82, 13
	s_and_b32 s83, s81, 31
	s_mul_i32 s83, s83, 0xc00000
	s_add_i32 s82, s82, s83
	s_cmp_lt_u32 s81, 32
	s_cselect_b32 s84, s92, s94
	s_cselect_b32 s85, s93, s95
	s_mov_b32 s83, 0x1f210000
	s_cselect_b32 s83, 0x7210000, s83
	s_add_u32 s84, s84, s82
	s_addc_u32 s85, s85, 0
	s_add_u32 s84, s84, 0xc000
	s_addc_u32 s85, s85, 0
	s_add_u32 s83, s83, s82
	s_add_u32 s86, s98, s83
	s_addc_u32 s87, s99, 0
	s_mul_hi_u32 s81, s101, 0x2ad5802b
	s_lshr_b32 s81, s81, 8
	s_mul_i32 s82, s81, 0x5fa
	s_sub_i32 s82, s101, s82
	s_lshl_b32 s82, s82, 13
	s_and_b32 s83, s81, 31
	s_mul_i32 s83, s83, 0xc00000
	s_add_i32 s82, s82, s83
	s_cmp_lt_u32 s81, 32
	s_cselect_b32 s88, s92, s94
	s_cselect_b32 s89, s93, s95
	s_mov_b32 s83, 0x1f210000
	s_cselect_b32 s83, 0x7210000, s83
	s_add_u32 s88, s88, s82
	s_addc_u32 s89, s89, 0
	s_add_u32 s88, s88, 0xc000
	s_addc_u32 s89, s89, 0
	s_add_u32 s83, s83, s82
	s_add_u32 s90, s98, s83
	s_addc_u32 s91, s99, 0
	global_load_dwordx4 v[64:67], v22, s[84:85] nt
	global_load_dwordx4 v[68:71], v22, s[84:85] offset:1024 nt
	global_load_dwordx4 v[72:75], v22, s[84:85] offset:2048 nt
	global_load_dwordx4 v[76:79], v22, s[84:85] offset:3072 nt
	global_load_dwordx4 v[80:83], v23, s[84:85] nt
	global_load_dwordx4 v[84:87], v23, s[84:85] offset:1024 nt
	global_load_dwordx4 v[88:91], v23, s[84:85] offset:2048 nt
	global_load_dwordx4 v[92:95], v23, s[84:85] offset:3072 nt
	global_load_dwordx4 v[96:99], v22, s[88:89] nt
	global_load_dwordx4 v[100:103], v22, s[88:89] offset:1024 nt
	global_load_dwordx4 v[104:107], v22, s[88:89] offset:2048 nt
	global_load_dwordx4 v[108:111], v22, s[88:89] offset:3072 nt
	global_load_dwordx4 v[112:115], v23, s[88:89] nt
	global_load_dwordx4 v[116:119], v23, s[88:89] offset:1024 nt
	global_load_dwordx4 v[120:123], v23, s[88:89] offset:2048 nt
	global_load_dwordx4 v[124:127], v23, s[88:89] offset:3072 nt
	s_waitcnt vmcnt(15)
	global_store_dwordx4 v22, v[64:67], s[86:87] nt
	s_waitcnt vmcnt(15)
	global_store_dwordx4 v22, v[68:71], s[86:87] offset:1024 nt
	s_waitcnt vmcnt(15)
	global_store_dwordx4 v22, v[72:75], s[86:87] offset:2048 nt
	s_waitcnt vmcnt(15)
	global_store_dwordx4 v22, v[76:79], s[86:87] offset:3072 nt
	s_waitcnt vmcnt(15)
	global_store_dwordx4 v23, v[80:83], s[86:87] nt
	s_waitcnt vmcnt(15)
	global_store_dwordx4 v23, v[84:87], s[86:87] offset:1024 nt
	s_waitcnt vmcnt(15)
	global_store_dwordx4 v23, v[88:91], s[86:87] offset:2048 nt
	s_waitcnt vmcnt(15)
	global_store_dwordx4 v23, v[92:95], s[86:87] offset:3072 nt
	s_waitcnt vmcnt(15)
	global_store_dwordx4 v22, v[96:99], s[90:91] nt
	s_waitcnt vmcnt(15)
	global_store_dwordx4 v22, v[100:103], s[90:91] offset:1024 nt
	s_waitcnt vmcnt(15)
	global_store_dwordx4 v22, v[104:107], s[90:91] offset:2048 nt
	s_waitcnt vmcnt(15)
	global_store_dwordx4 v22, v[108:111], s[90:91] offset:3072 nt
	s_waitcnt vmcnt(15)
	global_store_dwordx4 v23, v[112:115], s[90:91] nt
	s_waitcnt vmcnt(15)
	global_store_dwordx4 v23, v[116:119], s[90:91] offset:1024 nt
	s_waitcnt vmcnt(15)
	global_store_dwordx4 v23, v[120:123], s[90:91] offset:2048 nt
	s_waitcnt vmcnt(15)
	global_store_dwordx4 v23, v[124:127], s[90:91] offset:3072 nt
	s_add_i32 s80, s101, s100
	s_branch .Lcpyg_loop
.Lcpyg_tail:
	s_cmp_lt_u32 s80, 0x12590
	s_cbranch_scc0 .Lcpyg_end
	s_mul_hi_u32 s81, s80, 0x2ad5802b
	s_lshr_b32 s81, s81, 8
	s_mul_i32 s82, s81, 0x5fa
	s_sub_i32 s82, s80, s82
	s_lshl_b32 s82, s82, 13
	s_and_b32 s83, s81, 31
	s_mul_i32 s83, s83, 0xc00000
	s_add_i32 s82, s82, s83
	s_cmp_lt_u32 s81, 32
	s_cselect_b32 s84, s92, s94
	s_cselect_b32 s85, s93, s95
	s_mov_b32 s83, 0x1f210000
	s_cselect_b32 s83, 0x7210000, s83
	s_add_u32 s84, s84, s82
	s_addc_u32 s85, s85, 0
	s_add_u32 s84, s84, 0xc000
	s_addc_u32 s85, s85, 0
	s_add_u32 s83, s83, s82
	s_add_u32 s86, s98, s83
	s_addc_u32 s87, s99, 0
	global_load_dwordx4 v[64:67], v22, s[84:85] nt
	global_load_dwordx4 v[68:71], v22, s[84:85] offset:1024 nt
	global_load_dwordx4 v[72:75], v22, s[84:85] offset:2048 nt
	global_load_dwordx4 v[76:79], v22, s[84:85] offset:3072 nt
	global_load_dwordx4 v[80:83], v23, s[84:85] nt
	global_load_dwordx4 v[84:87], v23, s[84:85] offset:1024 nt
	global_load_dwordx4 v[88:91], v23, s[84:85] offset:2048 nt
	global_load_dwordx4 v[92:95], v23, s[84:85] offset:3072 nt
	s_waitcnt vmcnt(7)
	global_store_dwordx4 v22, v[64:67], s[86:87] nt
	s_waitcnt vmcnt(7)
	global_store_dwordx4 v22, v[68:71], s[86:87] offset:1024 nt
	s_waitcnt vmcnt(7)
	global_store_dwordx4 v22, v[72:75], s[86:87] offset:2048 nt
	s_waitcnt vmcnt(7)
	global_store_dwordx4 v22, v[76:79], s[86:87] offset:3072 nt
	s_waitcnt vmcnt(7)
	global_store_dwordx4 v23, v[80:83], s[86:87] nt
	s_waitcnt vmcnt(7)
	global_store_dwordx4 v23, v[84:87], s[86:87] offset:1024 nt
	s_waitcnt vmcnt(7)
	global_store_dwordx4 v23, v[88:91], s[86:87] offset:2048 nt
	s_waitcnt vmcnt(7)
	global_store_dwordx4 v23, v[92:95], s[86:87] offset:3072 nt

.LBB0_1481:
	s_or_b64 exec, exec, s[6:7]
	v_readlane_b32 s4, v234, 2
	v_mov_b32_e32 v8, v174
	v_readlane_b32 s5, v234, 3
	s_barrier
	s_and_b32 s80, s33, 64
	s_cmp_eq_u32 s80, 0
	s_cbranch_scc1 .Lpre4_skip
	v_lshrrev_b32_e32 v21, 6, v174
	v_and_b32_e32 v22, 63, v174
	v_lshlrev_b32_e32 v22, 4, v22
	v_readfirstlane_b32 s80, v21
	v_add_u32_e32 v23, 0x1000, v22
	v_readfirstlane_b32 s92, v235
	v_readfirstlane_b32 s93, v236
	v_readfirstlane_b32 s94, v237
	v_readfirstlane_b32 s95, v238
	v_readfirstlane_b32 s98, v239
	v_readfirstlane_b32 s99, v240
	s_lshr_b32 s100, s33, 7
	s_lshl_b32 s100, s100, 3
	s_lshr_b32 s101, s33, 3
	s_and_b32 s101, s101, 7
	s_add_i32 s100, s100, s101
	s_lshl_b32 s100, s100, 3
	s_add_i32 s80, s80, s100
	s_add_i32 s80, s80, 0x12590
	s_movk_i32 s100, 0x400
.Lcpy4p_loop:
	s_add_i32 s101, s80, s100
	s_cmp_lt_u32 s101, 0x13844
	s_cbranch_scc0 .Lcpy4p_tail
	s_mul_hi_u32 s81, s80, 0x2ad5802b
	s_lshr_b32 s81, s81, 8
	s_mul_i32 s82, s81, 0x5fa
	s_sub_i32 s82, s80, s82
	s_lshl_b32 s82, s82, 13
	s_and_b32 s83, s81, 31
	s_mul_i32 s83, s83, 0xc00000
	s_add_i32 s82, s82, s83
	s_cmp_lt_u32 s81, 32
	s_cselect_b32 s84, s92, s94
	s_cselect_b32 s85, s93, s95
	s_mov_b32 s83, 0x1f210000
	s_cselect_b32 s83, 0x7210000, s83
	s_add_u32 s84, s84, s82
	s_addc_u32 s85, s85, 0
	s_add_u32 s84, s84, 0xc000
	s_addc_u32 s85, s85, 0
	s_add_u32 s83, s83, s82
	s_add_u32 s86, s98, s83
	s_addc_u32 s87, s99, 0
	s_mul_hi_u32 s81, s101, 0x2ad5802b
	s_lshr_b32 s81, s81, 8
	s_mul_i32 s82, s81, 0x5fa
	s_sub_i32 s82, s101, s82
	s_lshl_b32 s82, s82, 13
	s_and_b32 s83, s81, 31
	s_mul_i32 s83, s83, 0xc00000
	s_add_i32 s82, s82, s83
	s_cmp_lt_u32 s81, 32
	s_cselect_b32 s88, s92, s94
	s_cselect_b32 s89, s93, s95
	s_mov_b32 s83, 0x1f210000
	s_cselect_b32 s83, 0x7210000, s83
	s_add_u32 s88, s88, s82
	s_addc_u32 s89, s89, 0
	s_add_u32 s88, s88, 0xc000
	s_addc_u32 s89, s89, 0
	s_add_u32 s83, s83, s82
	s_add_u32 s90, s98, s83
	s_addc_u32 s91, s99, 0
	global_load_dwordx4 v[64:67], v22, s[84:85] nt
	global_load_dwordx4 v[68:71], v22, s[84:85] offset:1024 nt
	global_load_dwordx4 v[72:75], v22, s[84:85] offset:2048 nt
	global_load_dwordx4 v[76:79], v22, s[84:85] offset:3072 nt
	global_load_dwordx4 v[80:83], v23, s[84:85] nt
	global_load_dwordx4 v[84:87], v23, s[84:85] offset:1024 nt
	global_load_dwordx4 v[88:91], v23, s[84:85] offset:2048 nt
	global_load_dwordx4 v[92:95], v23, s[84:85] offset:3072 nt
	global_load_dwordx4 v[96:99], v22, s[88:89] nt
	global_load_dwordx4 v[100:103], v22, s[88:89] offset:1024 nt
	global_load_dwordx4 v[104:107], v22, s[88:89] offset:2048 nt
	global_load_dwordx4 v[108:111], v22, s[88:89] offset:3072 nt
	global_load_dwordx4 v[112:115], v23, s[88:89] nt
	global_load_dwordx4 v[116:119], v23, s[88:89] offset:1024 nt
	global_load_dwordx4 v[120:123], v23, s[88:89] offset:2048 nt
	global_load_dwordx4 v[124:127], v23, s[88:89] offset:3072 nt
	s_waitcnt vmcnt(15)
	global_store_dwordx4 v22, v[64:67], s[86:87] nt
	s_waitcnt vmcnt(15)
	global_store_dwordx4 v22, v[68:71], s[86:87] offset:1024 nt
	s_waitcnt vmcnt(15)
	global_store_dwordx4 v22, v[72:75], s[86:87] offset:2048 nt
	s_waitcnt vmcnt(15)
	global_store_dwordx4 v22, v[76:79], s[86:87] offset:3072 nt
	s_waitcnt vmcnt(15)
	global_store_dwordx4 v23, v[80:83], s[86:87] nt
	s_waitcnt vmcnt(15)
	global_store_dwordx4 v23, v[84:87], s[86:87] offset:1024 nt
	s_waitcnt vmcnt(15)
	global_store_dwordx4 v23, v[88:91], s[86:87] offset:2048 nt
	s_waitcnt vmcnt(15)
	global_store_dwordx4 v23, v[92:95], s[86:87] offset:3072 nt
	s_waitcnt vmcnt(15)
	global_store_dwordx4 v22, v[96:99], s[90:91] nt
	s_waitcnt vmcnt(15)
	global_store_dwordx4 v22, v[100:103], s[90:91] offset:1024 nt
	s_waitcnt vmcnt(15)
	global_store_dwordx4 v22, v[104:107], s[90:91] offset:2048 nt
	s_waitcnt vmcnt(15)
	global_store_dwordx4 v22, v[108:111], s[90:91] offset:3072 nt
	s_waitcnt vmcnt(15)
	global_store_dwordx4 v23, v[112:115], s[90:91] nt
	s_waitcnt vmcnt(15)
	global_store_dwordx4 v23, v[116:119], s[90:91] offset:1024 nt
	s_waitcnt vmcnt(15)
	global_store_dwordx4 v23, v[120:123], s[90:91] offset:2048 nt
	s_waitcnt vmcnt(15)
	global_store_dwordx4 v23, v[124:127], s[90:91] offset:3072 nt
	s_add_i32 s80, s101, s100
	s_branch .Lcpy4p_loop
.Lcpy4p_tail:
	s_cmp_lt_u32 s80, 0x13844
	s_cbranch_scc0 .Lcpy4p_end
	s_mul_hi_u32 s81, s80, 0x2ad5802b
	s_lshr_b32 s81, s81, 8
	s_mul_i32 s82, s81, 0x5fa
	s_sub_i32 s82, s80, s82
	s_lshl_b32 s82, s82, 13
	s_and_b32 s83, s81, 31
	s_mul_i32 s83, s83, 0xc00000
	s_add_i32 s82, s82, s83
	s_cmp_lt_u32 s81, 32
	s_cselect_b32 s84, s92, s94
	s_cselect_b32 s85, s93, s95
	s_mov_b32 s83, 0x1f210000
	s_cselect_b32 s83, 0x7210000, s83
	s_add_u32 s84, s84, s82
	s_addc_u32 s85, s85, 0
	s_add_u32 s84, s84, 0xc000
	s_addc_u32 s85, s85, 0
	s_add_u32 s83, s83, s82
	s_add_u32 s86, s98, s83
	s_addc_u32 s87, s99, 0
	global_load_dwordx4 v[64:67], v22, s[84:85] nt
	global_load_dwordx4 v[68:71], v22, s[84:85] offset:1024 nt
	global_load_dwordx4 v[72:75], v22, s[84:85] offset:2048 nt
	global_load_dwordx4 v[76:79], v22, s[84:85] offset:3072 nt
	global_load_dwordx4 v[80:83], v23, s[84:85] nt
	global_load_dwordx4 v[84:87], v23, s[84:85] offset:1024 nt
	global_load_dwordx4 v[88:91], v23, s[84:85] offset:2048 nt
	global_load_dwordx4 v[92:95], v23, s[84:85] offset:3072 nt
	s_waitcnt vmcnt(7)
	global_store_dwordx4 v22, v[64:67], s[86:87] nt
	s_waitcnt vmcnt(7)
	global_store_dwordx4 v22, v[68:71], s[86:87] offset:1024 nt
	s_waitcnt vmcnt(7)
	global_store_dwordx4 v22, v[72:75], s[86:87] offset:2048 nt
	s_waitcnt vmcnt(7)
	global_store_dwordx4 v22, v[76:79], s[86:87] offset:3072 nt
	s_waitcnt vmcnt(7)
	global_store_dwordx4 v23, v[80:83], s[86:87] nt
	s_waitcnt vmcnt(7)
	global_store_dwordx4 v23, v[84:87], s[86:87] offset:1024 nt
	s_waitcnt vmcnt(7)
	global_store_dwordx4 v23, v[88:91], s[86:87] offset:2048 nt
	s_waitcnt vmcnt(7)
	global_store_dwordx4 v23, v[92:95], s[86:87] offset:3072 nt

.Lmg4_end:
	v_lshrrev_b32_e32 v21, 6, v174
	v_and_b32_e32 v22, 63, v174
	v_lshlrev_b32_e32 v22, 4, v22
	v_readfirstlane_b32 s80, v21
	v_add_u32_e32 v23, 0x1000, v22
	v_readfirstlane_b32 s92, v235
	v_readfirstlane_b32 s93, v236
	v_readfirstlane_b32 s94, v237
	v_readfirstlane_b32 s95, v238
	v_readfirstlane_b32 s98, v239
	v_readfirstlane_b32 s99, v240
	s_lshr_b32 s100, s33, 7
	s_lshl_b32 s100, s100, 3
	s_lshr_b32 s101, s33, 3
	s_and_b32 s101, s101, 7
	s_add_i32 s100, s100, s101
	s_lshl_b32 s100, s100, 3
	s_add_i32 s80, s80, s100
	s_add_i32 s80, s80, 0x13844
	s_movk_i32 s100, 0x400
.Lcpy4_loop:
	s_add_i32 s101, s80, s100
	s_cmp_lt_u32 s101, 0x13e80
	s_cbranch_scc0 .Lcpy4_tail
	s_mul_hi_u32 s81, s80, 0x2ad5802b
	s_lshr_b32 s81, s81, 8
	s_mul_i32 s82, s81, 0x5fa
	s_sub_i32 s82, s80, s82
	s_lshl_b32 s82, s82, 13
	s_and_b32 s83, s81, 31
	s_mul_i32 s83, s83, 0xc00000
	s_add_i32 s82, s82, s83
	s_cmp_lt_u32 s81, 32
	s_cselect_b32 s84, s92, s94
	s_cselect_b32 s85, s93, s95
	s_mov_b32 s83, 0x1f210000
	s_cselect_b32 s83, 0x7210000, s83
	s_add_u32 s84, s84, s82
	s_addc_u32 s85, s85, 0
	s_add_u32 s84, s84, 0xc000
	s_addc_u32 s85, s85, 0
	s_add_u32 s83, s83, s82
	s_add_u32 s86, s98, s83
	s_addc_u32 s87, s99, 0
	s_mul_hi_u32 s81, s101, 0x2ad5802b
	s_lshr_b32 s81, s81, 8
	s_mul_i32 s82, s81, 0x5fa
	s_sub_i32 s82, s101, s82
	s_lshl_b32 s82, s82, 13
	s_and_b32 s83, s81, 31
	s_mul_i32 s83, s83, 0xc00000
	s_add_i32 s82, s82, s83
	s_cmp_lt_u32 s81, 32
	s_cselect_b32 s88, s92, s94
	s_cselect_b32 s89, s93, s95
	s_mov_b32 s83, 0x1f210000
	s_cselect_b32 s83, 0x7210000, s83
	s_add_u32 s88, s88, s82
	s_addc_u32 s89, s89, 0
	s_add_u32 s88, s88, 0xc000
	s_addc_u32 s89, s89, 0
	s_add_u32 s83, s83, s82
	s_add_u32 s90, s98, s83
	s_addc_u32 s91, s99, 0
	global_load_dwordx4 v[64:67], v22, s[84:85] nt
	global_load_dwordx4 v[68:71], v22, s[84:85] offset:1024 nt
	global_load_dwordx4 v[72:75], v22, s[84:85] offset:2048 nt
	global_load_dwordx4 v[76:79], v22, s[84:85] offset:3072 nt
	global_load_dwordx4 v[80:83], v23, s[84:85] nt
	global_load_dwordx4 v[84:87], v23, s[84:85] offset:1024 nt
	global_load_dwordx4 v[88:91], v23, s[84:85] offset:2048 nt
	global_load_dwordx4 v[92:95], v23, s[84:85] offset:3072 nt
	global_load_dwordx4 v[96:99], v22, s[88:89] nt
	global_load_dwordx4 v[100:103], v22, s[88:89] offset:1024 nt
	global_load_dwordx4 v[104:107], v22, s[88:89] offset:2048 nt
	global_load_dwordx4 v[108:111], v22, s[88:89] offset:3072 nt
	global_load_dwordx4 v[112:115], v23, s[88:89] nt
	global_load_dwordx4 v[116:119], v23, s[88:89] offset:1024 nt
	global_load_dwordx4 v[120:123], v23, s[88:89] offset:2048 nt
	global_load_dwordx4 v[124:127], v23, s[88:89] offset:3072 nt
	s_waitcnt vmcnt(15)
	global_store_dwordx4 v22, v[64:67], s[86:87] nt
	s_waitcnt vmcnt(15)
	global_store_dwordx4 v22, v[68:71], s[86:87] offset:1024 nt
	s_waitcnt vmcnt(15)
	global_store_dwordx4 v22, v[72:75], s[86:87] offset:2048 nt
	s_waitcnt vmcnt(15)
	global_store_dwordx4 v22, v[76:79], s[86:87] offset:3072 nt
	s_waitcnt vmcnt(15)
	global_store_dwordx4 v23, v[80:83], s[86:87] nt
	s_waitcnt vmcnt(15)
	global_store_dwordx4 v23, v[84:87], s[86:87] offset:1024 nt
	s_waitcnt vmcnt(15)
	global_store_dwordx4 v23, v[88:91], s[86:87] offset:2048 nt
	s_waitcnt vmcnt(15)
	global_store_dwordx4 v23, v[92:95], s[86:87] offset:3072 nt
	s_waitcnt vmcnt(15)
	global_store_dwordx4 v22, v[96:99], s[90:91] nt
	s_waitcnt vmcnt(15)
	global_store_dwordx4 v22, v[100:103], s[90:91] offset:1024 nt
	s_waitcnt vmcnt(15)
	global_store_dwordx4 v22, v[104:107], s[90:91] offset:2048 nt
	s_waitcnt vmcnt(15)
	global_store_dwordx4 v22, v[108:111], s[90:91] offset:3072 nt
	s_waitcnt vmcnt(15)
	global_store_dwordx4 v23, v[112:115], s[90:91] nt
	s_waitcnt vmcnt(15)
	global_store_dwordx4 v23, v[116:119], s[90:91] offset:1024 nt
	s_waitcnt vmcnt(15)
	global_store_dwordx4 v23, v[120:123], s[90:91] offset:2048 nt
	s_waitcnt vmcnt(15)
	global_store_dwordx4 v23, v[124:127], s[90:91] offset:3072 nt
	s_add_i32 s80, s101, s100
	s_branch .Lcpy4_loop
.Lcpy4_tail:
	s_cmp_lt_u32 s80, 0x13e80
	s_cbranch_scc0 .Lcpy4_end
	s_mul_hi_u32 s81, s80, 0x2ad5802b
	s_lshr_b32 s81, s81, 8
	s_mul_i32 s82, s81, 0x5fa
	s_sub_i32 s82, s80, s82
	s_lshl_b32 s82, s82, 13
	s_and_b32 s83, s81, 31
	s_mul_i32 s83, s83, 0xc00000
	s_add_i32 s82, s82, s83
	s_cmp_lt_u32 s81, 32
	s_cselect_b32 s84, s92, s94
	s_cselect_b32 s85, s93, s95
	s_mov_b32 s83, 0x1f210000
	s_cselect_b32 s83, 0x7210000, s83
	s_add_u32 s84, s84, s82
	s_addc_u32 s85, s85, 0
	s_add_u32 s84, s84, 0xc000
	s_addc_u32 s85, s85, 0
	s_add_u32 s83, s83, s82
	s_add_u32 s86, s98, s83
	s_addc_u32 s87, s99, 0
	global_load_dwordx4 v[64:67], v22, s[84:85] nt
	global_load_dwordx4 v[68:71], v22, s[84:85] offset:1024 nt
	global_load_dwordx4 v[72:75], v22, s[84:85] offset:2048 nt
	global_load_dwordx4 v[76:79], v22, s[84:85] offset:3072 nt
	global_load_dwordx4 v[80:83], v23, s[84:85] nt
	global_load_dwordx4 v[84:87], v23, s[84:85] offset:1024 nt
	global_load_dwordx4 v[88:91], v23, s[84:85] offset:2048 nt
	global_load_dwordx4 v[92:95], v23, s[84:85] offset:3072 nt
	s_waitcnt vmcnt(7)
	global_store_dwordx4 v22, v[64:67], s[86:87] nt
	s_waitcnt vmcnt(7)
	global_store_dwordx4 v22, v[68:71], s[86:87] offset:1024 nt
	s_waitcnt vmcnt(7)
	global_store_dwordx4 v22, v[72:75], s[86:87] offset:2048 nt
	s_waitcnt vmcnt(7)
	global_store_dwordx4 v22, v[76:79], s[86:87] offset:3072 nt
	s_waitcnt vmcnt(7)
	global_store_dwordx4 v23, v[80:83], s[86:87] nt
	s_waitcnt vmcnt(7)
	global_store_dwordx4 v23, v[84:87], s[86:87] offset:1024 nt
	s_waitcnt vmcnt(7)
	global_store_dwordx4 v23, v[88:91], s[86:87] offset:2048 nt
	s_waitcnt vmcnt(7)
	global_store_dwordx4 v23, v[92:95], s[86:87] offset:3072 nt
